# GEMM main loops: removed the duplicate lgkmcnt(0) after each pre-MFMA barrier and the no-op setprio 0/1 pair between the two MFMA clusters
# speedup vs baseline: 1.0013x; 1.0013x over previous
; #define PG8_STAGE(bufoff, gbase, voff) do { _Pragma("unroll") for (int _i = 0; _i < 2; ++_i) \
;         __builtin_amdgcn_global_load_lds((const unsigned*)((const char*)(gbase) + (voff)[_i]), (LAS unsigned*)(lds + (bufoff) + ldsw + _i * 8192), 16, 0, 0); } while (0)
; #define PG8_LDA(dst, b, h) do { _Pragma("unroll") for (int m = 0; m < 4; ++m) _Pragma("unroll") for (int k = 0; k < 2; ++k) dst[m][k] = *(const LAS bf16x8*)(lds + PG8_SA(b, h) + aoff + m * 2048 + k * 1024); } while (0)
; #define PG8_LDB(dst, b, h) do { _Pragma("unroll") for (int n = 0; n < 2; ++n) _Pragma("unroll") for (int k = 0; k < 2; ++k) dst[n][k] = *(const LAS bf16x8*)(lds + PG8_SB(b, h) + boff + n * 2048 + k * 1024); } while (0)
; #define PG8_MMA(ai, bj, At, Bt) do { __builtin_amdgcn_s_setprio(1); _Pragma("unroll") for (int m = 0; m < 4; ++m) _Pragma("unroll") for (int n = 0; n < 2; ++n) _Pragma("unroll") for (int k = 0; k < 2; ++k) \
;         acc[ai][bj][m][n] = __builtin_amdgcn_mfma_f32_16x16x32_bf16(Bt[n][k], At[m][k], acc[ai][bj][m][n], 0, 0, 0); __builtin_amdgcn_s_setprio(0); } while (0)
; #define PG8_WAIT_V(n) asm volatile("s_waitcnt vmcnt(" #n ")" ::: "memory")
; #define PG8_WAIT_L(n) asm volatile("s_waitcnt lgkmcnt(" #n ")" ::: "memory")
; #define PG8_BAR __builtin_amdgcn_s_barrier()
; #define PG8_SCHED __builtin_amdgcn_sched_barrier(0)
; template <class Epi, class Sched, int LDA, int LDB, bool ALIGN_EPI = true>
; __device__ __forceinline__ void gemm_phase(LAS unsigned char* lds, const Gemm g, const Sched& S, const Epi& E, int wave) {
;     ...
;             const bool last = (t == nt - 2);
;             const char* a1 = cA + (size_t)(t + 1) * kstep;
;             const char* a2 = last ? nA : cA + (size_t)(t + 2) * kstep; const char* b2 = last ? nB : cB + (size_t)(t + 2) * kstep;
;             const char* a3 = a2 + kstep; const char* b3 = b2 + kstep;
;             PG8_LDB(B0, 0, 0); PG8_LDB(B1, 0, 1); PG8_SCHED; PG8_LDA(At, 0, 0); PG8_STAGE(PG8_SA(1, 1), a1 + hstepA, voffA);
;             PG8_WAIT_V(8); PG8_WAIT_L(0); PG8_BAR; PG8_MMA(0, 0, At, B0); PG8_MMA(0, 1, At, B1); PG8_BAR; PG8_SCHED;
;             PG8_LDA(At, 0, 1); PG8_STAGE(PG8_SB(0, 0), b2, voffB); PG8_STAGE(PG8_SB(0, 1), b2 + hstepB, voffB); PG8_STAGE(PG8_SA(0, 0), a2, voffA);
;             PG8_WAIT_V(8); PG8_WAIT_L(0); PG8_BAR; PG8_MMA(1, 0, At, B0); PG8_MMA(1, 1, At, B1); PG8_BAR; PG8_SCHED;
.LBB0_485:
	s_add_u32 s24, s18, 0x100
	s_addc_u32 s25, s19, 0
	s_add_i32 s54, 0, 0x10000
	s_cmp_eq_u32 s53, 28
	s_cselect_b32 s35, s3, s25
	s_cselect_b32 s34, s2, s24
	v_add_u32_e32 v140, s54, v143
	s_cselect_b32 s29, s1, s45
	s_cselect_b32 s28, s17, s44
	s_add_i32 s55, 0, 0x14000
	ds_read_b128 v[146:149], v140
	ds_read_b128 v[150:153], v140 offset:1024
	ds_read_b128 v[154:157], v140 offset:2048
	ds_read_b128 v[158:161], v140 offset:3072
	v_add_u32_e32 v140, s55, v143
	ds_read_b128 v[162:165], v140
	ds_read_b128 v[166:169], v140 offset:1024
	ds_read_b128 v[170:173], v140 offset:2048
	ds_read_b128 v[180:183], v140 offset:3072
	v_lshl_add_u64 v[140:141], s[18:19], 0, v[136:137]
	s_add_i32 m0, s38, 0xc000
	ds_read_b128 v[184:187], v145
	ds_read_b128 v[188:191], v145 offset:1024
	ds_read_b128 v[192:195], v145 offset:2048
	ds_read_b128 v[196:199], v145 offset:3072
	ds_read_b128 v[200:203], v145 offset:4096
	ds_read_b128 v[204:207], v145 offset:5120
	ds_read_b128 v[208:211], v145 offset:6144
	ds_read_b128 v[212:215], v145 offset:7168
	global_load_lds_dwordx4 v[140:141], off
	v_lshl_add_u64 v[140:141], s[18:19], 0, v[138:139]
	s_add_i32 m0, s38, 0xe000
	s_nop 0
	global_load_lds_dwordx4 v[140:141], off
	s_waitcnt vmcnt(8)
	s_waitcnt lgkmcnt(0)
	s_barrier
	s_setprio 1
	v_mfma_f32_16x16x32_bf16 v[126:129], v[146:149], v[184:187], v[126:129]
	v_mfma_f32_16x16x32_bf16 v[118:121], v[154:157], v[184:187], v[118:121]
	v_mfma_f32_16x16x32_bf16 v[110:113], v[146:149], v[192:195], v[110:113]
	v_mfma_f32_16x16x32_bf16 v[102:105], v[154:157], v[192:195], v[102:105]
	v_mfma_f32_16x16x32_bf16 v[94:97], v[146:149], v[200:203], v[94:97]
	v_mfma_f32_16x16x32_bf16 v[86:89], v[154:157], v[200:203], v[86:89]
	v_mfma_f32_16x16x32_bf16 v[78:81], v[146:149], v[208:211], v[78:81]
	v_mfma_f32_16x16x32_bf16 v[70:73], v[154:157], v[208:211], v[70:73]
	v_mfma_f32_16x16x32_bf16 v[126:129], v[150:153], v[188:191], v[126:129]
	v_mfma_f32_16x16x32_bf16 v[118:121], v[158:161], v[188:191], v[118:121]
	v_mfma_f32_16x16x32_bf16 v[110:113], v[150:153], v[196:199], v[110:113]
	v_mfma_f32_16x16x32_bf16 v[102:105], v[158:161], v[196:199], v[102:105]
	v_mfma_f32_16x16x32_bf16 v[94:97], v[150:153], v[204:207], v[94:97]
	v_mfma_f32_16x16x32_bf16 v[86:89], v[158:161], v[204:207], v[86:89]
	v_mfma_f32_16x16x32_bf16 v[78:81], v[150:153], v[212:215], v[78:81]
	v_mfma_f32_16x16x32_bf16 v[70:73], v[158:161], v[212:215], v[70:73]
	v_mfma_f32_16x16x32_bf16 v[122:125], v[162:165], v[184:187], v[122:125]
	v_mfma_f32_16x16x32_bf16 v[114:117], v[170:173], v[184:187], v[114:117]
	v_mfma_f32_16x16x32_bf16 v[106:109], v[162:165], v[192:195], v[106:109]
	v_mfma_f32_16x16x32_bf16 v[98:101], v[170:173], v[192:195], v[98:101]
	v_mfma_f32_16x16x32_bf16 v[90:93], v[162:165], v[200:203], v[90:93]
	v_mfma_f32_16x16x32_bf16 v[82:85], v[170:173], v[200:203], v[82:85]
	v_mfma_f32_16x16x32_bf16 v[74:77], v[162:165], v[208:211], v[74:77]
	v_mfma_f32_16x16x32_bf16 v[66:69], v[170:173], v[208:211], v[66:69]
	v_mfma_f32_16x16x32_bf16 v[122:125], v[166:169], v[188:191], v[122:125]
	v_mfma_f32_16x16x32_bf16 v[114:117], v[180:183], v[188:191], v[114:117]
	v_mfma_f32_16x16x32_bf16 v[106:109], v[166:169], v[196:199], v[106:109]
	v_mfma_f32_16x16x32_bf16 v[98:101], v[180:183], v[196:199], v[98:101]
	v_mfma_f32_16x16x32_bf16 v[90:93], v[166:169], v[204:207], v[90:93]
	v_mfma_f32_16x16x32_bf16 v[82:85], v[180:183], v[204:207], v[82:85]
	v_mfma_f32_16x16x32_bf16 v[74:77], v[166:169], v[212:215], v[74:77]
	v_mfma_f32_16x16x32_bf16 v[66:69], v[180:183], v[212:215], v[66:69]
	s_setprio 0
	s_barrier
	s_add_i32 s18, s54, s5
	v_lshl_add_u64 v[140:141], s[28:29], 0, v[0:1]
	s_mov_b32 m0, s18
	ds_read_b128 v[184:187], v145 offset:16384
	ds_read_b128 v[188:191], v145 offset:17408
	ds_read_b128 v[192:195], v145 offset:18432
	ds_read_b128 v[196:199], v145 offset:19456
	ds_read_b128 v[200:203], v145 offset:20480
	ds_read_b128 v[204:207], v145 offset:21504
	ds_read_b128 v[208:211], v145 offset:22528
	ds_read_b128 v[212:215], v145 offset:23552
	global_load_lds_dwordx4 v[140:141], off
	s_add_i32 m0, s18, 0x2000
	s_add_u32 s18, s28, 0x80000
	v_lshl_add_u64 v[174:175], s[28:29], 0, v[130:131]
	s_addc_u32 s19, s29, 0
	s_add_i32 s54, s55, s5
	global_load_lds_dwordx4 v[174:175], off
	v_lshl_add_u64 v[216:217], s[18:19], 0, v[0:1]
	s_mov_b32 m0, s54
	v_lshl_add_u64 v[218:219], s[34:35], 0, v[132:133]
	global_load_lds_dwordx4 v[216:217], off
	v_lshl_add_u64 v[216:217], s[18:19], 0, v[130:131]
	s_add_i32 m0, s54, 0x2000
	s_nop 0
	global_load_lds_dwordx4 v[216:217], off
	v_lshl_add_u64 v[216:217], s[34:35], 0, v[134:135]
	s_mov_b32 m0, s38
	s_nop 0
	global_load_lds_dwordx4 v[216:217], off
	s_mov_b32 m0, s39
	s_nop 0
	global_load_lds_dwordx4 v[218:219], off
	s_waitcnt vmcnt(8)
	s_waitcnt lgkmcnt(0)
	s_barrier
; #define PG8_STAGE(bufoff, gbase, voff) do { _Pragma("unroll") for (int _i = 0; _i < 2; ++_i) \
;         __builtin_amdgcn_global_load_lds((const unsigned*)((const char*)(gbase) + (voff)[_i]), (LAS unsigned*)(lds + (bufoff) + ldsw + _i * 8192), 16, 0, 0); } while (0)
; #define PG8_LDA(dst, b, h) do { _Pragma("unroll") for (int m = 0; m < 4; ++m) _Pragma("unroll") for (int k = 0; k < 2; ++k) dst[m][k] = *(const LAS bf16x8*)(lds + PG8_SA(b, h) + aoff + m * 2048 + k * 1024); } while (0)
; #define PG8_LDB(dst, b, h) do { _Pragma("unroll") for (int n = 0; n < 2; ++n) _Pragma("unroll") for (int k = 0; k < 2; ++k) dst[n][k] = *(const LAS bf16x8*)(lds + PG8_SB(b, h) + boff + n * 2048 + k * 1024); } while (0)
; #define PG8_MMA(ai, bj, At, Bt) do { __builtin_amdgcn_s_setprio(1); _Pragma("unroll") for (int m = 0; m < 4; ++m) _Pragma("unroll") for (int n = 0; n < 2; ++n) _Pragma("unroll") for (int k = 0; k < 2; ++k) \
;         acc[ai][bj][m][n] = __builtin_amdgcn_mfma_f32_16x16x32_bf16(Bt[n][k], At[m][k], acc[ai][bj][m][n], 0, 0, 0); __builtin_amdgcn_s_setprio(0); } while (0)
; #define PG8_WAIT_V(n) asm volatile("s_waitcnt vmcnt(" #n ")" ::: "memory")
; #define PG8_WAIT_L(n) asm volatile("s_waitcnt lgkmcnt(" #n ")" ::: "memory")
; #define PG8_BAR __builtin_amdgcn_s_barrier()
; #define PG8_SCHED __builtin_amdgcn_sched_barrier(0)
; template <class Epi, class Sched, int LDA, int LDB, bool ALIGN_EPI = true>
; __device__ __forceinline__ void gemm_phase(LAS unsigned char* lds, const Gemm g, const Sched& S, const Epi& E, int wave) {
;     ...
;             PG8_WAIT_V(8); PG8_WAIT_L(0); PG8_BAR; PG8_MMA(1, 0, At, B0); PG8_MMA(1, 1, At, B1); PG8_BAR; PG8_SCHED;
;             PG8_LDB(B0, 1, 0); PG8_LDB(B1, 1, 1); PG8_SCHED; PG8_LDA(At, 1, 0); PG8_STAGE(PG8_SA(0, 1), a2 + hstepA, voffA);
;             PG8_WAIT_V(8); PG8_WAIT_L(0); PG8_BAR; PG8_MMA(0, 0, At, B0); PG8_MMA(0, 1, At, B1); PG8_BAR; PG8_SCHED;
;             PG8_LDA(At, 1, 1); PG8_STAGE(PG8_SB(1, 0), b3, voffB); PG8_STAGE(PG8_SB(1, 1), b3 + hstepB, voffB); PG8_STAGE(PG8_SA(1, 0), a3, voffA);
	s_setprio 1
	v_mfma_f32_16x16x32_bf16 v[62:65], v[146:149], v[184:187], v[62:65]
	v_mfma_f32_16x16x32_bf16 v[54:57], v[154:157], v[184:187], v[54:57]
	v_mfma_f32_16x16x32_bf16 v[46:49], v[146:149], v[192:195], v[46:49]
	v_mfma_f32_16x16x32_bf16 v[38:41], v[154:157], v[192:195], v[38:41]
	v_mfma_f32_16x16x32_bf16 v[30:33], v[146:149], v[200:203], v[30:33]
	v_mfma_f32_16x16x32_bf16 v[22:25], v[154:157], v[200:203], v[22:25]
	v_mfma_f32_16x16x32_bf16 v[14:17], v[146:149], v[208:211], v[14:17]
	v_mfma_f32_16x16x32_bf16 v[6:9], v[154:157], v[208:211], v[6:9]
	v_mfma_f32_16x16x32_bf16 v[62:65], v[150:153], v[188:191], v[62:65]
	v_mfma_f32_16x16x32_bf16 v[54:57], v[158:161], v[188:191], v[54:57]
	v_mfma_f32_16x16x32_bf16 v[46:49], v[150:153], v[196:199], v[46:49]
	v_mfma_f32_16x16x32_bf16 v[38:41], v[158:161], v[196:199], v[38:41]
	v_mfma_f32_16x16x32_bf16 v[30:33], v[150:153], v[204:207], v[30:33]
	v_mfma_f32_16x16x32_bf16 v[22:25], v[158:161], v[204:207], v[22:25]
	v_mfma_f32_16x16x32_bf16 v[14:17], v[150:153], v[212:215], v[14:17]
	v_mfma_f32_16x16x32_bf16 v[6:9], v[158:161], v[212:215], v[6:9]
	v_mfma_f32_16x16x32_bf16 v[58:61], v[162:165], v[184:187], v[58:61]
	v_mfma_f32_16x16x32_bf16 v[50:53], v[170:173], v[184:187], v[50:53]
	v_mfma_f32_16x16x32_bf16 v[42:45], v[162:165], v[192:195], v[42:45]
	v_mfma_f32_16x16x32_bf16 v[34:37], v[170:173], v[192:195], v[34:37]
	v_mfma_f32_16x16x32_bf16 v[26:29], v[162:165], v[200:203], v[26:29]
	v_mfma_f32_16x16x32_bf16 v[18:21], v[170:173], v[200:203], v[18:21]
	v_mfma_f32_16x16x32_bf16 v[10:13], v[162:165], v[208:211], v[10:13]
	v_mfma_f32_16x16x32_bf16 v[2:5], v[170:173], v[208:211], v[2:5]
	v_mfma_f32_16x16x32_bf16 v[58:61], v[166:169], v[188:191], v[58:61]
	v_mfma_f32_16x16x32_bf16 v[50:53], v[180:183], v[188:191], v[50:53]
	v_mfma_f32_16x16x32_bf16 v[42:45], v[166:169], v[196:199], v[42:45]
	v_mfma_f32_16x16x32_bf16 v[34:37], v[180:183], v[196:199], v[34:37]
	v_mfma_f32_16x16x32_bf16 v[26:29], v[166:169], v[204:207], v[26:29]
	v_mfma_f32_16x16x32_bf16 v[18:21], v[180:183], v[204:207], v[18:21]
	v_mfma_f32_16x16x32_bf16 v[10:13], v[166:169], v[212:215], v[10:13]
	v_mfma_f32_16x16x32_bf16 v[2:5], v[180:183], v[212:215], v[2:5]
	s_setprio 0
	s_barrier
	s_add_i32 s54, 0, 0x18000
	s_add_i32 s55, 0, 0x1c000
	v_add_u32_e32 v158, s54, v143
	v_add_u32_e32 v180, s55, v143
	ds_read_b128 v[146:149], v158
	ds_read_b128 v[150:153], v158 offset:1024
	ds_read_b128 v[154:157], v158 offset:2048
	ds_read_b128 v[158:161], v158 offset:3072
	ds_read_b128 v[162:165], v180
	ds_read_b128 v[166:169], v180 offset:1024
	ds_read_b128 v[170:173], v180 offset:2048
	ds_read_b128 v[180:183], v180 offset:3072
	s_add_u32 s18, s34, 0x84000
	s_addc_u32 s19, s35, 0
	s_mov_b32 m0, s46
	v_lshl_add_u64 v[220:221], s[18:19], 0, v[134:135]
	ds_read_b128 v[184:187], v145 offset:32768
	ds_read_b128 v[188:191], v145 offset:33792
	ds_read_b128 v[192:195], v145 offset:34816
	ds_read_b128 v[196:199], v145 offset:35840
	ds_read_b128 v[200:203], v145 offset:36864
	ds_read_b128 v[204:207], v145 offset:37888
	ds_read_b128 v[208:211], v145 offset:38912
	ds_read_b128 v[212:215], v145 offset:39936
	global_load_lds_dwordx4 v[220:221], off
	v_lshl_add_u64 v[220:221], s[18:19], 0, v[132:133]
	s_mov_b32 m0, s47
	s_nop 0
	global_load_lds_dwordx4 v[220:221], off
	s_waitcnt vmcnt(8)
	s_waitcnt lgkmcnt(0)
	s_barrier
	s_setprio 1
	v_mfma_f32_16x16x32_bf16 v[126:129], v[146:149], v[184:187], v[126:129]
	v_mfma_f32_16x16x32_bf16 v[118:121], v[154:157], v[184:187], v[118:121]
	v_mfma_f32_16x16x32_bf16 v[110:113], v[146:149], v[192:195], v[110:113]
	v_mfma_f32_16x16x32_bf16 v[102:105], v[154:157], v[192:195], v[102:105]
	v_mfma_f32_16x16x32_bf16 v[94:97], v[146:149], v[200:203], v[94:97]
	v_mfma_f32_16x16x32_bf16 v[86:89], v[154:157], v[200:203], v[86:89]
	v_mfma_f32_16x16x32_bf16 v[78:81], v[146:149], v[208:211], v[78:81]
	v_mfma_f32_16x16x32_bf16 v[70:73], v[154:157], v[208:211], v[70:73]
	v_mfma_f32_16x16x32_bf16 v[126:129], v[150:153], v[188:191], v[126:129]
	v_mfma_f32_16x16x32_bf16 v[118:121], v[158:161], v[188:191], v[118:121]
	v_mfma_f32_16x16x32_bf16 v[110:113], v[150:153], v[196:199], v[110:113]
	v_mfma_f32_16x16x32_bf16 v[102:105], v[158:161], v[196:199], v[102:105]
	v_mfma_f32_16x16x32_bf16 v[94:97], v[150:153], v[204:207], v[94:97]
	v_mfma_f32_16x16x32_bf16 v[86:89], v[158:161], v[204:207], v[86:89]
	v_mfma_f32_16x16x32_bf16 v[78:81], v[150:153], v[212:215], v[78:81]
	v_mfma_f32_16x16x32_bf16 v[70:73], v[158:161], v[212:215], v[70:73]
	v_mfma_f32_16x16x32_bf16 v[122:125], v[162:165], v[184:187], v[122:125]
	v_mfma_f32_16x16x32_bf16 v[114:117], v[170:173], v[184:187], v[114:117]
	v_mfma_f32_16x16x32_bf16 v[106:109], v[162:165], v[192:195], v[106:109]
	v_mfma_f32_16x16x32_bf16 v[98:101], v[170:173], v[192:195], v[98:101]
	v_mfma_f32_16x16x32_bf16 v[90:93], v[162:165], v[200:203], v[90:93]
	v_mfma_f32_16x16x32_bf16 v[82:85], v[170:173], v[200:203], v[82:85]
	v_mfma_f32_16x16x32_bf16 v[74:77], v[162:165], v[208:211], v[74:77]
	v_mfma_f32_16x16x32_bf16 v[66:69], v[170:173], v[208:211], v[66:69]
	v_mfma_f32_16x16x32_bf16 v[122:125], v[166:169], v[188:191], v[122:125]
	v_mfma_f32_16x16x32_bf16 v[114:117], v[180:183], v[188:191], v[114:117]
	v_mfma_f32_16x16x32_bf16 v[106:109], v[166:169], v[196:199], v[106:109]
	v_mfma_f32_16x16x32_bf16 v[98:101], v[180:183], v[196:199], v[98:101]
	v_mfma_f32_16x16x32_bf16 v[90:93], v[166:169], v[204:207], v[90:93]
	v_mfma_f32_16x16x32_bf16 v[82:85], v[180:183], v[204:207], v[82:85]
	v_mfma_f32_16x16x32_bf16 v[74:77], v[166:169], v[212:215], v[74:77]
	v_mfma_f32_16x16x32_bf16 v[66:69], v[180:183], v[212:215], v[66:69]
	s_setprio 0
	s_barrier
; #define PG8_STAGE(bufoff, gbase, voff) do { _Pragma("unroll") for (int _i = 0; _i < 2; ++_i) \
;         __builtin_amdgcn_global_load_lds((const unsigned*)((const char*)(gbase) + (voff)[_i]), (LAS unsigned*)(lds + (bufoff) + ldsw + _i * 8192), 16, 0, 0); } while (0)
; #define PG8_LDA(dst, b, h) do { _Pragma("unroll") for (int m = 0; m < 4; ++m) _Pragma("unroll") for (int k = 0; k < 2; ++k) dst[m][k] = *(const LAS bf16x8*)(lds + PG8_SA(b, h) + aoff + m * 2048 + k * 1024); } while (0)
; #define PG8_MMA(ai, bj, At, Bt) do { __builtin_amdgcn_s_setprio(1); _Pragma("unroll") for (int m = 0; m < 4; ++m) _Pragma("unroll") for (int n = 0; n < 2; ++n) _Pragma("unroll") for (int k = 0; k < 2; ++k) \
;         acc[ai][bj][m][n] = __builtin_amdgcn_mfma_f32_16x16x32_bf16(Bt[n][k], At[m][k], acc[ai][bj][m][n], 0, 0, 0); __builtin_amdgcn_s_setprio(0); } while (0)
; #define PG8_WAIT_V(n) asm volatile("s_waitcnt vmcnt(" #n ")" ::: "memory")
; #define PG8_WAIT_L(n) asm volatile("s_waitcnt lgkmcnt(" #n ")" ::: "memory")
; #define PG8_BAR __builtin_amdgcn_s_barrier()
; #define PG8_SCHED __builtin_amdgcn_sched_barrier(0)
; template <class Epi, class Sched, int LDA, int LDB, bool ALIGN_EPI = true>
; __device__ __forceinline__ void gemm_phase(LAS unsigned char* lds, const Gemm g, const Sched& S, const Epi& E, int wave) {
;     ...
;             PG8_LDA(At, 1, 1); PG8_STAGE(PG8_SB(1, 0), b3, voffB); PG8_STAGE(PG8_SB(1, 1), b3 + hstepB, voffB); PG8_STAGE(PG8_SA(1, 0), a3, voffA);
;             PG8_WAIT_V(8); PG8_WAIT_L(0); PG8_BAR; PG8_MMA(1, 0, At, B0); PG8_MMA(1, 1, At, B1); PG8_BAR; PG8_SCHED;
;         }
;         if constexpr (ALIGN_EPI) { if (wr == 0) PG8_BAR; }
	s_add_i32 s18, s54, s5
	v_lshl_add_u64 v[140:141], v[140:141], 0, s[6:7]
	s_mov_b32 m0, s18
	ds_read_b128 v[184:187], v145 offset:49152
	ds_read_b128 v[188:191], v145 offset:50176
	ds_read_b128 v[192:195], v145 offset:51200
	ds_read_b128 v[196:199], v145 offset:52224
	ds_read_b128 v[200:203], v145 offset:53248
	ds_read_b128 v[204:207], v145 offset:54272
	ds_read_b128 v[208:211], v145 offset:55296
	ds_read_b128 v[212:215], v145 offset:56320
	global_load_lds_dwordx4 v[140:141], off
	s_add_i32 m0, s18, 0x2000
	s_add_u32 s18, s28, 0x80080
	v_lshl_add_u64 v[140:141], v[174:175], 0, s[6:7]
	s_addc_u32 s19, s29, 0
	s_add_i32 s28, s55, s5
	global_load_lds_dwordx4 v[140:141], off
	v_lshl_add_u64 v[140:141], s[18:19], 0, v[0:1]
	s_mov_b32 m0, s28
	s_nop 0
	global_load_lds_dwordx4 v[140:141], off
	v_lshl_add_u64 v[140:141], s[18:19], 0, v[130:131]
	s_add_i32 m0, s28, 0x2000
	s_nop 0
	global_load_lds_dwordx4 v[140:141], off
	v_lshl_add_u64 v[140:141], v[216:217], 0, s[6:7]
	s_mov_b32 m0, s48
	s_nop 0
	global_load_lds_dwordx4 v[140:141], off
	v_lshl_add_u64 v[140:141], v[218:219], 0, s[6:7]
	s_mov_b32 m0, s49
	s_nop 0
	global_load_lds_dwordx4 v[140:141], off
	s_waitcnt vmcnt(8)
	s_waitcnt lgkmcnt(0)
	s_barrier
	s_setprio 1
	v_mfma_f32_16x16x32_bf16 v[62:65], v[146:149], v[184:187], v[62:65]
	v_mfma_f32_16x16x32_bf16 v[54:57], v[154:157], v[184:187], v[54:57]
	v_mfma_f32_16x16x32_bf16 v[46:49], v[146:149], v[192:195], v[46:49]
	v_mfma_f32_16x16x32_bf16 v[38:41], v[154:157], v[192:195], v[38:41]
	v_mfma_f32_16x16x32_bf16 v[30:33], v[146:149], v[200:203], v[30:33]
	v_mfma_f32_16x16x32_bf16 v[22:25], v[154:157], v[200:203], v[22:25]
	v_mfma_f32_16x16x32_bf16 v[14:17], v[146:149], v[208:211], v[14:17]
	v_mfma_f32_16x16x32_bf16 v[6:9], v[154:157], v[208:211], v[6:9]
	v_mfma_f32_16x16x32_bf16 v[62:65], v[150:153], v[188:191], v[62:65]
	v_mfma_f32_16x16x32_bf16 v[54:57], v[158:161], v[188:191], v[54:57]
	v_mfma_f32_16x16x32_bf16 v[46:49], v[150:153], v[196:199], v[46:49]
	v_mfma_f32_16x16x32_bf16 v[38:41], v[158:161], v[196:199], v[38:41]
	v_mfma_f32_16x16x32_bf16 v[30:33], v[150:153], v[204:207], v[30:33]
	v_mfma_f32_16x16x32_bf16 v[22:25], v[158:161], v[204:207], v[22:25]
	v_mfma_f32_16x16x32_bf16 v[14:17], v[150:153], v[212:215], v[14:17]
	v_mfma_f32_16x16x32_bf16 v[6:9], v[158:161], v[212:215], v[6:9]
	v_mfma_f32_16x16x32_bf16 v[58:61], v[162:165], v[184:187], v[58:61]
	v_mfma_f32_16x16x32_bf16 v[50:53], v[170:173], v[184:187], v[50:53]
	v_mfma_f32_16x16x32_bf16 v[42:45], v[162:165], v[192:195], v[42:45]
	v_mfma_f32_16x16x32_bf16 v[34:37], v[170:173], v[192:195], v[34:37]
	v_mfma_f32_16x16x32_bf16 v[26:29], v[162:165], v[200:203], v[26:29]
	v_mfma_f32_16x16x32_bf16 v[18:21], v[170:173], v[200:203], v[18:21]
	v_mfma_f32_16x16x32_bf16 v[10:13], v[162:165], v[208:211], v[10:13]
	v_mfma_f32_16x16x32_bf16 v[2:5], v[170:173], v[208:211], v[2:5]
	v_mfma_f32_16x16x32_bf16 v[58:61], v[166:169], v[188:191], v[58:61]
	v_mfma_f32_16x16x32_bf16 v[50:53], v[180:183], v[188:191], v[50:53]
	v_mfma_f32_16x16x32_bf16 v[42:45], v[166:169], v[196:199], v[42:45]
	v_mfma_f32_16x16x32_bf16 v[34:37], v[180:183], v[196:199], v[34:37]
	v_mfma_f32_16x16x32_bf16 v[26:29], v[166:169], v[204:207], v[26:29]
	v_mfma_f32_16x16x32_bf16 v[18:21], v[180:183], v[204:207], v[18:21]
	v_mfma_f32_16x16x32_bf16 v[10:13], v[166:169], v[212:215], v[10:13]
	v_mfma_f32_16x16x32_bf16 v[2:5], v[180:183], v[212:215], v[2:5]
	s_setprio 0
	s_barrier
	s_add_i32 s53, s53, 2
	s_add_u32 s44, s44, 0x100
	s_addc_u32 s45, s45, 0
	s_cmp_gt_u32 s53, 29
	s_mov_b64 s[18:19], s[24:25]
	s_cbranch_scc0 .LBB0_485
	v_readlane_b32 s6, v252, 14
	v_readlane_b32 s7, v252, 15
	s_and_b64 vcc, exec, s[6:7]
	s_cbranch_vccz .LBB0_488
	s_barrier

; #define PG8_STAGE(bufoff, gbase, voff) do { _Pragma("unroll") for (int _i = 0; _i < 2; ++_i) \
;         __builtin_amdgcn_global_load_lds((const unsigned*)((const char*)(gbase) + (voff)[_i]), (LAS unsigned*)(lds + (bufoff) + ldsw + _i * 8192), 16, 0, 0); } while (0)
; #define PG8_LDA(dst, b, h) do { _Pragma("unroll") for (int m = 0; m < 4; ++m) _Pragma("unroll") for (int k = 0; k < 2; ++k) dst[m][k] = *(const LAS bf16x8*)(lds + PG8_SA(b, h) + aoff + m * 2048 + k * 1024); } while (0)
; #define PG8_LDB(dst, b, h) do { _Pragma("unroll") for (int n = 0; n < 2; ++n) _Pragma("unroll") for (int k = 0; k < 2; ++k) dst[n][k] = *(const LAS bf16x8*)(lds + PG8_SB(b, h) + boff + n * 2048 + k * 1024); } while (0)
; #define PG8_MMA(ai, bj, At, Bt) do { __builtin_amdgcn_s_setprio(1); _Pragma("unroll") for (int m = 0; m < 4; ++m) _Pragma("unroll") for (int n = 0; n < 2; ++n) _Pragma("unroll") for (int k = 0; k < 2; ++k) \
;         acc[ai][bj][m][n] = __builtin_amdgcn_mfma_f32_16x16x32_bf16(Bt[n][k], At[m][k], acc[ai][bj][m][n], 0, 0, 0); __builtin_amdgcn_s_setprio(0); } while (0)
; #define PG8_WAIT_V(n) asm volatile("s_waitcnt vmcnt(" #n ")" ::: "memory")
; #define PG8_WAIT_L(n) asm volatile("s_waitcnt lgkmcnt(" #n ")" ::: "memory")
; #define PG8_BAR __builtin_amdgcn_s_barrier()
; #define PG8_SCHED __builtin_amdgcn_sched_barrier(0)
; template <class Epi, class Sched, int LDA, int LDB, bool ALIGN_EPI = true>
; __device__ __forceinline__ void gemm_phase(LAS unsigned char* lds, const Gemm g, const Sched& S, const Epi& E, int wave) {
;     ...
;             const bool last = (t == nt - 2);
;             const char* a1 = cA + (size_t)(t + 1) * kstep;
;             const char* a2 = last ? nA : cA + (size_t)(t + 2) * kstep; const char* b2 = last ? nB : cB + (size_t)(t + 2) * kstep;
;             const char* a3 = a2 + kstep; const char* b3 = b2 + kstep;
;             PG8_LDB(B0, 0, 0); PG8_LDB(B1, 0, 1); PG8_SCHED; PG8_LDA(At, 0, 0); PG8_STAGE(PG8_SA(1, 1), a1 + hstepA, voffA);
;             PG8_WAIT_V(8); PG8_WAIT_L(0); PG8_BAR; PG8_MMA(0, 0, At, B0); PG8_MMA(0, 1, At, B1); PG8_BAR; PG8_SCHED;
;             PG8_LDA(At, 0, 1); PG8_STAGE(PG8_SB(0, 0), b2, voffB); PG8_STAGE(PG8_SB(0, 1), b2 + hstepB, voffB); PG8_STAGE(PG8_SA(0, 0), a2, voffA);
;             PG8_WAIT_V(8); PG8_WAIT_L(0); PG8_BAR; PG8_MMA(1, 0, At, B0); PG8_MMA(1, 1, At, B1); PG8_BAR; PG8_SCHED;
.LBB0_1893:
	s_add_i32 s79, s46, 2
	s_add_u32 s38, s36, 0x100
	s_addc_u32 s39, s37, 0
	s_add_i32 s82, 0, 0x10000
	s_cmp_eq_u32 s25, s46
	s_cselect_b32 s49, s29, s39
	s_cselect_b32 s48, s28, s38
	s_cselect_b32 s47, s35, s78
	s_cselect_b32 s46, s34, s77
	s_add_i32 s85, 0, 0x14000
	v_add_u32_e32 v152, s82, v249
	v_add_u32_e32 v168, s85, v249
	ds_read_b128 v[130:133], v152
	ds_read_b128 v[134:137], v152 offset:1024
	ds_read_b128 v[148:151], v152 offset:2048
	ds_read_b128 v[152:155], v152 offset:3072
	ds_read_b128 v[156:159], v168
	ds_read_b128 v[160:163], v168 offset:1024
	ds_read_b128 v[164:167], v168 offset:2048
	ds_read_b128 v[168:171], v168 offset:3072
	v_lshl_add_u64 v[208:209], s[36:37], 0, v[144:145]
	s_add_i32 m0, s50, 0xc000
	ds_read_b128 v[172:175], v236
	ds_read_b128 v[180:183], v236 offset:1024
	ds_read_b128 v[184:187], v236 offset:2048
	ds_read_b128 v[188:191], v236 offset:3072
	ds_read_b128 v[192:195], v236 offset:4096
	ds_read_b128 v[196:199], v236 offset:5120
	ds_read_b128 v[200:203], v236 offset:6144
	ds_read_b128 v[204:207], v236 offset:7168
	global_load_lds_dwordx4 v[208:209], off
	v_lshl_add_u64 v[208:209], s[36:37], 0, v[146:147]
	s_add_i32 m0, s50, 0xe000
	s_nop 0
	global_load_lds_dwordx4 v[208:209], off
	s_waitcnt vmcnt(8)
	s_waitcnt lgkmcnt(0)
	s_barrier
	s_setprio 1
	v_mfma_f32_16x16x32_bf16 v[126:129], v[130:133], v[172:175], v[126:129]
	v_mfma_f32_16x16x32_bf16 v[122:125], v[148:151], v[172:175], v[122:125]
	v_mfma_f32_16x16x32_bf16 v[110:113], v[130:133], v[184:187], v[110:113]
	v_mfma_f32_16x16x32_bf16 v[106:109], v[148:151], v[184:187], v[106:109]
	v_mfma_f32_16x16x32_bf16 v[94:97], v[130:133], v[192:195], v[94:97]
	v_mfma_f32_16x16x32_bf16 v[90:93], v[148:151], v[192:195], v[90:93]
	v_mfma_f32_16x16x32_bf16 v[78:81], v[130:133], v[200:203], v[78:81]
	v_mfma_f32_16x16x32_bf16 v[74:77], v[148:151], v[200:203], v[74:77]
	v_mfma_f32_16x16x32_bf16 v[126:129], v[134:137], v[180:183], v[126:129]
	v_mfma_f32_16x16x32_bf16 v[122:125], v[152:155], v[180:183], v[122:125]
	v_mfma_f32_16x16x32_bf16 v[110:113], v[134:137], v[188:191], v[110:113]
	v_mfma_f32_16x16x32_bf16 v[106:109], v[152:155], v[188:191], v[106:109]
	v_mfma_f32_16x16x32_bf16 v[94:97], v[134:137], v[196:199], v[94:97]
	v_mfma_f32_16x16x32_bf16 v[90:93], v[152:155], v[196:199], v[90:93]
	v_mfma_f32_16x16x32_bf16 v[78:81], v[134:137], v[204:207], v[78:81]
	v_mfma_f32_16x16x32_bf16 v[74:77], v[152:155], v[204:207], v[74:77]
	v_mfma_f32_16x16x32_bf16 v[118:121], v[156:159], v[172:175], v[118:121]
	v_mfma_f32_16x16x32_bf16 v[114:117], v[164:167], v[172:175], v[114:117]
	v_mfma_f32_16x16x32_bf16 v[102:105], v[156:159], v[184:187], v[102:105]
	v_mfma_f32_16x16x32_bf16 v[98:101], v[164:167], v[184:187], v[98:101]
	v_mfma_f32_16x16x32_bf16 v[86:89], v[156:159], v[192:195], v[86:89]
	v_mfma_f32_16x16x32_bf16 v[82:85], v[164:167], v[192:195], v[82:85]
	v_mfma_f32_16x16x32_bf16 v[70:73], v[156:159], v[200:203], v[70:73]
	v_mfma_f32_16x16x32_bf16 v[66:69], v[164:167], v[200:203], v[66:69]
	v_mfma_f32_16x16x32_bf16 v[118:121], v[160:163], v[180:183], v[118:121]
	v_mfma_f32_16x16x32_bf16 v[114:117], v[168:171], v[180:183], v[114:117]
	v_mfma_f32_16x16x32_bf16 v[102:105], v[160:163], v[188:191], v[102:105]
	v_mfma_f32_16x16x32_bf16 v[98:101], v[168:171], v[188:191], v[98:101]
	v_mfma_f32_16x16x32_bf16 v[86:89], v[160:163], v[196:199], v[86:89]
	v_mfma_f32_16x16x32_bf16 v[82:85], v[168:171], v[196:199], v[82:85]
	v_mfma_f32_16x16x32_bf16 v[70:73], v[160:163], v[204:207], v[70:73]
	v_mfma_f32_16x16x32_bf16 v[66:69], v[168:171], v[204:207], v[66:69]
	s_setprio 0
	s_barrier
	s_add_i32 s36, s82, s2
	v_lshl_add_u64 v[208:209], s[46:47], 0, v[0:1]
	s_mov_b32 m0, s36
	ds_read_b128 v[172:175], v236 offset:16384
	ds_read_b128 v[180:183], v236 offset:17408
	ds_read_b128 v[184:187], v236 offset:18432
	ds_read_b128 v[188:191], v236 offset:19456
	ds_read_b128 v[192:195], v236 offset:20480
	ds_read_b128 v[196:199], v236 offset:21504
	ds_read_b128 v[200:203], v236 offset:22528
	ds_read_b128 v[204:207], v236 offset:23552
	global_load_lds_dwordx4 v[208:209], off
	s_add_i32 m0, s36, 0x2000
	s_add_u32 s36, s46, 0x160000
	v_lshl_add_u64 v[210:211], s[46:47], 0, v[142:143]
	s_addc_u32 s37, s47, 0
	s_add_i32 s82, s85, s2
	global_load_lds_dwordx4 v[210:211], off
	v_lshl_add_u64 v[212:213], s[36:37], 0, v[0:1]
	s_mov_b32 m0, s82
	v_lshl_add_u64 v[214:215], s[48:49], 0, v[140:141]
	global_load_lds_dwordx4 v[212:213], off
	v_lshl_add_u64 v[212:213], s[36:37], 0, v[142:143]
	s_add_i32 m0, s82, 0x2000
	s_nop 0
	global_load_lds_dwordx4 v[212:213], off
	v_lshl_add_u64 v[212:213], s[48:49], 0, v[138:139]
	s_mov_b32 m0, s50
	s_nop 0
	global_load_lds_dwordx4 v[212:213], off
	s_mov_b32 m0, s51
	s_nop 0
	global_load_lds_dwordx4 v[214:215], off
	s_waitcnt vmcnt(8)
	s_waitcnt lgkmcnt(0)
	s_barrier
; #define PG8_STAGE(bufoff, gbase, voff) do { _Pragma("unroll") for (int _i = 0; _i < 2; ++_i) \
;         __builtin_amdgcn_global_load_lds((const unsigned*)((const char*)(gbase) + (voff)[_i]), (LAS unsigned*)(lds + (bufoff) + ldsw + _i * 8192), 16, 0, 0); } while (0)
; #define PG8_LDA(dst, b, h) do { _Pragma("unroll") for (int m = 0; m < 4; ++m) _Pragma("unroll") for (int k = 0; k < 2; ++k) dst[m][k] = *(const LAS bf16x8*)(lds + PG8_SA(b, h) + aoff + m * 2048 + k * 1024); } while (0)
; #define PG8_LDB(dst, b, h) do { _Pragma("unroll") for (int n = 0; n < 2; ++n) _Pragma("unroll") for (int k = 0; k < 2; ++k) dst[n][k] = *(const LAS bf16x8*)(lds + PG8_SB(b, h) + boff + n * 2048 + k * 1024); } while (0)
; #define PG8_MMA(ai, bj, At, Bt) do { __builtin_amdgcn_s_setprio(1); _Pragma("unroll") for (int m = 0; m < 4; ++m) _Pragma("unroll") for (int n = 0; n < 2; ++n) _Pragma("unroll") for (int k = 0; k < 2; ++k) \
;         acc[ai][bj][m][n] = __builtin_amdgcn_mfma_f32_16x16x32_bf16(Bt[n][k], At[m][k], acc[ai][bj][m][n], 0, 0, 0); __builtin_amdgcn_s_setprio(0); } while (0)
; #define PG8_WAIT_V(n) asm volatile("s_waitcnt vmcnt(" #n ")" ::: "memory")
; #define PG8_WAIT_L(n) asm volatile("s_waitcnt lgkmcnt(" #n ")" ::: "memory")
; #define PG8_BAR __builtin_amdgcn_s_barrier()
; #define PG8_SCHED __builtin_amdgcn_sched_barrier(0)
; template <class Epi, class Sched, int LDA, int LDB, bool ALIGN_EPI = true>
; __device__ __forceinline__ void gemm_phase(LAS unsigned char* lds, const Gemm g, const Sched& S, const Epi& E, int wave) {
;     ...
;             PG8_WAIT_V(8); PG8_WAIT_L(0); PG8_BAR; PG8_MMA(1, 0, At, B0); PG8_MMA(1, 1, At, B1); PG8_BAR; PG8_SCHED;
;             PG8_LDB(B0, 1, 0); PG8_LDB(B1, 1, 1); PG8_SCHED; PG8_LDA(At, 1, 0); PG8_STAGE(PG8_SA(0, 1), a2 + hstepA, voffA);
;             PG8_WAIT_V(8); PG8_WAIT_L(0); PG8_BAR; PG8_MMA(0, 0, At, B0); PG8_MMA(0, 1, At, B1); PG8_BAR; PG8_SCHED;
;             PG8_LDA(At, 1, 1); PG8_STAGE(PG8_SB(1, 0), b3, voffB); PG8_STAGE(PG8_SB(1, 1), b3 + hstepB, voffB); PG8_STAGE(PG8_SA(1, 0), a3, voffA);
	s_setprio 1
	v_mfma_f32_16x16x32_bf16 v[62:65], v[130:133], v[172:175], v[62:65]
	v_mfma_f32_16x16x32_bf16 v[58:61], v[148:151], v[172:175], v[58:61]
	v_mfma_f32_16x16x32_bf16 v[46:49], v[130:133], v[184:187], v[46:49]
	v_mfma_f32_16x16x32_bf16 v[42:45], v[148:151], v[184:187], v[42:45]
	v_mfma_f32_16x16x32_bf16 v[30:33], v[130:133], v[192:195], v[30:33]
	v_mfma_f32_16x16x32_bf16 v[26:29], v[148:151], v[192:195], v[26:29]
	v_mfma_f32_16x16x32_bf16 v[14:17], v[130:133], v[200:203], v[14:17]
	v_mfma_f32_16x16x32_bf16 v[10:13], v[148:151], v[200:203], v[10:13]
	v_mfma_f32_16x16x32_bf16 v[62:65], v[134:137], v[180:183], v[62:65]
	v_mfma_f32_16x16x32_bf16 v[58:61], v[152:155], v[180:183], v[58:61]
	v_mfma_f32_16x16x32_bf16 v[46:49], v[134:137], v[188:191], v[46:49]
	v_mfma_f32_16x16x32_bf16 v[42:45], v[152:155], v[188:191], v[42:45]
	v_mfma_f32_16x16x32_bf16 v[30:33], v[134:137], v[196:199], v[30:33]
	v_mfma_f32_16x16x32_bf16 v[26:29], v[152:155], v[196:199], v[26:29]
	v_mfma_f32_16x16x32_bf16 v[14:17], v[134:137], v[204:207], v[14:17]
	v_mfma_f32_16x16x32_bf16 v[10:13], v[152:155], v[204:207], v[10:13]
	v_mfma_f32_16x16x32_bf16 v[54:57], v[156:159], v[172:175], v[54:57]
	v_mfma_f32_16x16x32_bf16 v[50:53], v[164:167], v[172:175], v[50:53]
	v_mfma_f32_16x16x32_bf16 v[38:41], v[156:159], v[184:187], v[38:41]
	v_mfma_f32_16x16x32_bf16 v[34:37], v[164:167], v[184:187], v[34:37]
	v_mfma_f32_16x16x32_bf16 v[22:25], v[156:159], v[192:195], v[22:25]
	v_mfma_f32_16x16x32_bf16 v[18:21], v[164:167], v[192:195], v[18:21]
	v_mfma_f32_16x16x32_bf16 v[6:9], v[156:159], v[200:203], v[6:9]
	v_mfma_f32_16x16x32_bf16 v[2:5], v[164:167], v[200:203], v[2:5]
	v_mfma_f32_16x16x32_bf16 v[54:57], v[160:163], v[180:183], v[54:57]
	v_mfma_f32_16x16x32_bf16 v[50:53], v[168:171], v[180:183], v[50:53]
	v_mfma_f32_16x16x32_bf16 v[38:41], v[160:163], v[188:191], v[38:41]
	v_mfma_f32_16x16x32_bf16 v[34:37], v[168:171], v[188:191], v[34:37]
	v_mfma_f32_16x16x32_bf16 v[22:25], v[160:163], v[196:199], v[22:25]
	v_mfma_f32_16x16x32_bf16 v[18:21], v[168:171], v[196:199], v[18:21]
	v_mfma_f32_16x16x32_bf16 v[6:9], v[160:163], v[204:207], v[6:9]
	v_mfma_f32_16x16x32_bf16 v[2:5], v[168:171], v[204:207], v[2:5]
	s_setprio 0
	s_barrier
	s_add_i32 s82, 0, 0x18000
	s_add_i32 s85, 0, 0x1c000
	v_add_u32_e32 v152, s82, v249
	v_add_u32_e32 v168, s85, v249
	ds_read_b128 v[130:133], v152
	ds_read_b128 v[134:137], v152 offset:1024
	ds_read_b128 v[148:151], v152 offset:2048
	ds_read_b128 v[152:155], v152 offset:3072
	ds_read_b128 v[156:159], v168
	ds_read_b128 v[160:163], v168 offset:1024
	ds_read_b128 v[164:167], v168 offset:2048
	ds_read_b128 v[168:171], v168 offset:3072
	s_add_u32 s36, s48, 0x160000
	s_addc_u32 s37, s49, 0
	s_mov_b32 m0, s52
	v_lshl_add_u64 v[216:217], s[36:37], 0, v[138:139]
	ds_read_b128 v[172:175], v236 offset:32768
	ds_read_b128 v[180:183], v236 offset:33792
	ds_read_b128 v[184:187], v236 offset:34816
	ds_read_b128 v[188:191], v236 offset:35840
	ds_read_b128 v[192:195], v236 offset:36864
	ds_read_b128 v[196:199], v236 offset:37888
	ds_read_b128 v[200:203], v236 offset:38912
	ds_read_b128 v[204:207], v236 offset:39936
	global_load_lds_dwordx4 v[216:217], off
	v_lshl_add_u64 v[216:217], s[36:37], 0, v[140:141]
	s_mov_b32 m0, s53
	s_nop 0
	global_load_lds_dwordx4 v[216:217], off
	s_waitcnt vmcnt(8)
	s_waitcnt lgkmcnt(0)
	s_barrier
	s_setprio 1
	v_mfma_f32_16x16x32_bf16 v[126:129], v[130:133], v[172:175], v[126:129]
	v_mfma_f32_16x16x32_bf16 v[122:125], v[148:151], v[172:175], v[122:125]
	v_mfma_f32_16x16x32_bf16 v[110:113], v[130:133], v[184:187], v[110:113]
	v_mfma_f32_16x16x32_bf16 v[106:109], v[148:151], v[184:187], v[106:109]
	v_mfma_f32_16x16x32_bf16 v[94:97], v[130:133], v[192:195], v[94:97]
	v_mfma_f32_16x16x32_bf16 v[90:93], v[148:151], v[192:195], v[90:93]
	v_mfma_f32_16x16x32_bf16 v[78:81], v[130:133], v[200:203], v[78:81]
	v_mfma_f32_16x16x32_bf16 v[74:77], v[148:151], v[200:203], v[74:77]
	v_mfma_f32_16x16x32_bf16 v[126:129], v[134:137], v[180:183], v[126:129]
	v_mfma_f32_16x16x32_bf16 v[122:125], v[152:155], v[180:183], v[122:125]
	v_mfma_f32_16x16x32_bf16 v[110:113], v[134:137], v[188:191], v[110:113]
	v_mfma_f32_16x16x32_bf16 v[106:109], v[152:155], v[188:191], v[106:109]
	v_mfma_f32_16x16x32_bf16 v[94:97], v[134:137], v[196:199], v[94:97]
	v_mfma_f32_16x16x32_bf16 v[90:93], v[152:155], v[196:199], v[90:93]
	v_mfma_f32_16x16x32_bf16 v[78:81], v[134:137], v[204:207], v[78:81]
	v_mfma_f32_16x16x32_bf16 v[74:77], v[152:155], v[204:207], v[74:77]
	v_mfma_f32_16x16x32_bf16 v[118:121], v[156:159], v[172:175], v[118:121]
	v_mfma_f32_16x16x32_bf16 v[114:117], v[164:167], v[172:175], v[114:117]
	v_mfma_f32_16x16x32_bf16 v[102:105], v[156:159], v[184:187], v[102:105]
	v_mfma_f32_16x16x32_bf16 v[98:101], v[164:167], v[184:187], v[98:101]
	v_mfma_f32_16x16x32_bf16 v[86:89], v[156:159], v[192:195], v[86:89]
	v_mfma_f32_16x16x32_bf16 v[82:85], v[164:167], v[192:195], v[82:85]
	v_mfma_f32_16x16x32_bf16 v[70:73], v[156:159], v[200:203], v[70:73]
	v_mfma_f32_16x16x32_bf16 v[66:69], v[164:167], v[200:203], v[66:69]
	v_mfma_f32_16x16x32_bf16 v[118:121], v[160:163], v[180:183], v[118:121]
	v_mfma_f32_16x16x32_bf16 v[114:117], v[168:171], v[180:183], v[114:117]
	v_mfma_f32_16x16x32_bf16 v[102:105], v[160:163], v[188:191], v[102:105]
	v_mfma_f32_16x16x32_bf16 v[98:101], v[168:171], v[188:191], v[98:101]
	v_mfma_f32_16x16x32_bf16 v[86:89], v[160:163], v[196:199], v[86:89]
	v_mfma_f32_16x16x32_bf16 v[82:85], v[168:171], v[196:199], v[82:85]
	v_mfma_f32_16x16x32_bf16 v[70:73], v[160:163], v[204:207], v[70:73]
	v_mfma_f32_16x16x32_bf16 v[66:69], v[168:171], v[204:207], v[66:69]
	s_setprio 0
	s_barrier
; #define PG8_STAGE(bufoff, gbase, voff) do { _Pragma("unroll") for (int _i = 0; _i < 2; ++_i) \
;         __builtin_amdgcn_global_load_lds((const unsigned*)((const char*)(gbase) + (voff)[_i]), (LAS unsigned*)(lds + (bufoff) + ldsw + _i * 8192), 16, 0, 0); } while (0)
; #define PG8_LDA(dst, b, h) do { _Pragma("unroll") for (int m = 0; m < 4; ++m) _Pragma("unroll") for (int k = 0; k < 2; ++k) dst[m][k] = *(const LAS bf16x8*)(lds + PG8_SA(b, h) + aoff + m * 2048 + k * 1024); } while (0)
; #define PG8_MMA(ai, bj, At, Bt) do { __builtin_amdgcn_s_setprio(1); _Pragma("unroll") for (int m = 0; m < 4; ++m) _Pragma("unroll") for (int n = 0; n < 2; ++n) _Pragma("unroll") for (int k = 0; k < 2; ++k) \
;         acc[ai][bj][m][n] = __builtin_amdgcn_mfma_f32_16x16x32_bf16(Bt[n][k], At[m][k], acc[ai][bj][m][n], 0, 0, 0); __builtin_amdgcn_s_setprio(0); } while (0)
; #define PG8_WAIT_V(n) asm volatile("s_waitcnt vmcnt(" #n ")" ::: "memory")
; #define PG8_WAIT_L(n) asm volatile("s_waitcnt lgkmcnt(" #n ")" ::: "memory")
; #define PG8_BAR __builtin_amdgcn_s_barrier()
; #define PG8_SCHED __builtin_amdgcn_sched_barrier(0)
; template <class Epi, class Sched, int LDA, int LDB, bool ALIGN_EPI = true>
; __device__ __forceinline__ void gemm_phase(LAS unsigned char* lds, const Gemm g, const Sched& S, const Epi& E, int wave) {
;     ...
;             PG8_LDA(At, 1, 1); PG8_STAGE(PG8_SB(1, 0), b3, voffB); PG8_STAGE(PG8_SB(1, 1), b3 + hstepB, voffB); PG8_STAGE(PG8_SA(1, 0), a3, voffA);
;             PG8_WAIT_V(8); PG8_WAIT_L(0); PG8_BAR; PG8_MMA(1, 0, At, B0); PG8_MMA(1, 1, At, B1); PG8_BAR; PG8_SCHED;
;         }
;         if constexpr (ALIGN_EPI) { if (wr == 0) PG8_BAR; }
	s_add_i32 s36, s82, s2
	v_lshl_add_u64 v[208:209], v[208:209], 0, s[8:9]
	s_mov_b32 m0, s36
	ds_read_b128 v[172:175], v236 offset:49152
	ds_read_b128 v[180:183], v236 offset:50176
	ds_read_b128 v[184:187], v236 offset:51200
	ds_read_b128 v[188:191], v236 offset:52224
	ds_read_b128 v[192:195], v236 offset:53248
	ds_read_b128 v[196:199], v236 offset:54272
	ds_read_b128 v[200:203], v236 offset:55296
	ds_read_b128 v[204:207], v236 offset:56320
	global_load_lds_dwordx4 v[208:209], off
	s_add_i32 m0, s36, 0x2000
	s_add_u32 s36, s46, 0x160080
	v_lshl_add_u64 v[208:209], v[210:211], 0, s[8:9]
	s_addc_u32 s37, s47, 0
	s_add_i32 s46, s85, s2
	global_load_lds_dwordx4 v[208:209], off
	v_lshl_add_u64 v[208:209], s[36:37], 0, v[0:1]
	s_mov_b32 m0, s46
	s_nop 0
	global_load_lds_dwordx4 v[208:209], off
	v_lshl_add_u64 v[208:209], s[36:37], 0, v[142:143]
	s_add_i32 m0, s46, 0x2000
	s_nop 0
	global_load_lds_dwordx4 v[208:209], off
	v_lshl_add_u64 v[208:209], v[212:213], 0, s[8:9]
	s_mov_b32 m0, s5
	s_nop 0
	global_load_lds_dwordx4 v[208:209], off
	v_lshl_add_u64 v[208:209], v[214:215], 0, s[8:9]
	s_mov_b32 m0, s59
	s_nop 0
	global_load_lds_dwordx4 v[208:209], off
	s_waitcnt vmcnt(8)
	s_waitcnt lgkmcnt(0)
	s_barrier
	s_setprio 1
	v_mfma_f32_16x16x32_bf16 v[62:65], v[130:133], v[172:175], v[62:65]
	v_mfma_f32_16x16x32_bf16 v[58:61], v[148:151], v[172:175], v[58:61]
	v_mfma_f32_16x16x32_bf16 v[46:49], v[130:133], v[184:187], v[46:49]
	v_mfma_f32_16x16x32_bf16 v[42:45], v[148:151], v[184:187], v[42:45]
	v_mfma_f32_16x16x32_bf16 v[30:33], v[130:133], v[192:195], v[30:33]
	v_mfma_f32_16x16x32_bf16 v[26:29], v[148:151], v[192:195], v[26:29]
	v_mfma_f32_16x16x32_bf16 v[14:17], v[130:133], v[200:203], v[14:17]
	v_mfma_f32_16x16x32_bf16 v[10:13], v[148:151], v[200:203], v[10:13]
	v_mfma_f32_16x16x32_bf16 v[62:65], v[134:137], v[180:183], v[62:65]
	v_mfma_f32_16x16x32_bf16 v[58:61], v[152:155], v[180:183], v[58:61]
	v_mfma_f32_16x16x32_bf16 v[46:49], v[134:137], v[188:191], v[46:49]
	v_mfma_f32_16x16x32_bf16 v[42:45], v[152:155], v[188:191], v[42:45]
	v_mfma_f32_16x16x32_bf16 v[30:33], v[134:137], v[196:199], v[30:33]
	v_mfma_f32_16x16x32_bf16 v[26:29], v[152:155], v[196:199], v[26:29]
	v_mfma_f32_16x16x32_bf16 v[14:17], v[134:137], v[204:207], v[14:17]
	v_mfma_f32_16x16x32_bf16 v[10:13], v[152:155], v[204:207], v[10:13]
	v_mfma_f32_16x16x32_bf16 v[54:57], v[156:159], v[172:175], v[54:57]
	v_mfma_f32_16x16x32_bf16 v[50:53], v[164:167], v[172:175], v[50:53]
	v_mfma_f32_16x16x32_bf16 v[38:41], v[156:159], v[184:187], v[38:41]
	v_mfma_f32_16x16x32_bf16 v[34:37], v[164:167], v[184:187], v[34:37]
	v_mfma_f32_16x16x32_bf16 v[22:25], v[156:159], v[192:195], v[22:25]
	v_mfma_f32_16x16x32_bf16 v[18:21], v[164:167], v[192:195], v[18:21]
	v_mfma_f32_16x16x32_bf16 v[6:9], v[156:159], v[200:203], v[6:9]
	v_mfma_f32_16x16x32_bf16 v[2:5], v[164:167], v[200:203], v[2:5]
	v_mfma_f32_16x16x32_bf16 v[54:57], v[160:163], v[180:183], v[54:57]
	v_mfma_f32_16x16x32_bf16 v[50:53], v[168:171], v[180:183], v[50:53]
	v_mfma_f32_16x16x32_bf16 v[38:41], v[160:163], v[188:191], v[38:41]
	v_mfma_f32_16x16x32_bf16 v[34:37], v[168:171], v[188:191], v[34:37]
	v_mfma_f32_16x16x32_bf16 v[22:25], v[160:163], v[196:199], v[22:25]
	v_mfma_f32_16x16x32_bf16 v[18:21], v[168:171], v[196:199], v[18:21]
	v_mfma_f32_16x16x32_bf16 v[6:9], v[160:163], v[204:207], v[6:9]
	v_mfma_f32_16x16x32_bf16 v[2:5], v[168:171], v[204:207], v[2:5]
	s_setprio 0
	s_barrier
	s_add_u32 s77, s77, 0x100
	s_addc_u32 s78, s78, 0
	s_cmp_ge_i32 s79, s75
	s_mov_b64 s[36:37], s[38:39]
	s_mov_b32 s46, s79
	s_cbranch_scc0 .LBB0_1893
	v_readlane_b32 s2, v252, 14
	v_readlane_b32 s3, v252, 15
	s_and_b64 vcc, exec, s[2:3]
	s_cbranch_vccz .LBB0_1896
	s_barrier

; #define PG8_STAGE(bufoff, gbase, voff) do { _Pragma("unroll") for (int _i = 0; _i < 2; ++_i) \
;         __builtin_amdgcn_global_load_lds((const unsigned*)((const char*)(gbase) + (voff)[_i]), (LAS unsigned*)(lds + (bufoff) + ldsw + _i * 8192), 16, 0, 0); } while (0)
; #define PG8_LDA(dst, b, h) do { _Pragma("unroll") for (int m = 0; m < 4; ++m) _Pragma("unroll") for (int k = 0; k < 2; ++k) dst[m][k] = *(const LAS bf16x8*)(lds + PG8_SA(b, h) + aoff + m * 2048 + k * 1024); } while (0)
; #define PG8_LDB(dst, b, h) do { _Pragma("unroll") for (int n = 0; n < 2; ++n) _Pragma("unroll") for (int k = 0; k < 2; ++k) dst[n][k] = *(const LAS bf16x8*)(lds + PG8_SB(b, h) + boff + n * 2048 + k * 1024); } while (0)
; #define PG8_MMA(ai, bj, At, Bt) do { __builtin_amdgcn_s_setprio(1); _Pragma("unroll") for (int m = 0; m < 4; ++m) _Pragma("unroll") for (int n = 0; n < 2; ++n) _Pragma("unroll") for (int k = 0; k < 2; ++k) \
;         acc[ai][bj][m][n] = __builtin_amdgcn_mfma_f32_16x16x32_bf16(Bt[n][k], At[m][k], acc[ai][bj][m][n], 0, 0, 0); __builtin_amdgcn_s_setprio(0); } while (0)
; #define PG8_WAIT_V(n) asm volatile("s_waitcnt vmcnt(" #n ")" ::: "memory")
; #define PG8_WAIT_L(n) asm volatile("s_waitcnt lgkmcnt(" #n ")" ::: "memory")
; #define PG8_BAR __builtin_amdgcn_s_barrier()
; #define PG8_SCHED __builtin_amdgcn_sched_barrier(0)
; template <class Epi, class Sched, int LDA, int LDB, bool ALIGN_EPI = true>
; __device__ __forceinline__ void gemm_phase(LAS unsigned char* lds, const Gemm g, const Sched& S, const Epi& E, int wave) {
;     ...
;             const bool last = (t == nt - 2);
;             const char* a1 = cA + (size_t)(t + 1) * kstep;
;             const char* a2 = last ? nA : cA + (size_t)(t + 2) * kstep; const char* b2 = last ? nB : cB + (size_t)(t + 2) * kstep;
;             const char* a3 = a2 + kstep; const char* b3 = b2 + kstep;
;             PG8_LDB(B0, 0, 0); PG8_LDB(B1, 0, 1); PG8_SCHED; PG8_LDA(At, 0, 0); PG8_STAGE(PG8_SA(1, 1), a1 + hstepA, voffA);
;             PG8_WAIT_V(8); PG8_WAIT_L(0); PG8_BAR; PG8_MMA(0, 0, At, B0); PG8_MMA(0, 1, At, B1); PG8_BAR; PG8_SCHED;
;             PG8_LDA(At, 0, 1); PG8_STAGE(PG8_SB(0, 0), b2, voffB); PG8_STAGE(PG8_SB(0, 1), b2 + hstepB, voffB); PG8_STAGE(PG8_SA(0, 0), a2, voffA);
;             PG8_WAIT_V(8); PG8_WAIT_L(0); PG8_BAR; PG8_MMA(1, 0, At, B0); PG8_MMA(1, 1, At, B1); PG8_BAR; PG8_SCHED;
.LBB0_2254:
	s_add_u32 s2, s0, 0x100
	s_addc_u32 s3, s1, 0
	s_add_i32 s64, 0, 0x10000
	s_cmp_eq_u32 s59, 28
	s_cselect_b32 s29, s15, s3
	s_cselect_b32 s28, s14, s2
	v_add_u32_e32 v0, s64, v161
	s_cselect_b32 s25, s13, s58
	s_cselect_b32 s24, s48, s49
	s_add_i32 s65, 0, 0x14000
	ds_read_b128 v[144:147], v0
	ds_read_b128 v[148:151], v0 offset:1024
	ds_read_b128 v[152:155], v0 offset:2048
	ds_read_b128 v[156:159], v0 offset:3072
	v_add_u32_e32 v0, s65, v161
	ds_read_b128 v[164:167], v0
	ds_read_b128 v[168:171], v0 offset:1024
	ds_read_b128 v[172:175], v0 offset:2048
	ds_read_b128 v[180:183], v0 offset:3072
	v_lshl_add_u64 v[216:217], s[0:1], 0, v[140:141]
	s_add_i32 m0, s19, 0xc000
	ds_read_b128 v[184:187], v163
	ds_read_b128 v[188:191], v163 offset:1024
	ds_read_b128 v[192:195], v163 offset:2048
	ds_read_b128 v[196:199], v163 offset:3072
	ds_read_b128 v[200:203], v163 offset:4096
	ds_read_b128 v[204:207], v163 offset:5120
	ds_read_b128 v[208:211], v163 offset:6144
	ds_read_b128 v[212:215], v163 offset:7168
	global_load_lds_dwordx4 v[216:217], off
	v_lshl_add_u64 v[216:217], s[0:1], 0, v[142:143]
	s_add_i32 m0, s19, 0xe000
	s_nop 0
	global_load_lds_dwordx4 v[216:217], off
	s_waitcnt vmcnt(8)
	s_waitcnt lgkmcnt(0)
	s_barrier
	s_setprio 1
	v_mfma_f32_16x16x32_bf16 v[126:129], v[144:147], v[184:187], v[126:129]
	v_mfma_f32_16x16x32_bf16 v[122:125], v[152:155], v[184:187], v[122:125]
	v_mfma_f32_16x16x32_bf16 v[118:121], v[144:147], v[192:195], v[118:121]
	v_mfma_f32_16x16x32_bf16 v[114:117], v[152:155], v[192:195], v[114:117]
	v_mfma_f32_16x16x32_bf16 v[110:113], v[144:147], v[200:203], v[110:113]
	v_mfma_f32_16x16x32_bf16 v[106:109], v[152:155], v[200:203], v[106:109]
	v_mfma_f32_16x16x32_bf16 v[102:105], v[144:147], v[208:211], v[102:105]
	v_mfma_f32_16x16x32_bf16 v[98:101], v[152:155], v[208:211], v[98:101]
	v_mfma_f32_16x16x32_bf16 v[126:129], v[148:151], v[188:191], v[126:129]
	v_mfma_f32_16x16x32_bf16 v[122:125], v[156:159], v[188:191], v[122:125]
	v_mfma_f32_16x16x32_bf16 v[118:121], v[148:151], v[196:199], v[118:121]
	v_mfma_f32_16x16x32_bf16 v[114:117], v[156:159], v[196:199], v[114:117]
	v_mfma_f32_16x16x32_bf16 v[110:113], v[148:151], v[204:207], v[110:113]
	v_mfma_f32_16x16x32_bf16 v[106:109], v[156:159], v[204:207], v[106:109]
	v_mfma_f32_16x16x32_bf16 v[102:105], v[148:151], v[212:215], v[102:105]
	v_mfma_f32_16x16x32_bf16 v[98:101], v[156:159], v[212:215], v[98:101]
	v_mfma_f32_16x16x32_bf16 v[62:65], v[164:167], v[184:187], v[62:65]
	v_mfma_f32_16x16x32_bf16 v[58:61], v[172:175], v[184:187], v[58:61]
	v_mfma_f32_16x16x32_bf16 v[54:57], v[164:167], v[192:195], v[54:57]
	v_mfma_f32_16x16x32_bf16 v[50:53], v[172:175], v[192:195], v[50:53]
	v_mfma_f32_16x16x32_bf16 v[46:49], v[164:167], v[200:203], v[46:49]
	v_mfma_f32_16x16x32_bf16 v[42:45], v[172:175], v[200:203], v[42:45]
	v_mfma_f32_16x16x32_bf16 v[38:41], v[164:167], v[208:211], v[38:41]
	v_mfma_f32_16x16x32_bf16 v[34:37], v[172:175], v[208:211], v[34:37]
	v_mfma_f32_16x16x32_bf16 v[62:65], v[168:171], v[188:191], v[62:65]
	v_mfma_f32_16x16x32_bf16 v[58:61], v[180:183], v[188:191], v[58:61]
	v_mfma_f32_16x16x32_bf16 v[54:57], v[168:171], v[196:199], v[54:57]
	v_mfma_f32_16x16x32_bf16 v[50:53], v[180:183], v[196:199], v[50:53]
	v_mfma_f32_16x16x32_bf16 v[46:49], v[168:171], v[204:207], v[46:49]
	v_mfma_f32_16x16x32_bf16 v[42:45], v[180:183], v[204:207], v[42:45]
	v_mfma_f32_16x16x32_bf16 v[38:41], v[168:171], v[212:215], v[38:41]
	v_mfma_f32_16x16x32_bf16 v[34:37], v[180:183], v[212:215], v[34:37]
	s_setprio 0
	s_barrier
	s_add_i32 s0, s64, s61
	v_lshl_add_u64 v[216:217], s[24:25], 0, v[132:133]
	s_mov_b32 m0, s0
	ds_read_b128 v[184:187], v163 offset:16384
	ds_read_b128 v[188:191], v163 offset:17408
	ds_read_b128 v[192:195], v163 offset:18432
	ds_read_b128 v[196:199], v163 offset:19456
	ds_read_b128 v[200:203], v163 offset:20480
	ds_read_b128 v[204:207], v163 offset:21504
	ds_read_b128 v[208:211], v163 offset:22528
	ds_read_b128 v[212:215], v163 offset:23552
	global_load_lds_dwordx4 v[216:217], off
	s_add_i32 m0, s0, 0x2000
	s_add_u32 s0, s24, 0x80000
	v_lshl_add_u64 v[218:219], s[24:25], 0, v[136:137]
	s_addc_u32 s1, s25, 0
	s_add_i32 s64, s65, s61
	global_load_lds_dwordx4 v[218:219], off
	v_lshl_add_u64 v[220:221], s[0:1], 0, v[132:133]
	s_mov_b32 m0, s64
	v_lshl_add_u64 v[222:223], s[28:29], 0, v[134:135]
	global_load_lds_dwordx4 v[220:221], off
	v_lshl_add_u64 v[220:221], s[0:1], 0, v[136:137]
	s_add_i32 m0, s64, 0x2000
	s_nop 0
	global_load_lds_dwordx4 v[220:221], off
	v_lshl_add_u64 v[220:221], s[28:29], 0, v[130:131]
	s_mov_b32 m0, s19
	s_nop 0
	global_load_lds_dwordx4 v[220:221], off
	s_mov_b32 m0, s35
	s_nop 0
	global_load_lds_dwordx4 v[222:223], off
	s_waitcnt vmcnt(8)
	s_waitcnt lgkmcnt(0)
	s_barrier
; #define PG8_STAGE(bufoff, gbase, voff) do { _Pragma("unroll") for (int _i = 0; _i < 2; ++_i) \
;         __builtin_amdgcn_global_load_lds((const unsigned*)((const char*)(gbase) + (voff)[_i]), (LAS unsigned*)(lds + (bufoff) + ldsw + _i * 8192), 16, 0, 0); } while (0)
; #define PG8_LDA(dst, b, h) do { _Pragma("unroll") for (int m = 0; m < 4; ++m) _Pragma("unroll") for (int k = 0; k < 2; ++k) dst[m][k] = *(const LAS bf16x8*)(lds + PG8_SA(b, h) + aoff + m * 2048 + k * 1024); } while (0)
; #define PG8_LDB(dst, b, h) do { _Pragma("unroll") for (int n = 0; n < 2; ++n) _Pragma("unroll") for (int k = 0; k < 2; ++k) dst[n][k] = *(const LAS bf16x8*)(lds + PG8_SB(b, h) + boff + n * 2048 + k * 1024); } while (0)
; #define PG8_MMA(ai, bj, At, Bt) do { __builtin_amdgcn_s_setprio(1); _Pragma("unroll") for (int m = 0; m < 4; ++m) _Pragma("unroll") for (int n = 0; n < 2; ++n) _Pragma("unroll") for (int k = 0; k < 2; ++k) \
;         acc[ai][bj][m][n] = __builtin_amdgcn_mfma_f32_16x16x32_bf16(Bt[n][k], At[m][k], acc[ai][bj][m][n], 0, 0, 0); __builtin_amdgcn_s_setprio(0); } while (0)
; #define PG8_WAIT_V(n) asm volatile("s_waitcnt vmcnt(" #n ")" ::: "memory")
; #define PG8_WAIT_L(n) asm volatile("s_waitcnt lgkmcnt(" #n ")" ::: "memory")
; #define PG8_BAR __builtin_amdgcn_s_barrier()
; #define PG8_SCHED __builtin_amdgcn_sched_barrier(0)
; template <class Epi, class Sched, int LDA, int LDB, bool ALIGN_EPI = true>
; __device__ __forceinline__ void gemm_phase(LAS unsigned char* lds, const Gemm g, const Sched& S, const Epi& E, int wave) {
;     ...
;             PG8_WAIT_V(8); PG8_WAIT_L(0); PG8_BAR; PG8_MMA(1, 0, At, B0); PG8_MMA(1, 1, At, B1); PG8_BAR; PG8_SCHED;
;             PG8_LDB(B0, 1, 0); PG8_LDB(B1, 1, 1); PG8_SCHED; PG8_LDA(At, 1, 0); PG8_STAGE(PG8_SA(0, 1), a2 + hstepA, voffA);
;             PG8_WAIT_V(8); PG8_WAIT_L(0); PG8_BAR; PG8_MMA(0, 0, At, B0); PG8_MMA(0, 1, At, B1); PG8_BAR; PG8_SCHED;
;             PG8_LDA(At, 1, 1); PG8_STAGE(PG8_SB(1, 0), b3, voffB); PG8_STAGE(PG8_SB(1, 1), b3 + hstepB, voffB); PG8_STAGE(PG8_SA(1, 0), a3, voffA);
	s_setprio 1
	v_mfma_f32_16x16x32_bf16 v[94:97], v[144:147], v[184:187], v[94:97]
	v_mfma_f32_16x16x32_bf16 v[90:93], v[152:155], v[184:187], v[90:93]
	v_mfma_f32_16x16x32_bf16 v[86:89], v[144:147], v[192:195], v[86:89]
	v_mfma_f32_16x16x32_bf16 v[82:85], v[152:155], v[192:195], v[82:85]
	v_mfma_f32_16x16x32_bf16 v[78:81], v[144:147], v[200:203], v[78:81]
	v_mfma_f32_16x16x32_bf16 v[74:77], v[152:155], v[200:203], v[74:77]
	v_mfma_f32_16x16x32_bf16 v[70:73], v[144:147], v[208:211], v[70:73]
	v_mfma_f32_16x16x32_bf16 v[66:69], v[152:155], v[208:211], v[66:69]
	v_mfma_f32_16x16x32_bf16 v[94:97], v[148:151], v[188:191], v[94:97]
	v_mfma_f32_16x16x32_bf16 v[90:93], v[156:159], v[188:191], v[90:93]
	v_mfma_f32_16x16x32_bf16 v[86:89], v[148:151], v[196:199], v[86:89]
	v_mfma_f32_16x16x32_bf16 v[82:85], v[156:159], v[196:199], v[82:85]
	v_mfma_f32_16x16x32_bf16 v[78:81], v[148:151], v[204:207], v[78:81]
	v_mfma_f32_16x16x32_bf16 v[74:77], v[156:159], v[204:207], v[74:77]
	v_mfma_f32_16x16x32_bf16 v[70:73], v[148:151], v[212:215], v[70:73]
	v_mfma_f32_16x16x32_bf16 v[66:69], v[156:159], v[212:215], v[66:69]
	v_mfma_f32_16x16x32_bf16 v[30:33], v[164:167], v[184:187], v[30:33]
	v_mfma_f32_16x16x32_bf16 v[26:29], v[172:175], v[184:187], v[26:29]
	v_mfma_f32_16x16x32_bf16 v[22:25], v[164:167], v[192:195], v[22:25]
	v_mfma_f32_16x16x32_bf16 v[18:21], v[172:175], v[192:195], v[18:21]
	v_mfma_f32_16x16x32_bf16 v[14:17], v[164:167], v[200:203], v[14:17]
	v_mfma_f32_16x16x32_bf16 v[10:13], v[172:175], v[200:203], v[10:13]
	v_mfma_f32_16x16x32_bf16 v[6:9], v[164:167], v[208:211], v[6:9]
	v_mfma_f32_16x16x32_bf16 v[2:5], v[172:175], v[208:211], v[2:5]
	v_mfma_f32_16x16x32_bf16 v[30:33], v[168:171], v[188:191], v[30:33]
	v_mfma_f32_16x16x32_bf16 v[26:29], v[180:183], v[188:191], v[26:29]
	v_mfma_f32_16x16x32_bf16 v[22:25], v[168:171], v[196:199], v[22:25]
	v_mfma_f32_16x16x32_bf16 v[18:21], v[180:183], v[196:199], v[18:21]
	v_mfma_f32_16x16x32_bf16 v[14:17], v[168:171], v[204:207], v[14:17]
	v_mfma_f32_16x16x32_bf16 v[10:13], v[180:183], v[204:207], v[10:13]
	v_mfma_f32_16x16x32_bf16 v[6:9], v[168:171], v[212:215], v[6:9]
	v_mfma_f32_16x16x32_bf16 v[2:5], v[180:183], v[212:215], v[2:5]
	s_setprio 0
	s_barrier
	s_add_i32 s64, 0, 0x18000
	v_add_u32_e32 v0, s64, v161
	s_add_i32 s65, 0, 0x1c000
	ds_read_b128 v[144:147], v0
	ds_read_b128 v[148:151], v0 offset:1024
	ds_read_b128 v[152:155], v0 offset:2048
	ds_read_b128 v[156:159], v0 offset:3072
	v_add_u32_e32 v0, s65, v161
	ds_read_b128 v[164:167], v0
	ds_read_b128 v[168:171], v0 offset:1024
	ds_read_b128 v[172:175], v0 offset:2048
	ds_read_b128 v[180:183], v0 offset:3072
	s_add_u32 s0, s28, 0x84000
	s_addc_u32 s1, s29, 0
	s_mov_b32 m0, s36
	v_lshl_add_u64 v[224:225], s[0:1], 0, v[130:131]
	ds_read_b128 v[184:187], v163 offset:32768
	ds_read_b128 v[188:191], v163 offset:33792
	ds_read_b128 v[192:195], v163 offset:34816
	ds_read_b128 v[196:199], v163 offset:35840
	ds_read_b128 v[200:203], v163 offset:36864
	ds_read_b128 v[204:207], v163 offset:37888
	ds_read_b128 v[208:211], v163 offset:38912
	ds_read_b128 v[212:215], v163 offset:39936
	global_load_lds_dwordx4 v[224:225], off
	v_lshl_add_u64 v[224:225], s[0:1], 0, v[134:135]
	s_mov_b32 m0, s37
	s_nop 0
	global_load_lds_dwordx4 v[224:225], off
	s_waitcnt vmcnt(8)
	s_waitcnt lgkmcnt(0)
	s_barrier
	s_setprio 1
	v_mfma_f32_16x16x32_bf16 v[126:129], v[144:147], v[184:187], v[126:129]
	v_mfma_f32_16x16x32_bf16 v[122:125], v[152:155], v[184:187], v[122:125]
	v_mfma_f32_16x16x32_bf16 v[118:121], v[144:147], v[192:195], v[118:121]
	v_mfma_f32_16x16x32_bf16 v[114:117], v[152:155], v[192:195], v[114:117]
	v_mfma_f32_16x16x32_bf16 v[110:113], v[144:147], v[200:203], v[110:113]
	v_mfma_f32_16x16x32_bf16 v[106:109], v[152:155], v[200:203], v[106:109]
	v_mfma_f32_16x16x32_bf16 v[102:105], v[144:147], v[208:211], v[102:105]
	v_mfma_f32_16x16x32_bf16 v[98:101], v[152:155], v[208:211], v[98:101]
	v_mfma_f32_16x16x32_bf16 v[126:129], v[148:151], v[188:191], v[126:129]
	v_mfma_f32_16x16x32_bf16 v[122:125], v[156:159], v[188:191], v[122:125]
	v_mfma_f32_16x16x32_bf16 v[118:121], v[148:151], v[196:199], v[118:121]
	v_mfma_f32_16x16x32_bf16 v[114:117], v[156:159], v[196:199], v[114:117]
	v_mfma_f32_16x16x32_bf16 v[110:113], v[148:151], v[204:207], v[110:113]
	v_mfma_f32_16x16x32_bf16 v[106:109], v[156:159], v[204:207], v[106:109]
	v_mfma_f32_16x16x32_bf16 v[102:105], v[148:151], v[212:215], v[102:105]
	v_mfma_f32_16x16x32_bf16 v[98:101], v[156:159], v[212:215], v[98:101]
	v_mfma_f32_16x16x32_bf16 v[62:65], v[164:167], v[184:187], v[62:65]
	v_mfma_f32_16x16x32_bf16 v[58:61], v[172:175], v[184:187], v[58:61]
	v_mfma_f32_16x16x32_bf16 v[54:57], v[164:167], v[192:195], v[54:57]
	v_mfma_f32_16x16x32_bf16 v[50:53], v[172:175], v[192:195], v[50:53]
	v_mfma_f32_16x16x32_bf16 v[46:49], v[164:167], v[200:203], v[46:49]
	v_mfma_f32_16x16x32_bf16 v[42:45], v[172:175], v[200:203], v[42:45]
	v_mfma_f32_16x16x32_bf16 v[38:41], v[164:167], v[208:211], v[38:41]
	v_mfma_f32_16x16x32_bf16 v[34:37], v[172:175], v[208:211], v[34:37]
	v_mfma_f32_16x16x32_bf16 v[62:65], v[168:171], v[188:191], v[62:65]
	v_mfma_f32_16x16x32_bf16 v[58:61], v[180:183], v[188:191], v[58:61]
	v_mfma_f32_16x16x32_bf16 v[54:57], v[168:171], v[196:199], v[54:57]
	v_mfma_f32_16x16x32_bf16 v[50:53], v[180:183], v[196:199], v[50:53]
	v_mfma_f32_16x16x32_bf16 v[46:49], v[168:171], v[204:207], v[46:49]
	v_mfma_f32_16x16x32_bf16 v[42:45], v[180:183], v[204:207], v[42:45]
	v_mfma_f32_16x16x32_bf16 v[38:41], v[168:171], v[212:215], v[38:41]
	v_mfma_f32_16x16x32_bf16 v[34:37], v[180:183], v[212:215], v[34:37]
	s_setprio 0
	s_barrier
; #define PG8_STAGE(bufoff, gbase, voff) do { _Pragma("unroll") for (int _i = 0; _i < 2; ++_i) \
;         __builtin_amdgcn_global_load_lds((const unsigned*)((const char*)(gbase) + (voff)[_i]), (LAS unsigned*)(lds + (bufoff) + ldsw + _i * 8192), 16, 0, 0); } while (0)
; #define PG8_LDA(dst, b, h) do { _Pragma("unroll") for (int m = 0; m < 4; ++m) _Pragma("unroll") for (int k = 0; k < 2; ++k) dst[m][k] = *(const LAS bf16x8*)(lds + PG8_SA(b, h) + aoff + m * 2048 + k * 1024); } while (0)
; #define PG8_MMA(ai, bj, At, Bt) do { __builtin_amdgcn_s_setprio(1); _Pragma("unroll") for (int m = 0; m < 4; ++m) _Pragma("unroll") for (int n = 0; n < 2; ++n) _Pragma("unroll") for (int k = 0; k < 2; ++k) \
;         acc[ai][bj][m][n] = __builtin_amdgcn_mfma_f32_16x16x32_bf16(Bt[n][k], At[m][k], acc[ai][bj][m][n], 0, 0, 0); __builtin_amdgcn_s_setprio(0); } while (0)
; #define PG8_WAIT_V(n) asm volatile("s_waitcnt vmcnt(" #n ")" ::: "memory")
; #define PG8_WAIT_L(n) asm volatile("s_waitcnt lgkmcnt(" #n ")" ::: "memory")
; #define PG8_BAR __builtin_amdgcn_s_barrier()
; #define PG8_SCHED __builtin_amdgcn_sched_barrier(0)
; template <class Epi, class Sched, int LDA, int LDB, bool ALIGN_EPI = true>
; __device__ __forceinline__ void gemm_phase(LAS unsigned char* lds, const Gemm g, const Sched& S, const Epi& E, int wave) {
;     ...
;             PG8_LDA(At, 1, 1); PG8_STAGE(PG8_SB(1, 0), b3, voffB); PG8_STAGE(PG8_SB(1, 1), b3 + hstepB, voffB); PG8_STAGE(PG8_SA(1, 0), a3, voffA);
;             PG8_WAIT_V(8); PG8_WAIT_L(0); PG8_BAR; PG8_MMA(1, 0, At, B0); PG8_MMA(1, 1, At, B1); PG8_BAR; PG8_SCHED;
;         }
;         if constexpr (ALIGN_EPI) { if (wr == 0) PG8_BAR; }
	s_add_i32 s0, s64, s61
	v_lshl_add_u64 v[216:217], v[216:217], 0, s[70:71]
	s_mov_b32 m0, s0
	ds_read_b128 v[184:187], v163 offset:49152
	ds_read_b128 v[188:191], v163 offset:50176
	ds_read_b128 v[192:195], v163 offset:51200
	ds_read_b128 v[196:199], v163 offset:52224
	ds_read_b128 v[200:203], v163 offset:53248
	ds_read_b128 v[204:207], v163 offset:54272
	ds_read_b128 v[208:211], v163 offset:55296
	ds_read_b128 v[212:215], v163 offset:56320
	global_load_lds_dwordx4 v[216:217], off
	s_add_i32 m0, s0, 0x2000
	s_add_u32 s0, s24, 0x80080
	v_lshl_add_u64 v[216:217], v[218:219], 0, s[70:71]
	s_addc_u32 s1, s25, 0
	s_add_i32 s24, s65, s61
	global_load_lds_dwordx4 v[216:217], off
	v_lshl_add_u64 v[216:217], s[0:1], 0, v[132:133]
	s_mov_b32 m0, s24
	s_nop 0
	global_load_lds_dwordx4 v[216:217], off
	v_lshl_add_u64 v[216:217], s[0:1], 0, v[136:137]
	s_add_i32 m0, s24, 0x2000
	s_nop 0
	global_load_lds_dwordx4 v[216:217], off
	v_lshl_add_u64 v[216:217], v[220:221], 0, s[70:71]
	s_mov_b32 m0, s38
	s_nop 0
	global_load_lds_dwordx4 v[216:217], off
	v_lshl_add_u64 v[216:217], v[222:223], 0, s[70:71]
	s_mov_b32 m0, s39
	s_nop 0
	global_load_lds_dwordx4 v[216:217], off
	s_waitcnt vmcnt(8)
	s_waitcnt lgkmcnt(0)
	s_barrier
	s_setprio 1
	v_mfma_f32_16x16x32_bf16 v[94:97], v[144:147], v[184:187], v[94:97]
	v_mfma_f32_16x16x32_bf16 v[90:93], v[152:155], v[184:187], v[90:93]
	v_mfma_f32_16x16x32_bf16 v[86:89], v[144:147], v[192:195], v[86:89]
	v_mfma_f32_16x16x32_bf16 v[82:85], v[152:155], v[192:195], v[82:85]
	v_mfma_f32_16x16x32_bf16 v[78:81], v[144:147], v[200:203], v[78:81]
	v_mfma_f32_16x16x32_bf16 v[74:77], v[152:155], v[200:203], v[74:77]
	v_mfma_f32_16x16x32_bf16 v[70:73], v[144:147], v[208:211], v[70:73]
	v_mfma_f32_16x16x32_bf16 v[66:69], v[152:155], v[208:211], v[66:69]
	v_mfma_f32_16x16x32_bf16 v[94:97], v[148:151], v[188:191], v[94:97]
	v_mfma_f32_16x16x32_bf16 v[90:93], v[156:159], v[188:191], v[90:93]
	v_mfma_f32_16x16x32_bf16 v[86:89], v[148:151], v[196:199], v[86:89]
	v_mfma_f32_16x16x32_bf16 v[82:85], v[156:159], v[196:199], v[82:85]
	v_mfma_f32_16x16x32_bf16 v[78:81], v[148:151], v[204:207], v[78:81]
	v_mfma_f32_16x16x32_bf16 v[74:77], v[156:159], v[204:207], v[74:77]
	v_mfma_f32_16x16x32_bf16 v[70:73], v[148:151], v[212:215], v[70:73]
	v_mfma_f32_16x16x32_bf16 v[66:69], v[156:159], v[212:215], v[66:69]
	v_mfma_f32_16x16x32_bf16 v[30:33], v[164:167], v[184:187], v[30:33]
	v_mfma_f32_16x16x32_bf16 v[26:29], v[172:175], v[184:187], v[26:29]
	v_mfma_f32_16x16x32_bf16 v[22:25], v[164:167], v[192:195], v[22:25]
	v_mfma_f32_16x16x32_bf16 v[18:21], v[172:175], v[192:195], v[18:21]
	v_mfma_f32_16x16x32_bf16 v[14:17], v[164:167], v[200:203], v[14:17]
	v_mfma_f32_16x16x32_bf16 v[10:13], v[172:175], v[200:203], v[10:13]
	v_mfma_f32_16x16x32_bf16 v[6:9], v[164:167], v[208:211], v[6:9]
	v_mfma_f32_16x16x32_bf16 v[2:5], v[172:175], v[208:211], v[2:5]
	v_mfma_f32_16x16x32_bf16 v[30:33], v[168:171], v[188:191], v[30:33]
	v_mfma_f32_16x16x32_bf16 v[26:29], v[180:183], v[188:191], v[26:29]
	v_mfma_f32_16x16x32_bf16 v[22:25], v[168:171], v[196:199], v[22:25]
	v_mfma_f32_16x16x32_bf16 v[18:21], v[180:183], v[196:199], v[18:21]
	v_mfma_f32_16x16x32_bf16 v[14:17], v[168:171], v[204:207], v[14:17]
	v_mfma_f32_16x16x32_bf16 v[10:13], v[180:183], v[204:207], v[10:13]
	v_mfma_f32_16x16x32_bf16 v[6:9], v[168:171], v[212:215], v[6:9]
	v_mfma_f32_16x16x32_bf16 v[2:5], v[180:183], v[212:215], v[2:5]
	s_setprio 0
	s_barrier
	s_add_i32 s59, s59, 2
	s_add_u32 s49, s49, 0x100
	s_addc_u32 s58, s58, 0
	s_cmp_gt_u32 s59, 29
	s_mov_b64 s[0:1], s[2:3]
	s_cbranch_scc0 .LBB0_2254
	v_readlane_b32 s0, v252, 14
	v_readlane_b32 s1, v252, 15
	s_and_b64 vcc, exec, s[0:1]
	s_cbranch_vccz .LBB0_2257
	s_barrier

; #define PG8_STAGE(bufoff, gbase, voff) do { _Pragma("unroll") for (int _i = 0; _i < 2; ++_i) \
;         __builtin_amdgcn_global_load_lds((const unsigned*)((const char*)(gbase) + (voff)[_i]), (LAS unsigned*)(lds + (bufoff) + ldsw + _i * 8192), 16, 0, 0); } while (0)
; #define PG8_LDA(dst, b, h) do { _Pragma("unroll") for (int m = 0; m < 4; ++m) _Pragma("unroll") for (int k = 0; k < 2; ++k) dst[m][k] = *(const LAS bf16x8*)(lds + PG8_SA(b, h) + aoff + m * 2048 + k * 1024); } while (0)
; #define PG8_LDB(dst, b, h) do { _Pragma("unroll") for (int n = 0; n < 2; ++n) _Pragma("unroll") for (int k = 0; k < 2; ++k) dst[n][k] = *(const LAS bf16x8*)(lds + PG8_SB(b, h) + boff + n * 2048 + k * 1024); } while (0)
; #define PG8_MMA(ai, bj, At, Bt) do { __builtin_amdgcn_s_setprio(1); _Pragma("unroll") for (int m = 0; m < 4; ++m) _Pragma("unroll") for (int n = 0; n < 2; ++n) _Pragma("unroll") for (int k = 0; k < 2; ++k) \
;         acc[ai][bj][m][n] = __builtin_amdgcn_mfma_f32_16x16x32_bf16(Bt[n][k], At[m][k], acc[ai][bj][m][n], 0, 0, 0); __builtin_amdgcn_s_setprio(0); } while (0)
; #define PG8_WAIT_V(n) asm volatile("s_waitcnt vmcnt(" #n ")" ::: "memory")
; #define PG8_WAIT_L(n) asm volatile("s_waitcnt lgkmcnt(" #n ")" ::: "memory")
; #define PG8_BAR __builtin_amdgcn_s_barrier()
; #define PG8_SCHED __builtin_amdgcn_sched_barrier(0)
; template <class Epi, class Sched, int LDA, int LDB, bool ALIGN_EPI = true>
; __device__ __forceinline__ void gemm_phase(LAS unsigned char* lds, const Gemm g, const Sched& S, const Epi& E, int wave) {
;     ...
;             const bool last = (t == nt - 2);
;             const char* a1 = cA + (size_t)(t + 1) * kstep;
;             const char* a2 = last ? nA : cA + (size_t)(t + 2) * kstep; const char* b2 = last ? nB : cB + (size_t)(t + 2) * kstep;
;             const char* a3 = a2 + kstep; const char* b3 = b2 + kstep;
;             PG8_LDB(B0, 0, 0); PG8_LDB(B1, 0, 1); PG8_SCHED; PG8_LDA(At, 0, 0); PG8_STAGE(PG8_SA(1, 1), a1 + hstepA, voffA);
;             PG8_WAIT_V(8); PG8_WAIT_L(0); PG8_BAR; PG8_MMA(0, 0, At, B0); PG8_MMA(0, 1, At, B1); PG8_BAR; PG8_SCHED;
;             PG8_LDA(At, 0, 1); PG8_STAGE(PG8_SB(0, 0), b2, voffB); PG8_STAGE(PG8_SB(0, 1), b2 + hstepB, voffB); PG8_STAGE(PG8_SA(0, 0), a2, voffA);
;             PG8_WAIT_V(8); PG8_WAIT_L(0); PG8_BAR; PG8_MMA(1, 0, At, B0); PG8_MMA(1, 1, At, B1); PG8_BAR; PG8_SCHED;
.LBB0_2415:
	s_add_u32 s12, s10, 0xfff80080
	s_addc_u32 s13, s11, -1
	s_add_i32 s39, 0, 0x10000
	s_cmp_eq_u32 s38, 28
	s_cselect_b32 s15, s1, s13
	s_cselect_b32 s14, s3, s12
	v_add_u32_e32 v140, s39, v143
	s_cselect_b32 s13, s7, s37
	s_cselect_b32 s12, s6, s36
	s_add_i32 s46, 0, 0x14000
	ds_read_b128 v[146:149], v140
	ds_read_b128 v[150:153], v140 offset:1024
	ds_read_b128 v[154:157], v140 offset:2048
	ds_read_b128 v[158:161], v140 offset:3072
	v_add_u32_e32 v140, s46, v143
	ds_read_b128 v[162:165], v140
	ds_read_b128 v[166:169], v140 offset:1024
	ds_read_b128 v[170:173], v140 offset:2048
	ds_read_b128 v[180:183], v140 offset:3072
	v_lshl_add_u64 v[140:141], s[10:11], 0, v[136:137]
	s_add_i32 m0, s18, 0xc000
	ds_read_b128 v[184:187], v145
	ds_read_b128 v[188:191], v145 offset:1024
	ds_read_b128 v[192:195], v145 offset:2048
	ds_read_b128 v[196:199], v145 offset:3072
	ds_read_b128 v[200:203], v145 offset:4096
	ds_read_b128 v[204:207], v145 offset:5120
	ds_read_b128 v[208:211], v145 offset:6144
	ds_read_b128 v[212:215], v145 offset:7168
	global_load_lds_dwordx4 v[140:141], off
	v_lshl_add_u64 v[140:141], s[10:11], 0, v[138:139]
	s_add_i32 m0, s18, 0xe000
	s_nop 0
	global_load_lds_dwordx4 v[140:141], off
	s_waitcnt vmcnt(8)
	s_waitcnt lgkmcnt(0)
	s_barrier
	s_setprio 1
	v_mfma_f32_16x16x32_bf16 v[126:129], v[146:149], v[184:187], v[126:129]
	v_mfma_f32_16x16x32_bf16 v[122:125], v[154:157], v[184:187], v[122:125]
	v_mfma_f32_16x16x32_bf16 v[114:117], v[146:149], v[192:195], v[114:117]
	v_mfma_f32_16x16x32_bf16 v[106:109], v[154:157], v[192:195], v[106:109]
	v_mfma_f32_16x16x32_bf16 v[98:101], v[146:149], v[200:203], v[98:101]
	v_mfma_f32_16x16x32_bf16 v[90:93], v[154:157], v[200:203], v[90:93]
	v_mfma_f32_16x16x32_bf16 v[82:85], v[146:149], v[208:211], v[82:85]
	v_mfma_f32_16x16x32_bf16 v[74:77], v[154:157], v[208:211], v[74:77]
	v_mfma_f32_16x16x32_bf16 v[126:129], v[150:153], v[188:191], v[126:129]
	v_mfma_f32_16x16x32_bf16 v[122:125], v[158:161], v[188:191], v[122:125]
	v_mfma_f32_16x16x32_bf16 v[114:117], v[150:153], v[196:199], v[114:117]
	v_mfma_f32_16x16x32_bf16 v[106:109], v[158:161], v[196:199], v[106:109]
	v_mfma_f32_16x16x32_bf16 v[98:101], v[150:153], v[204:207], v[98:101]
	v_mfma_f32_16x16x32_bf16 v[90:93], v[158:161], v[204:207], v[90:93]
	v_mfma_f32_16x16x32_bf16 v[82:85], v[150:153], v[212:215], v[82:85]
	v_mfma_f32_16x16x32_bf16 v[74:77], v[158:161], v[212:215], v[74:77]
	v_mfma_f32_16x16x32_bf16 v[118:121], v[162:165], v[184:187], v[118:121]
	v_mfma_f32_16x16x32_bf16 v[110:113], v[170:173], v[184:187], v[110:113]
	v_mfma_f32_16x16x32_bf16 v[102:105], v[162:165], v[192:195], v[102:105]
	v_mfma_f32_16x16x32_bf16 v[94:97], v[170:173], v[192:195], v[94:97]
	v_mfma_f32_16x16x32_bf16 v[86:89], v[162:165], v[200:203], v[86:89]
	v_mfma_f32_16x16x32_bf16 v[78:81], v[170:173], v[200:203], v[78:81]
	v_mfma_f32_16x16x32_bf16 v[70:73], v[162:165], v[208:211], v[70:73]
	v_mfma_f32_16x16x32_bf16 v[66:69], v[170:173], v[208:211], v[66:69]
	v_mfma_f32_16x16x32_bf16 v[118:121], v[166:169], v[188:191], v[118:121]
	v_mfma_f32_16x16x32_bf16 v[110:113], v[180:183], v[188:191], v[110:113]
	v_mfma_f32_16x16x32_bf16 v[102:105], v[166:169], v[196:199], v[102:105]
	v_mfma_f32_16x16x32_bf16 v[94:97], v[180:183], v[196:199], v[94:97]
	v_mfma_f32_16x16x32_bf16 v[86:89], v[166:169], v[204:207], v[86:89]
	v_mfma_f32_16x16x32_bf16 v[78:81], v[180:183], v[204:207], v[78:81]
	v_mfma_f32_16x16x32_bf16 v[70:73], v[166:169], v[212:215], v[70:73]
	v_mfma_f32_16x16x32_bf16 v[66:69], v[180:183], v[212:215], v[66:69]
	s_setprio 0
	s_barrier
	s_add_i32 s39, s39, s47
	v_lshl_add_u64 v[140:141], s[12:13], 0, v[0:1]
	s_mov_b32 m0, s39
	ds_read_b128 v[184:187], v145 offset:16384
	ds_read_b128 v[188:191], v145 offset:17408
	ds_read_b128 v[192:195], v145 offset:18432
	ds_read_b128 v[196:199], v145 offset:19456
	ds_read_b128 v[200:203], v145 offset:20480
	ds_read_b128 v[204:207], v145 offset:21504
	ds_read_b128 v[208:211], v145 offset:22528
	ds_read_b128 v[212:215], v145 offset:23552
	global_load_lds_dwordx4 v[140:141], off
	s_add_i32 m0, s39, 0x2000
	s_add_u32 s44, s12, 0x84000
	v_lshl_add_u64 v[174:175], s[12:13], 0, v[134:135]
	s_addc_u32 s45, s13, 0
	s_add_i32 s39, s46, s47
	global_load_lds_dwordx4 v[174:175], off
	v_lshl_add_u64 v[216:217], s[44:45], 0, v[0:1]
	s_mov_b32 m0, s39
	v_lshl_add_u64 v[218:219], s[14:15], 0, v[132:133]
	global_load_lds_dwordx4 v[216:217], off
	v_lshl_add_u64 v[216:217], s[44:45], 0, v[134:135]
	s_add_i32 m0, s39, 0x2000
	s_nop 0
	global_load_lds_dwordx4 v[216:217], off
	v_lshl_add_u64 v[216:217], s[14:15], 0, v[130:131]
	s_mov_b32 m0, s18
	s_nop 0
	global_load_lds_dwordx4 v[216:217], off
	s_mov_b32 m0, s19
	s_nop 0
	global_load_lds_dwordx4 v[218:219], off
	s_waitcnt vmcnt(8)
	s_waitcnt lgkmcnt(0)
	s_barrier
; #define PG8_STAGE(bufoff, gbase, voff) do { _Pragma("unroll") for (int _i = 0; _i < 2; ++_i) \
;         __builtin_amdgcn_global_load_lds((const unsigned*)((const char*)(gbase) + (voff)[_i]), (LAS unsigned*)(lds + (bufoff) + ldsw + _i * 8192), 16, 0, 0); } while (0)
; #define PG8_LDA(dst, b, h) do { _Pragma("unroll") for (int m = 0; m < 4; ++m) _Pragma("unroll") for (int k = 0; k < 2; ++k) dst[m][k] = *(const LAS bf16x8*)(lds + PG8_SA(b, h) + aoff + m * 2048 + k * 1024); } while (0)
; #define PG8_LDB(dst, b, h) do { _Pragma("unroll") for (int n = 0; n < 2; ++n) _Pragma("unroll") for (int k = 0; k < 2; ++k) dst[n][k] = *(const LAS bf16x8*)(lds + PG8_SB(b, h) + boff + n * 2048 + k * 1024); } while (0)
; #define PG8_MMA(ai, bj, At, Bt) do { __builtin_amdgcn_s_setprio(1); _Pragma("unroll") for (int m = 0; m < 4; ++m) _Pragma("unroll") for (int n = 0; n < 2; ++n) _Pragma("unroll") for (int k = 0; k < 2; ++k) \
;         acc[ai][bj][m][n] = __builtin_amdgcn_mfma_f32_16x16x32_bf16(Bt[n][k], At[m][k], acc[ai][bj][m][n], 0, 0, 0); __builtin_amdgcn_s_setprio(0); } while (0)
; #define PG8_WAIT_V(n) asm volatile("s_waitcnt vmcnt(" #n ")" ::: "memory")
; #define PG8_WAIT_L(n) asm volatile("s_waitcnt lgkmcnt(" #n ")" ::: "memory")
; #define PG8_BAR __builtin_amdgcn_s_barrier()
; #define PG8_SCHED __builtin_amdgcn_sched_barrier(0)
; template <class Epi, class Sched, int LDA, int LDB, bool ALIGN_EPI = true>
; __device__ __forceinline__ void gemm_phase(LAS unsigned char* lds, const Gemm g, const Sched& S, const Epi& E, int wave) {
;     ...
;             PG8_WAIT_V(8); PG8_WAIT_L(0); PG8_BAR; PG8_MMA(1, 0, At, B0); PG8_MMA(1, 1, At, B1); PG8_BAR; PG8_SCHED;
;             PG8_LDB(B0, 1, 0); PG8_LDB(B1, 1, 1); PG8_SCHED; PG8_LDA(At, 1, 0); PG8_STAGE(PG8_SA(0, 1), a2 + hstepA, voffA);
;             PG8_WAIT_V(8); PG8_WAIT_L(0); PG8_BAR; PG8_MMA(0, 0, At, B0); PG8_MMA(0, 1, At, B1); PG8_BAR; PG8_SCHED;
;             PG8_LDA(At, 1, 1); PG8_STAGE(PG8_SB(1, 0), b3, voffB); PG8_STAGE(PG8_SB(1, 1), b3 + hstepB, voffB); PG8_STAGE(PG8_SA(1, 0), a3, voffA);
	s_setprio 1
	v_mfma_f32_16x16x32_bf16 v[62:65], v[146:149], v[184:187], v[62:65]
	v_mfma_f32_16x16x32_bf16 v[58:61], v[154:157], v[184:187], v[58:61]
	v_mfma_f32_16x16x32_bf16 v[50:53], v[146:149], v[192:195], v[50:53]
	v_mfma_f32_16x16x32_bf16 v[42:45], v[154:157], v[192:195], v[42:45]
	v_mfma_f32_16x16x32_bf16 v[34:37], v[146:149], v[200:203], v[34:37]
	v_mfma_f32_16x16x32_bf16 v[26:29], v[154:157], v[200:203], v[26:29]
	v_mfma_f32_16x16x32_bf16 v[18:21], v[146:149], v[208:211], v[18:21]
	v_mfma_f32_16x16x32_bf16 v[10:13], v[154:157], v[208:211], v[10:13]
	v_mfma_f32_16x16x32_bf16 v[62:65], v[150:153], v[188:191], v[62:65]
	v_mfma_f32_16x16x32_bf16 v[58:61], v[158:161], v[188:191], v[58:61]
	v_mfma_f32_16x16x32_bf16 v[50:53], v[150:153], v[196:199], v[50:53]
	v_mfma_f32_16x16x32_bf16 v[42:45], v[158:161], v[196:199], v[42:45]
	v_mfma_f32_16x16x32_bf16 v[34:37], v[150:153], v[204:207], v[34:37]
	v_mfma_f32_16x16x32_bf16 v[26:29], v[158:161], v[204:207], v[26:29]
	v_mfma_f32_16x16x32_bf16 v[18:21], v[150:153], v[212:215], v[18:21]
	v_mfma_f32_16x16x32_bf16 v[10:13], v[158:161], v[212:215], v[10:13]
	v_mfma_f32_16x16x32_bf16 v[54:57], v[162:165], v[184:187], v[54:57]
	v_mfma_f32_16x16x32_bf16 v[46:49], v[170:173], v[184:187], v[46:49]
	v_mfma_f32_16x16x32_bf16 v[38:41], v[162:165], v[192:195], v[38:41]
	v_mfma_f32_16x16x32_bf16 v[30:33], v[170:173], v[192:195], v[30:33]
	v_mfma_f32_16x16x32_bf16 v[22:25], v[162:165], v[200:203], v[22:25]
	v_mfma_f32_16x16x32_bf16 v[14:17], v[170:173], v[200:203], v[14:17]
	v_mfma_f32_16x16x32_bf16 v[6:9], v[162:165], v[208:211], v[6:9]
	v_mfma_f32_16x16x32_bf16 v[2:5], v[170:173], v[208:211], v[2:5]
	v_mfma_f32_16x16x32_bf16 v[54:57], v[166:169], v[188:191], v[54:57]
	v_mfma_f32_16x16x32_bf16 v[46:49], v[180:183], v[188:191], v[46:49]
	v_mfma_f32_16x16x32_bf16 v[38:41], v[166:169], v[196:199], v[38:41]
	v_mfma_f32_16x16x32_bf16 v[30:33], v[180:183], v[196:199], v[30:33]
	v_mfma_f32_16x16x32_bf16 v[22:25], v[166:169], v[204:207], v[22:25]
	v_mfma_f32_16x16x32_bf16 v[14:17], v[180:183], v[204:207], v[14:17]
	v_mfma_f32_16x16x32_bf16 v[6:9], v[166:169], v[212:215], v[6:9]
	v_mfma_f32_16x16x32_bf16 v[2:5], v[180:183], v[212:215], v[2:5]
	s_setprio 0
	s_barrier
	s_add_i32 s39, 0, 0x18000
	s_add_i32 s44, 0, 0x1c000
	v_add_u32_e32 v158, s39, v143
	v_add_u32_e32 v180, s44, v143
	ds_read_b128 v[146:149], v158
	ds_read_b128 v[150:153], v158 offset:1024
	ds_read_b128 v[154:157], v158 offset:2048
	ds_read_b128 v[158:161], v158 offset:3072
	ds_read_b128 v[162:165], v180
	ds_read_b128 v[166:169], v180 offset:1024
	ds_read_b128 v[170:173], v180 offset:2048
	ds_read_b128 v[180:183], v180 offset:3072
	s_add_u32 s14, s14, 0x80000
	s_addc_u32 s15, s15, 0
	s_mov_b32 m0, s24
	v_lshl_add_u64 v[220:221], s[14:15], 0, v[130:131]
	ds_read_b128 v[184:187], v145 offset:32768
	ds_read_b128 v[188:191], v145 offset:33792
	ds_read_b128 v[192:195], v145 offset:34816
	ds_read_b128 v[196:199], v145 offset:35840
	ds_read_b128 v[200:203], v145 offset:36864
	ds_read_b128 v[204:207], v145 offset:37888
	ds_read_b128 v[208:211], v145 offset:38912
	ds_read_b128 v[212:215], v145 offset:39936
	global_load_lds_dwordx4 v[220:221], off
	v_lshl_add_u64 v[220:221], s[14:15], 0, v[132:133]
	s_mov_b32 m0, s25
	s_nop 0
	global_load_lds_dwordx4 v[220:221], off
	s_waitcnt vmcnt(8)
	s_waitcnt lgkmcnt(0)
	s_barrier
	s_setprio 1
	v_mfma_f32_16x16x32_bf16 v[126:129], v[146:149], v[184:187], v[126:129]
	v_mfma_f32_16x16x32_bf16 v[122:125], v[154:157], v[184:187], v[122:125]
	v_mfma_f32_16x16x32_bf16 v[114:117], v[146:149], v[192:195], v[114:117]
	v_mfma_f32_16x16x32_bf16 v[106:109], v[154:157], v[192:195], v[106:109]
	v_mfma_f32_16x16x32_bf16 v[98:101], v[146:149], v[200:203], v[98:101]
	v_mfma_f32_16x16x32_bf16 v[90:93], v[154:157], v[200:203], v[90:93]
	v_mfma_f32_16x16x32_bf16 v[82:85], v[146:149], v[208:211], v[82:85]
	v_mfma_f32_16x16x32_bf16 v[74:77], v[154:157], v[208:211], v[74:77]
	v_mfma_f32_16x16x32_bf16 v[126:129], v[150:153], v[188:191], v[126:129]
	v_mfma_f32_16x16x32_bf16 v[122:125], v[158:161], v[188:191], v[122:125]
	v_mfma_f32_16x16x32_bf16 v[114:117], v[150:153], v[196:199], v[114:117]
	v_mfma_f32_16x16x32_bf16 v[106:109], v[158:161], v[196:199], v[106:109]
	v_mfma_f32_16x16x32_bf16 v[98:101], v[150:153], v[204:207], v[98:101]
	v_mfma_f32_16x16x32_bf16 v[90:93], v[158:161], v[204:207], v[90:93]
	v_mfma_f32_16x16x32_bf16 v[82:85], v[150:153], v[212:215], v[82:85]
	v_mfma_f32_16x16x32_bf16 v[74:77], v[158:161], v[212:215], v[74:77]
	v_mfma_f32_16x16x32_bf16 v[118:121], v[162:165], v[184:187], v[118:121]
	v_mfma_f32_16x16x32_bf16 v[110:113], v[170:173], v[184:187], v[110:113]
	v_mfma_f32_16x16x32_bf16 v[102:105], v[162:165], v[192:195], v[102:105]
	v_mfma_f32_16x16x32_bf16 v[94:97], v[170:173], v[192:195], v[94:97]
	v_mfma_f32_16x16x32_bf16 v[86:89], v[162:165], v[200:203], v[86:89]
	v_mfma_f32_16x16x32_bf16 v[78:81], v[170:173], v[200:203], v[78:81]
	v_mfma_f32_16x16x32_bf16 v[70:73], v[162:165], v[208:211], v[70:73]
	v_mfma_f32_16x16x32_bf16 v[66:69], v[170:173], v[208:211], v[66:69]
	v_mfma_f32_16x16x32_bf16 v[118:121], v[166:169], v[188:191], v[118:121]
	v_mfma_f32_16x16x32_bf16 v[110:113], v[180:183], v[188:191], v[110:113]
	v_mfma_f32_16x16x32_bf16 v[102:105], v[166:169], v[196:199], v[102:105]
	v_mfma_f32_16x16x32_bf16 v[94:97], v[180:183], v[196:199], v[94:97]
	v_mfma_f32_16x16x32_bf16 v[86:89], v[166:169], v[204:207], v[86:89]
	v_mfma_f32_16x16x32_bf16 v[78:81], v[180:183], v[204:207], v[78:81]
	v_mfma_f32_16x16x32_bf16 v[70:73], v[166:169], v[212:215], v[70:73]
	v_mfma_f32_16x16x32_bf16 v[66:69], v[180:183], v[212:215], v[66:69]
	s_setprio 0
	s_barrier
; #define PG8_STAGE(bufoff, gbase, voff) do { _Pragma("unroll") for (int _i = 0; _i < 2; ++_i) \
;         __builtin_amdgcn_global_load_lds((const unsigned*)((const char*)(gbase) + (voff)[_i]), (LAS unsigned*)(lds + (bufoff) + ldsw + _i * 8192), 16, 0, 0); } while (0)
; #define PG8_LDA(dst, b, h) do { _Pragma("unroll") for (int m = 0; m < 4; ++m) _Pragma("unroll") for (int k = 0; k < 2; ++k) dst[m][k] = *(const LAS bf16x8*)(lds + PG8_SA(b, h) + aoff + m * 2048 + k * 1024); } while (0)
; #define PG8_MMA(ai, bj, At, Bt) do { __builtin_amdgcn_s_setprio(1); _Pragma("unroll") for (int m = 0; m < 4; ++m) _Pragma("unroll") for (int n = 0; n < 2; ++n) _Pragma("unroll") for (int k = 0; k < 2; ++k) \
;         acc[ai][bj][m][n] = __builtin_amdgcn_mfma_f32_16x16x32_bf16(Bt[n][k], At[m][k], acc[ai][bj][m][n], 0, 0, 0); __builtin_amdgcn_s_setprio(0); } while (0)
; #define PG8_WAIT_V(n) asm volatile("s_waitcnt vmcnt(" #n ")" ::: "memory")
; #define PG8_WAIT_L(n) asm volatile("s_waitcnt lgkmcnt(" #n ")" ::: "memory")
; #define PG8_BAR __builtin_amdgcn_s_barrier()
; #define PG8_SCHED __builtin_amdgcn_sched_barrier(0)
; template <class Epi, class Sched, int LDA, int LDB, bool ALIGN_EPI = true>
; __device__ __forceinline__ void gemm_phase(LAS unsigned char* lds, const Gemm g, const Sched& S, const Epi& E, int wave) {
;     ...
;             PG8_LDA(At, 1, 1); PG8_STAGE(PG8_SB(1, 0), b3, voffB); PG8_STAGE(PG8_SB(1, 1), b3 + hstepB, voffB); PG8_STAGE(PG8_SA(1, 0), a3, voffA);
;             PG8_WAIT_V(8); PG8_WAIT_L(0); PG8_BAR; PG8_MMA(1, 0, At, B0); PG8_MMA(1, 1, At, B1); PG8_BAR; PG8_SCHED;
;         }
;         if constexpr (ALIGN_EPI) { if (wr == 0) PG8_BAR; }
	s_add_i32 s14, s39, s47
	v_lshl_add_u64 v[140:141], v[140:141], 0, s[48:49]
	s_mov_b32 m0, s14
	ds_read_b128 v[184:187], v145 offset:49152
	ds_read_b128 v[188:191], v145 offset:50176
	ds_read_b128 v[192:195], v145 offset:51200
	ds_read_b128 v[196:199], v145 offset:52224
	ds_read_b128 v[200:203], v145 offset:53248
	ds_read_b128 v[204:207], v145 offset:54272
	ds_read_b128 v[208:211], v145 offset:55296
	ds_read_b128 v[212:215], v145 offset:56320
	global_load_lds_dwordx4 v[140:141], off
	s_add_i32 m0, s14, 0x2000
	s_add_u32 s12, s12, 0x84080
	v_lshl_add_u64 v[140:141], v[174:175], 0, s[48:49]
	s_addc_u32 s13, s13, 0
	s_add_i32 s14, s44, s47
	global_load_lds_dwordx4 v[140:141], off
	v_lshl_add_u64 v[140:141], s[12:13], 0, v[0:1]
	s_mov_b32 m0, s14
	s_nop 0
	global_load_lds_dwordx4 v[140:141], off
	v_lshl_add_u64 v[140:141], s[12:13], 0, v[134:135]
	s_add_i32 m0, s14, 0x2000
	s_nop 0
	global_load_lds_dwordx4 v[140:141], off
	v_lshl_add_u64 v[140:141], v[216:217], 0, s[48:49]
	s_mov_b32 m0, s26
	s_nop 0
	global_load_lds_dwordx4 v[140:141], off
	v_lshl_add_u64 v[140:141], v[218:219], 0, s[48:49]
	s_mov_b32 m0, s27
	s_nop 0
	global_load_lds_dwordx4 v[140:141], off
	s_waitcnt vmcnt(8)
	s_waitcnt lgkmcnt(0)
	s_barrier
	s_setprio 1
	v_mfma_f32_16x16x32_bf16 v[62:65], v[146:149], v[184:187], v[62:65]
	v_mfma_f32_16x16x32_bf16 v[58:61], v[154:157], v[184:187], v[58:61]
	v_mfma_f32_16x16x32_bf16 v[50:53], v[146:149], v[192:195], v[50:53]
	v_mfma_f32_16x16x32_bf16 v[42:45], v[154:157], v[192:195], v[42:45]
	v_mfma_f32_16x16x32_bf16 v[34:37], v[146:149], v[200:203], v[34:37]
	v_mfma_f32_16x16x32_bf16 v[26:29], v[154:157], v[200:203], v[26:29]
	v_mfma_f32_16x16x32_bf16 v[18:21], v[146:149], v[208:211], v[18:21]
	v_mfma_f32_16x16x32_bf16 v[10:13], v[154:157], v[208:211], v[10:13]
	v_mfma_f32_16x16x32_bf16 v[62:65], v[150:153], v[188:191], v[62:65]
	v_mfma_f32_16x16x32_bf16 v[58:61], v[158:161], v[188:191], v[58:61]
	v_mfma_f32_16x16x32_bf16 v[50:53], v[150:153], v[196:199], v[50:53]
	v_mfma_f32_16x16x32_bf16 v[42:45], v[158:161], v[196:199], v[42:45]
	v_mfma_f32_16x16x32_bf16 v[34:37], v[150:153], v[204:207], v[34:37]
	v_mfma_f32_16x16x32_bf16 v[26:29], v[158:161], v[204:207], v[26:29]
	v_mfma_f32_16x16x32_bf16 v[18:21], v[150:153], v[212:215], v[18:21]
	v_mfma_f32_16x16x32_bf16 v[10:13], v[158:161], v[212:215], v[10:13]
	v_mfma_f32_16x16x32_bf16 v[54:57], v[162:165], v[184:187], v[54:57]
	v_mfma_f32_16x16x32_bf16 v[46:49], v[170:173], v[184:187], v[46:49]
	v_mfma_f32_16x16x32_bf16 v[38:41], v[162:165], v[192:195], v[38:41]
	v_mfma_f32_16x16x32_bf16 v[30:33], v[170:173], v[192:195], v[30:33]
	v_mfma_f32_16x16x32_bf16 v[22:25], v[162:165], v[200:203], v[22:25]
	v_mfma_f32_16x16x32_bf16 v[14:17], v[170:173], v[200:203], v[14:17]
	v_mfma_f32_16x16x32_bf16 v[6:9], v[162:165], v[208:211], v[6:9]
	v_mfma_f32_16x16x32_bf16 v[2:5], v[170:173], v[208:211], v[2:5]
	v_mfma_f32_16x16x32_bf16 v[54:57], v[166:169], v[188:191], v[54:57]
	v_mfma_f32_16x16x32_bf16 v[46:49], v[180:183], v[188:191], v[46:49]
	v_mfma_f32_16x16x32_bf16 v[38:41], v[166:169], v[196:199], v[38:41]
	v_mfma_f32_16x16x32_bf16 v[30:33], v[180:183], v[196:199], v[30:33]
	v_mfma_f32_16x16x32_bf16 v[22:25], v[166:169], v[204:207], v[22:25]
	v_mfma_f32_16x16x32_bf16 v[14:17], v[180:183], v[204:207], v[14:17]
	v_mfma_f32_16x16x32_bf16 v[6:9], v[166:169], v[212:215], v[6:9]
	v_mfma_f32_16x16x32_bf16 v[2:5], v[180:183], v[212:215], v[2:5]
	s_setprio 0
	s_barrier
	s_add_i32 s38, s38, 2
	s_add_u32 s10, s10, 0x100
	s_addc_u32 s11, s11, 0
	s_add_u32 s36, s36, 0x100
	s_addc_u32 s37, s37, 0
	s_cmp_gt_u32 s38, 29
	s_cbranch_scc0 .LBB0_2415
	v_readlane_b32 s10, v252, 14
	v_readlane_b32 s11, v252, 15
	s_and_b64 vcc, exec, s[10:11]
	s_cbranch_vccz .LBB0_2418
	s_barrier

; #define PG8_STAGE(bufoff, gbase, voff) do { _Pragma("unroll") for (int _i = 0; _i < 2; ++_i) \
;         __builtin_amdgcn_global_load_lds((const unsigned*)((const char*)(gbase) + (voff)[_i]), (LAS unsigned*)(lds + (bufoff) + ldsw + _i * 8192), 16, 0, 0); } while (0)
; #define PG8_LDA(dst, b, h) do { _Pragma("unroll") for (int m = 0; m < 4; ++m) _Pragma("unroll") for (int k = 0; k < 2; ++k) dst[m][k] = *(const LAS bf16x8*)(lds + PG8_SA(b, h) + aoff + m * 2048 + k * 1024); } while (0)
; #define PG8_LDB(dst, b, h) do { _Pragma("unroll") for (int n = 0; n < 2; ++n) _Pragma("unroll") for (int k = 0; k < 2; ++k) dst[n][k] = *(const LAS bf16x8*)(lds + PG8_SB(b, h) + boff + n * 2048 + k * 1024); } while (0)
; #define PG8_MMA(ai, bj, At, Bt) do { __builtin_amdgcn_s_setprio(1); _Pragma("unroll") for (int m = 0; m < 4; ++m) _Pragma("unroll") for (int n = 0; n < 2; ++n) _Pragma("unroll") for (int k = 0; k < 2; ++k) \
;         acc[ai][bj][m][n] = __builtin_amdgcn_mfma_f32_16x16x32_bf16(Bt[n][k], At[m][k], acc[ai][bj][m][n], 0, 0, 0); __builtin_amdgcn_s_setprio(0); } while (0)
; #define PG8_WAIT_V(n) asm volatile("s_waitcnt vmcnt(" #n ")" ::: "memory")
; #define PG8_WAIT_L(n) asm volatile("s_waitcnt lgkmcnt(" #n ")" ::: "memory")
; #define PG8_BAR __builtin_amdgcn_s_barrier()
; #define PG8_SCHED __builtin_amdgcn_sched_barrier(0)
; template <class Epi, class Sched, int LDA, int LDB, bool ALIGN_EPI = true>
; __device__ __forceinline__ void gemm_phase(LAS unsigned char* lds, const Gemm g, const Sched& S, const Epi& E, int wave) {
;     ...
;             const bool last = (t == nt - 2);
;             const char* a1 = cA + (size_t)(t + 1) * kstep;
;             const char* a2 = last ? nA : cA + (size_t)(t + 2) * kstep; const char* b2 = last ? nB : cB + (size_t)(t + 2) * kstep;
;             const char* a3 = a2 + kstep; const char* b3 = b2 + kstep;
;             PG8_LDB(B0, 0, 0); PG8_LDB(B1, 0, 1); PG8_SCHED; PG8_LDA(At, 0, 0); PG8_STAGE(PG8_SA(1, 1), a1 + hstepA, voffA);
;             PG8_WAIT_V(8); PG8_WAIT_L(0); PG8_BAR; PG8_MMA(0, 0, At, B0); PG8_MMA(0, 1, At, B1); PG8_BAR; PG8_SCHED;
;             PG8_LDA(At, 0, 1); PG8_STAGE(PG8_SB(0, 0), b2, voffB); PG8_STAGE(PG8_SB(0, 1), b2 + hstepB, voffB); PG8_STAGE(PG8_SA(0, 0), a2, voffA);
;             PG8_WAIT_V(8); PG8_WAIT_L(0); PG8_BAR; PG8_MMA(1, 0, At, B0); PG8_MMA(1, 1, At, B1); PG8_BAR; PG8_SCHED;
.LBB0_2513:
	s_add_u32 s14, s12, 0xfff80080
	s_addc_u32 s15, s13, -1
	s_add_i32 s44, 0, 0x10000
	s_cmp_eq_u32 s39, 28
	s_cselect_b32 s17, s1, s15
	s_cselect_b32 s16, s3, s14
	v_add_u32_e32 v140, s44, v143
	s_cselect_b32 s15, s9, s38
	s_cselect_b32 s14, s8, s37
	s_add_i32 s46, 0, 0x14000
	ds_read_b128 v[146:149], v140
	ds_read_b128 v[150:153], v140 offset:1024
	ds_read_b128 v[154:157], v140 offset:2048
	ds_read_b128 v[158:161], v140 offset:3072
	v_add_u32_e32 v140, s46, v143
	ds_read_b128 v[162:165], v140
	ds_read_b128 v[166:169], v140 offset:1024
	ds_read_b128 v[170:173], v140 offset:2048
	ds_read_b128 v[180:183], v140 offset:3072
	v_lshl_add_u64 v[140:141], s[12:13], 0, v[136:137]
	s_add_i32 m0, s24, 0xc000
	ds_read_b128 v[184:187], v145
	ds_read_b128 v[188:191], v145 offset:1024
	ds_read_b128 v[192:195], v145 offset:2048
	ds_read_b128 v[196:199], v145 offset:3072
	ds_read_b128 v[200:203], v145 offset:4096
	ds_read_b128 v[204:207], v145 offset:5120
	ds_read_b128 v[208:211], v145 offset:6144
	ds_read_b128 v[212:215], v145 offset:7168
	global_load_lds_dwordx4 v[140:141], off
	v_lshl_add_u64 v[140:141], s[12:13], 0, v[138:139]
	s_add_i32 m0, s24, 0xe000
	s_nop 0
	global_load_lds_dwordx4 v[140:141], off
	s_waitcnt vmcnt(8)
	s_waitcnt lgkmcnt(0)
	s_barrier
	s_setprio 1
	v_mfma_f32_16x16x32_bf16 v[126:129], v[146:149], v[184:187], v[126:129]
	v_mfma_f32_16x16x32_bf16 v[122:125], v[154:157], v[184:187], v[122:125]
	v_mfma_f32_16x16x32_bf16 v[114:117], v[146:149], v[192:195], v[114:117]
	v_mfma_f32_16x16x32_bf16 v[106:109], v[154:157], v[192:195], v[106:109]
	v_mfma_f32_16x16x32_bf16 v[98:101], v[146:149], v[200:203], v[98:101]
	v_mfma_f32_16x16x32_bf16 v[90:93], v[154:157], v[200:203], v[90:93]
	v_mfma_f32_16x16x32_bf16 v[82:85], v[146:149], v[208:211], v[82:85]
	v_mfma_f32_16x16x32_bf16 v[74:77], v[154:157], v[208:211], v[74:77]
	v_mfma_f32_16x16x32_bf16 v[126:129], v[150:153], v[188:191], v[126:129]
	v_mfma_f32_16x16x32_bf16 v[122:125], v[158:161], v[188:191], v[122:125]
	v_mfma_f32_16x16x32_bf16 v[114:117], v[150:153], v[196:199], v[114:117]
	v_mfma_f32_16x16x32_bf16 v[106:109], v[158:161], v[196:199], v[106:109]
	v_mfma_f32_16x16x32_bf16 v[98:101], v[150:153], v[204:207], v[98:101]
	v_mfma_f32_16x16x32_bf16 v[90:93], v[158:161], v[204:207], v[90:93]
	v_mfma_f32_16x16x32_bf16 v[82:85], v[150:153], v[212:215], v[82:85]
	v_mfma_f32_16x16x32_bf16 v[74:77], v[158:161], v[212:215], v[74:77]
	v_mfma_f32_16x16x32_bf16 v[118:121], v[162:165], v[184:187], v[118:121]
	v_mfma_f32_16x16x32_bf16 v[110:113], v[170:173], v[184:187], v[110:113]
	v_mfma_f32_16x16x32_bf16 v[102:105], v[162:165], v[192:195], v[102:105]
	v_mfma_f32_16x16x32_bf16 v[94:97], v[170:173], v[192:195], v[94:97]
	v_mfma_f32_16x16x32_bf16 v[86:89], v[162:165], v[200:203], v[86:89]
	v_mfma_f32_16x16x32_bf16 v[78:81], v[170:173], v[200:203], v[78:81]
	v_mfma_f32_16x16x32_bf16 v[70:73], v[162:165], v[208:211], v[70:73]
	v_mfma_f32_16x16x32_bf16 v[66:69], v[170:173], v[208:211], v[66:69]
	v_mfma_f32_16x16x32_bf16 v[118:121], v[166:169], v[188:191], v[118:121]
	v_mfma_f32_16x16x32_bf16 v[110:113], v[180:183], v[188:191], v[110:113]
	v_mfma_f32_16x16x32_bf16 v[102:105], v[166:169], v[196:199], v[102:105]
	v_mfma_f32_16x16x32_bf16 v[94:97], v[180:183], v[196:199], v[94:97]
	v_mfma_f32_16x16x32_bf16 v[86:89], v[166:169], v[204:207], v[86:89]
	v_mfma_f32_16x16x32_bf16 v[78:81], v[180:183], v[204:207], v[78:81]
	v_mfma_f32_16x16x32_bf16 v[70:73], v[166:169], v[212:215], v[70:73]
	v_mfma_f32_16x16x32_bf16 v[66:69], v[180:183], v[212:215], v[66:69]
	s_setprio 0
	s_barrier
	s_add_i32 s44, s44, s47
	v_lshl_add_u64 v[140:141], s[14:15], 0, v[0:1]
	s_mov_b32 m0, s44
	ds_read_b128 v[184:187], v145 offset:16384
	ds_read_b128 v[188:191], v145 offset:17408
	ds_read_b128 v[192:195], v145 offset:18432
	ds_read_b128 v[196:199], v145 offset:19456
	ds_read_b128 v[200:203], v145 offset:20480
	ds_read_b128 v[204:207], v145 offset:21504
	ds_read_b128 v[208:211], v145 offset:22528
	ds_read_b128 v[212:215], v145 offset:23552
	global_load_lds_dwordx4 v[140:141], off
	s_add_i32 m0, s44, 0x2000
	s_add_u32 s44, s14, 0x84000
	v_lshl_add_u64 v[174:175], s[14:15], 0, v[134:135]
	s_addc_u32 s45, s15, 0
	s_add_i32 s46, s46, s47
	global_load_lds_dwordx4 v[174:175], off
	v_lshl_add_u64 v[216:217], s[44:45], 0, v[0:1]
	s_mov_b32 m0, s46
	v_lshl_add_u64 v[218:219], s[16:17], 0, v[132:133]
	global_load_lds_dwordx4 v[216:217], off
	v_lshl_add_u64 v[216:217], s[44:45], 0, v[134:135]
	s_add_i32 m0, s46, 0x2000
	s_nop 0
	global_load_lds_dwordx4 v[216:217], off
	v_lshl_add_u64 v[216:217], s[16:17], 0, v[130:131]
	s_mov_b32 m0, s24
	s_nop 0
	global_load_lds_dwordx4 v[216:217], off
	s_mov_b32 m0, s25
	s_nop 0
	global_load_lds_dwordx4 v[218:219], off
	s_waitcnt vmcnt(8)
	s_waitcnt lgkmcnt(0)
	s_barrier
; #define PG8_STAGE(bufoff, gbase, voff) do { _Pragma("unroll") for (int _i = 0; _i < 2; ++_i) \
;         __builtin_amdgcn_global_load_lds((const unsigned*)((const char*)(gbase) + (voff)[_i]), (LAS unsigned*)(lds + (bufoff) + ldsw + _i * 8192), 16, 0, 0); } while (0)
; #define PG8_LDA(dst, b, h) do { _Pragma("unroll") for (int m = 0; m < 4; ++m) _Pragma("unroll") for (int k = 0; k < 2; ++k) dst[m][k] = *(const LAS bf16x8*)(lds + PG8_SA(b, h) + aoff + m * 2048 + k * 1024); } while (0)
; #define PG8_LDB(dst, b, h) do { _Pragma("unroll") for (int n = 0; n < 2; ++n) _Pragma("unroll") for (int k = 0; k < 2; ++k) dst[n][k] = *(const LAS bf16x8*)(lds + PG8_SB(b, h) + boff + n * 2048 + k * 1024); } while (0)
; #define PG8_MMA(ai, bj, At, Bt) do { __builtin_amdgcn_s_setprio(1); _Pragma("unroll") for (int m = 0; m < 4; ++m) _Pragma("unroll") for (int n = 0; n < 2; ++n) _Pragma("unroll") for (int k = 0; k < 2; ++k) \
;         acc[ai][bj][m][n] = __builtin_amdgcn_mfma_f32_16x16x32_bf16(Bt[n][k], At[m][k], acc[ai][bj][m][n], 0, 0, 0); __builtin_amdgcn_s_setprio(0); } while (0)
; #define PG8_WAIT_V(n) asm volatile("s_waitcnt vmcnt(" #n ")" ::: "memory")
; #define PG8_WAIT_L(n) asm volatile("s_waitcnt lgkmcnt(" #n ")" ::: "memory")
; #define PG8_BAR __builtin_amdgcn_s_barrier()
; #define PG8_SCHED __builtin_amdgcn_sched_barrier(0)
; template <class Epi, class Sched, int LDA, int LDB, bool ALIGN_EPI = true>
; __device__ __forceinline__ void gemm_phase(LAS unsigned char* lds, const Gemm g, const Sched& S, const Epi& E, int wave) {
;     ...
;             PG8_WAIT_V(8); PG8_WAIT_L(0); PG8_BAR; PG8_MMA(1, 0, At, B0); PG8_MMA(1, 1, At, B1); PG8_BAR; PG8_SCHED;
;             PG8_LDB(B0, 1, 0); PG8_LDB(B1, 1, 1); PG8_SCHED; PG8_LDA(At, 1, 0); PG8_STAGE(PG8_SA(0, 1), a2 + hstepA, voffA);
;             PG8_WAIT_V(8); PG8_WAIT_L(0); PG8_BAR; PG8_MMA(0, 0, At, B0); PG8_MMA(0, 1, At, B1); PG8_BAR; PG8_SCHED;
;             PG8_LDA(At, 1, 1); PG8_STAGE(PG8_SB(1, 0), b3, voffB); PG8_STAGE(PG8_SB(1, 1), b3 + hstepB, voffB); PG8_STAGE(PG8_SA(1, 0), a3, voffA);
	s_setprio 1
	v_mfma_f32_16x16x32_bf16 v[62:65], v[146:149], v[184:187], v[62:65]
	v_mfma_f32_16x16x32_bf16 v[58:61], v[154:157], v[184:187], v[58:61]
	v_mfma_f32_16x16x32_bf16 v[50:53], v[146:149], v[192:195], v[50:53]
	v_mfma_f32_16x16x32_bf16 v[42:45], v[154:157], v[192:195], v[42:45]
	v_mfma_f32_16x16x32_bf16 v[34:37], v[146:149], v[200:203], v[34:37]
	v_mfma_f32_16x16x32_bf16 v[26:29], v[154:157], v[200:203], v[26:29]
	v_mfma_f32_16x16x32_bf16 v[18:21], v[146:149], v[208:211], v[18:21]
	v_mfma_f32_16x16x32_bf16 v[10:13], v[154:157], v[208:211], v[10:13]
	v_mfma_f32_16x16x32_bf16 v[62:65], v[150:153], v[188:191], v[62:65]
	v_mfma_f32_16x16x32_bf16 v[58:61], v[158:161], v[188:191], v[58:61]
	v_mfma_f32_16x16x32_bf16 v[50:53], v[150:153], v[196:199], v[50:53]
	v_mfma_f32_16x16x32_bf16 v[42:45], v[158:161], v[196:199], v[42:45]
	v_mfma_f32_16x16x32_bf16 v[34:37], v[150:153], v[204:207], v[34:37]
	v_mfma_f32_16x16x32_bf16 v[26:29], v[158:161], v[204:207], v[26:29]
	v_mfma_f32_16x16x32_bf16 v[18:21], v[150:153], v[212:215], v[18:21]
	v_mfma_f32_16x16x32_bf16 v[10:13], v[158:161], v[212:215], v[10:13]
	v_mfma_f32_16x16x32_bf16 v[54:57], v[162:165], v[184:187], v[54:57]
	v_mfma_f32_16x16x32_bf16 v[46:49], v[170:173], v[184:187], v[46:49]
	v_mfma_f32_16x16x32_bf16 v[38:41], v[162:165], v[192:195], v[38:41]
	v_mfma_f32_16x16x32_bf16 v[30:33], v[170:173], v[192:195], v[30:33]
	v_mfma_f32_16x16x32_bf16 v[22:25], v[162:165], v[200:203], v[22:25]
	v_mfma_f32_16x16x32_bf16 v[14:17], v[170:173], v[200:203], v[14:17]
	v_mfma_f32_16x16x32_bf16 v[6:9], v[162:165], v[208:211], v[6:9]
	v_mfma_f32_16x16x32_bf16 v[2:5], v[170:173], v[208:211], v[2:5]
	v_mfma_f32_16x16x32_bf16 v[54:57], v[166:169], v[188:191], v[54:57]
	v_mfma_f32_16x16x32_bf16 v[46:49], v[180:183], v[188:191], v[46:49]
	v_mfma_f32_16x16x32_bf16 v[38:41], v[166:169], v[196:199], v[38:41]
	v_mfma_f32_16x16x32_bf16 v[30:33], v[180:183], v[196:199], v[30:33]
	v_mfma_f32_16x16x32_bf16 v[22:25], v[166:169], v[204:207], v[22:25]
	v_mfma_f32_16x16x32_bf16 v[14:17], v[180:183], v[204:207], v[14:17]
	v_mfma_f32_16x16x32_bf16 v[6:9], v[166:169], v[212:215], v[6:9]
	v_mfma_f32_16x16x32_bf16 v[2:5], v[180:183], v[212:215], v[2:5]
	s_setprio 0
	s_barrier
	s_add_i32 s44, 0, 0x18000
	s_add_i32 s45, 0, 0x1c000
	v_add_u32_e32 v158, s44, v143
	v_add_u32_e32 v180, s45, v143
	ds_read_b128 v[146:149], v158
	ds_read_b128 v[150:153], v158 offset:1024
	ds_read_b128 v[154:157], v158 offset:2048
	ds_read_b128 v[158:161], v158 offset:3072
	ds_read_b128 v[162:165], v180
	ds_read_b128 v[166:169], v180 offset:1024
	ds_read_b128 v[170:173], v180 offset:2048
	ds_read_b128 v[180:183], v180 offset:3072
	s_add_u32 s16, s16, 0x80000
	s_addc_u32 s17, s17, 0
	s_mov_b32 m0, s26
	v_lshl_add_u64 v[220:221], s[16:17], 0, v[130:131]
	ds_read_b128 v[184:187], v145 offset:32768
	ds_read_b128 v[188:191], v145 offset:33792
	ds_read_b128 v[192:195], v145 offset:34816
	ds_read_b128 v[196:199], v145 offset:35840
	ds_read_b128 v[200:203], v145 offset:36864
	ds_read_b128 v[204:207], v145 offset:37888
	ds_read_b128 v[208:211], v145 offset:38912
	ds_read_b128 v[212:215], v145 offset:39936
	global_load_lds_dwordx4 v[220:221], off
	v_lshl_add_u64 v[220:221], s[16:17], 0, v[132:133]
	s_mov_b32 m0, s27
	s_nop 0
	global_load_lds_dwordx4 v[220:221], off
	s_waitcnt vmcnt(8)
	s_waitcnt lgkmcnt(0)
	s_barrier
	s_setprio 1
	v_mfma_f32_16x16x32_bf16 v[126:129], v[146:149], v[184:187], v[126:129]
	v_mfma_f32_16x16x32_bf16 v[122:125], v[154:157], v[184:187], v[122:125]
	v_mfma_f32_16x16x32_bf16 v[114:117], v[146:149], v[192:195], v[114:117]
	v_mfma_f32_16x16x32_bf16 v[106:109], v[154:157], v[192:195], v[106:109]
	v_mfma_f32_16x16x32_bf16 v[98:101], v[146:149], v[200:203], v[98:101]
	v_mfma_f32_16x16x32_bf16 v[90:93], v[154:157], v[200:203], v[90:93]
	v_mfma_f32_16x16x32_bf16 v[82:85], v[146:149], v[208:211], v[82:85]
	v_mfma_f32_16x16x32_bf16 v[74:77], v[154:157], v[208:211], v[74:77]
	v_mfma_f32_16x16x32_bf16 v[126:129], v[150:153], v[188:191], v[126:129]
	v_mfma_f32_16x16x32_bf16 v[122:125], v[158:161], v[188:191], v[122:125]
	v_mfma_f32_16x16x32_bf16 v[114:117], v[150:153], v[196:199], v[114:117]
	v_mfma_f32_16x16x32_bf16 v[106:109], v[158:161], v[196:199], v[106:109]
	v_mfma_f32_16x16x32_bf16 v[98:101], v[150:153], v[204:207], v[98:101]
	v_mfma_f32_16x16x32_bf16 v[90:93], v[158:161], v[204:207], v[90:93]
	v_mfma_f32_16x16x32_bf16 v[82:85], v[150:153], v[212:215], v[82:85]
	v_mfma_f32_16x16x32_bf16 v[74:77], v[158:161], v[212:215], v[74:77]
	v_mfma_f32_16x16x32_bf16 v[118:121], v[162:165], v[184:187], v[118:121]
	v_mfma_f32_16x16x32_bf16 v[110:113], v[170:173], v[184:187], v[110:113]
	v_mfma_f32_16x16x32_bf16 v[102:105], v[162:165], v[192:195], v[102:105]
	v_mfma_f32_16x16x32_bf16 v[94:97], v[170:173], v[192:195], v[94:97]
	v_mfma_f32_16x16x32_bf16 v[86:89], v[162:165], v[200:203], v[86:89]
	v_mfma_f32_16x16x32_bf16 v[78:81], v[170:173], v[200:203], v[78:81]
	v_mfma_f32_16x16x32_bf16 v[70:73], v[162:165], v[208:211], v[70:73]
	v_mfma_f32_16x16x32_bf16 v[66:69], v[170:173], v[208:211], v[66:69]
	v_mfma_f32_16x16x32_bf16 v[118:121], v[166:169], v[188:191], v[118:121]
	v_mfma_f32_16x16x32_bf16 v[110:113], v[180:183], v[188:191], v[110:113]
	v_mfma_f32_16x16x32_bf16 v[102:105], v[166:169], v[196:199], v[102:105]
	v_mfma_f32_16x16x32_bf16 v[94:97], v[180:183], v[196:199], v[94:97]
	v_mfma_f32_16x16x32_bf16 v[86:89], v[166:169], v[204:207], v[86:89]
	v_mfma_f32_16x16x32_bf16 v[78:81], v[180:183], v[204:207], v[78:81]
	v_mfma_f32_16x16x32_bf16 v[70:73], v[166:169], v[212:215], v[70:73]
	v_mfma_f32_16x16x32_bf16 v[66:69], v[180:183], v[212:215], v[66:69]
	s_setprio 0
	s_barrier
; #define PG8_STAGE(bufoff, gbase, voff) do { _Pragma("unroll") for (int _i = 0; _i < 2; ++_i) \
;         __builtin_amdgcn_global_load_lds((const unsigned*)((const char*)(gbase) + (voff)[_i]), (LAS unsigned*)(lds + (bufoff) + ldsw + _i * 8192), 16, 0, 0); } while (0)
; #define PG8_LDA(dst, b, h) do { _Pragma("unroll") for (int m = 0; m < 4; ++m) _Pragma("unroll") for (int k = 0; k < 2; ++k) dst[m][k] = *(const LAS bf16x8*)(lds + PG8_SA(b, h) + aoff + m * 2048 + k * 1024); } while (0)
; #define PG8_MMA(ai, bj, At, Bt) do { __builtin_amdgcn_s_setprio(1); _Pragma("unroll") for (int m = 0; m < 4; ++m) _Pragma("unroll") for (int n = 0; n < 2; ++n) _Pragma("unroll") for (int k = 0; k < 2; ++k) \
;         acc[ai][bj][m][n] = __builtin_amdgcn_mfma_f32_16x16x32_bf16(Bt[n][k], At[m][k], acc[ai][bj][m][n], 0, 0, 0); __builtin_amdgcn_s_setprio(0); } while (0)
; #define PG8_WAIT_V(n) asm volatile("s_waitcnt vmcnt(" #n ")" ::: "memory")
; #define PG8_WAIT_L(n) asm volatile("s_waitcnt lgkmcnt(" #n ")" ::: "memory")
; #define PG8_BAR __builtin_amdgcn_s_barrier()
; #define PG8_SCHED __builtin_amdgcn_sched_barrier(0)
; template <class Epi, class Sched, int LDA, int LDB, bool ALIGN_EPI = true>
; __device__ __forceinline__ void gemm_phase(LAS unsigned char* lds, const Gemm g, const Sched& S, const Epi& E, int wave) {
;     ...
;             PG8_LDA(At, 1, 1); PG8_STAGE(PG8_SB(1, 0), b3, voffB); PG8_STAGE(PG8_SB(1, 1), b3 + hstepB, voffB); PG8_STAGE(PG8_SA(1, 0), a3, voffA);
;             PG8_WAIT_V(8); PG8_WAIT_L(0); PG8_BAR; PG8_MMA(1, 0, At, B0); PG8_MMA(1, 1, At, B1); PG8_BAR; PG8_SCHED;
;         }
;         if constexpr (ALIGN_EPI) { if (wr == 0) PG8_BAR; }
	s_add_i32 s16, s44, s47
	v_lshl_add_u64 v[140:141], v[140:141], 0, s[72:73]
	s_mov_b32 m0, s16
	ds_read_b128 v[184:187], v145 offset:49152
	ds_read_b128 v[188:191], v145 offset:50176
	ds_read_b128 v[192:195], v145 offset:51200
	ds_read_b128 v[196:199], v145 offset:52224
	ds_read_b128 v[200:203], v145 offset:53248
	ds_read_b128 v[204:207], v145 offset:54272
	ds_read_b128 v[208:211], v145 offset:55296
	ds_read_b128 v[212:215], v145 offset:56320
	global_load_lds_dwordx4 v[140:141], off
	s_add_i32 m0, s16, 0x2000
	s_add_u32 s14, s14, 0x84080
	v_lshl_add_u64 v[140:141], v[174:175], 0, s[72:73]
	s_addc_u32 s15, s15, 0
	s_add_i32 s16, s45, s47
	global_load_lds_dwordx4 v[140:141], off
	v_lshl_add_u64 v[140:141], s[14:15], 0, v[0:1]
	s_mov_b32 m0, s16
	s_nop 0
	global_load_lds_dwordx4 v[140:141], off
	v_lshl_add_u64 v[140:141], s[14:15], 0, v[134:135]
	s_add_i32 m0, s16, 0x2000
	s_nop 0
	global_load_lds_dwordx4 v[140:141], off
	v_lshl_add_u64 v[140:141], v[216:217], 0, s[72:73]
	s_mov_b32 m0, s28
	s_nop 0
	global_load_lds_dwordx4 v[140:141], off
	v_lshl_add_u64 v[140:141], v[218:219], 0, s[72:73]
	s_mov_b32 m0, s29
	s_nop 0
	global_load_lds_dwordx4 v[140:141], off
	s_waitcnt vmcnt(8)
	s_waitcnt lgkmcnt(0)
	s_barrier
	s_setprio 1
	v_mfma_f32_16x16x32_bf16 v[62:65], v[146:149], v[184:187], v[62:65]
	v_mfma_f32_16x16x32_bf16 v[58:61], v[154:157], v[184:187], v[58:61]
	v_mfma_f32_16x16x32_bf16 v[50:53], v[146:149], v[192:195], v[50:53]
	v_mfma_f32_16x16x32_bf16 v[42:45], v[154:157], v[192:195], v[42:45]
	v_mfma_f32_16x16x32_bf16 v[34:37], v[146:149], v[200:203], v[34:37]
	v_mfma_f32_16x16x32_bf16 v[26:29], v[154:157], v[200:203], v[26:29]
	v_mfma_f32_16x16x32_bf16 v[18:21], v[146:149], v[208:211], v[18:21]
	v_mfma_f32_16x16x32_bf16 v[10:13], v[154:157], v[208:211], v[10:13]
	v_mfma_f32_16x16x32_bf16 v[62:65], v[150:153], v[188:191], v[62:65]
	v_mfma_f32_16x16x32_bf16 v[58:61], v[158:161], v[188:191], v[58:61]
	v_mfma_f32_16x16x32_bf16 v[50:53], v[150:153], v[196:199], v[50:53]
	v_mfma_f32_16x16x32_bf16 v[42:45], v[158:161], v[196:199], v[42:45]
	v_mfma_f32_16x16x32_bf16 v[34:37], v[150:153], v[204:207], v[34:37]
	v_mfma_f32_16x16x32_bf16 v[26:29], v[158:161], v[204:207], v[26:29]
	v_mfma_f32_16x16x32_bf16 v[18:21], v[150:153], v[212:215], v[18:21]
	v_mfma_f32_16x16x32_bf16 v[10:13], v[158:161], v[212:215], v[10:13]
	v_mfma_f32_16x16x32_bf16 v[54:57], v[162:165], v[184:187], v[54:57]
	v_mfma_f32_16x16x32_bf16 v[46:49], v[170:173], v[184:187], v[46:49]
	v_mfma_f32_16x16x32_bf16 v[38:41], v[162:165], v[192:195], v[38:41]
	v_mfma_f32_16x16x32_bf16 v[30:33], v[170:173], v[192:195], v[30:33]
	v_mfma_f32_16x16x32_bf16 v[22:25], v[162:165], v[200:203], v[22:25]
	v_mfma_f32_16x16x32_bf16 v[14:17], v[170:173], v[200:203], v[14:17]
	v_mfma_f32_16x16x32_bf16 v[6:9], v[162:165], v[208:211], v[6:9]
	v_mfma_f32_16x16x32_bf16 v[2:5], v[170:173], v[208:211], v[2:5]
	v_mfma_f32_16x16x32_bf16 v[54:57], v[166:169], v[188:191], v[54:57]
	v_mfma_f32_16x16x32_bf16 v[46:49], v[180:183], v[188:191], v[46:49]
	v_mfma_f32_16x16x32_bf16 v[38:41], v[166:169], v[196:199], v[38:41]
	v_mfma_f32_16x16x32_bf16 v[30:33], v[180:183], v[196:199], v[30:33]
	v_mfma_f32_16x16x32_bf16 v[22:25], v[166:169], v[204:207], v[22:25]
	v_mfma_f32_16x16x32_bf16 v[14:17], v[180:183], v[204:207], v[14:17]
	v_mfma_f32_16x16x32_bf16 v[6:9], v[166:169], v[212:215], v[6:9]
	v_mfma_f32_16x16x32_bf16 v[2:5], v[180:183], v[212:215], v[2:5]
	s_setprio 0
	s_barrier
	s_add_i32 s39, s39, 2
	s_add_u32 s12, s12, 0x100
	s_addc_u32 s13, s13, 0
	s_add_u32 s37, s37, 0x100
	s_addc_u32 s38, s38, 0
	s_cmp_gt_u32 s39, 29
	s_cbranch_scc0 .LBB0_2513
	v_readlane_b32 s12, v252, 14
	v_readlane_b32 s13, v252, 15
	s_and_b64 vcc, exec, s[12:13]
	s_cbranch_vccz .LBB0_2516
	s_barrier

; #define PG8_STAGE(bufoff, gbase, voff) do { _Pragma("unroll") for (int _i = 0; _i < 2; ++_i) \
;         __builtin_amdgcn_global_load_lds((const unsigned*)((const char*)(gbase) + (voff)[_i]), (LAS unsigned*)(lds + (bufoff) + ldsw + _i * 8192), 16, 0, 0); } while (0)
; #define PG8_LDA(dst, b, h) do { _Pragma("unroll") for (int m = 0; m < 4; ++m) _Pragma("unroll") for (int k = 0; k < 2; ++k) dst[m][k] = *(const LAS bf16x8*)(lds + PG8_SA(b, h) + aoff + m * 2048 + k * 1024); } while (0)
; #define PG8_LDB(dst, b, h) do { _Pragma("unroll") for (int n = 0; n < 2; ++n) _Pragma("unroll") for (int k = 0; k < 2; ++k) dst[n][k] = *(const LAS bf16x8*)(lds + PG8_SB(b, h) + boff + n * 2048 + k * 1024); } while (0)
; #define PG8_MMA(ai, bj, At, Bt) do { __builtin_amdgcn_s_setprio(1); _Pragma("unroll") for (int m = 0; m < 4; ++m) _Pragma("unroll") for (int n = 0; n < 2; ++n) _Pragma("unroll") for (int k = 0; k < 2; ++k) \
;         acc[ai][bj][m][n] = __builtin_amdgcn_mfma_f32_16x16x32_bf16(Bt[n][k], At[m][k], acc[ai][bj][m][n], 0, 0, 0); __builtin_amdgcn_s_setprio(0); } while (0)
; #define PG8_WAIT_V(n) asm volatile("s_waitcnt vmcnt(" #n ")" ::: "memory")
; #define PG8_WAIT_L(n) asm volatile("s_waitcnt lgkmcnt(" #n ")" ::: "memory")
; #define PG8_BAR __builtin_amdgcn_s_barrier()
; #define PG8_SCHED __builtin_amdgcn_sched_barrier(0)
; template <class Epi, class Sched, int LDA, int LDB, bool ALIGN_EPI = true>
; __device__ __forceinline__ void gemm_phase(LAS unsigned char* lds, const Gemm g, const Sched& S, const Epi& E, int wave) {
;     ...
;             const bool last = (t == nt - 2);
;             const char* a1 = cA + (size_t)(t + 1) * kstep;
;             const char* a2 = last ? nA : cA + (size_t)(t + 2) * kstep; const char* b2 = last ? nB : cB + (size_t)(t + 2) * kstep;
;             const char* a3 = a2 + kstep; const char* b3 = b2 + kstep;
;             PG8_LDB(B0, 0, 0); PG8_LDB(B1, 0, 1); PG8_SCHED; PG8_LDA(At, 0, 0); PG8_STAGE(PG8_SA(1, 1), a1 + hstepA, voffA);
;             PG8_WAIT_V(8); PG8_WAIT_L(0); PG8_BAR; PG8_MMA(0, 0, At, B0); PG8_MMA(0, 1, At, B1); PG8_BAR; PG8_SCHED;
;             PG8_LDA(At, 0, 1); PG8_STAGE(PG8_SB(0, 0), b2, voffB); PG8_STAGE(PG8_SB(0, 1), b2 + hstepB, voffB); PG8_STAGE(PG8_SA(0, 0), a2, voffA);
;             PG8_WAIT_V(8); PG8_WAIT_L(0); PG8_BAR; PG8_MMA(1, 0, At, B0); PG8_MMA(1, 1, At, B1); PG8_BAR; PG8_SCHED;
.LBB0_2551:
	s_add_u32 s2, s0, 0x100
	s_addc_u32 s3, s1, 0
	s_add_i32 s50, 0, 0x10000
	s_cmp_eq_u32 s49, 8
	s_cselect_b32 s17, s11, s3
	s_cselect_b32 s16, s10, s2
	v_add_u32_e32 v0, s50, v154
	s_cselect_b32 s15, s13, s47
	s_cselect_b32 s14, s12, s46
	s_add_i32 s51, 0, 0x14000
	ds_read_b128 v[130:133], v0
	ds_read_b128 v[148:151], v0 offset:1024
	ds_read_b128 v[158:161], v0 offset:2048
	ds_read_b128 v[162:165], v0 offset:3072
	v_add_u32_e32 v0, s51, v154
	ds_read_b128 v[166:169], v0
	ds_read_b128 v[170:173], v0 offset:1024
	ds_read_b128 v[180:183], v0 offset:2048
	ds_read_b128 v[184:187], v0 offset:3072
	v_lshl_add_u64 v[152:153], s[0:1], 0, v[144:145]
	s_add_i32 m0, s28, 0xc000
	ds_read_b128 v[188:191], v156
	ds_read_b128 v[192:195], v156 offset:1024
	ds_read_b128 v[196:199], v156 offset:2048
	ds_read_b128 v[200:203], v156 offset:3072
	ds_read_b128 v[204:207], v156 offset:4096
	ds_read_b128 v[208:211], v156 offset:5120
	ds_read_b128 v[212:215], v156 offset:6144
	ds_read_b128 v[216:219], v156 offset:7168
	global_load_lds_dwordx4 v[152:153], off
	v_lshl_add_u64 v[152:153], s[0:1], 0, v[146:147]
	s_add_i32 m0, s28, 0xe000
	s_nop 0
	global_load_lds_dwordx4 v[152:153], off
	s_waitcnt vmcnt(8)
	s_waitcnt lgkmcnt(0)
	s_barrier
	s_setprio 1
	v_mfma_f32_16x16x32_bf16 v[126:129], v[130:133], v[188:191], v[126:129]
	v_mfma_f32_16x16x32_bf16 v[122:125], v[158:161], v[188:191], v[122:125]
	v_mfma_f32_16x16x32_bf16 v[118:121], v[130:133], v[196:199], v[118:121]
	v_mfma_f32_16x16x32_bf16 v[114:117], v[158:161], v[196:199], v[114:117]
	v_mfma_f32_16x16x32_bf16 v[110:113], v[130:133], v[204:207], v[110:113]
	v_mfma_f32_16x16x32_bf16 v[106:109], v[158:161], v[204:207], v[106:109]
	v_mfma_f32_16x16x32_bf16 v[102:105], v[130:133], v[212:215], v[102:105]
	v_mfma_f32_16x16x32_bf16 v[98:101], v[158:161], v[212:215], v[98:101]
	v_mfma_f32_16x16x32_bf16 v[126:129], v[148:151], v[192:195], v[126:129]
	v_mfma_f32_16x16x32_bf16 v[122:125], v[162:165], v[192:195], v[122:125]
	v_mfma_f32_16x16x32_bf16 v[118:121], v[148:151], v[200:203], v[118:121]
	v_mfma_f32_16x16x32_bf16 v[114:117], v[162:165], v[200:203], v[114:117]
	v_mfma_f32_16x16x32_bf16 v[110:113], v[148:151], v[208:211], v[110:113]
	v_mfma_f32_16x16x32_bf16 v[106:109], v[162:165], v[208:211], v[106:109]
	v_mfma_f32_16x16x32_bf16 v[102:105], v[148:151], v[216:219], v[102:105]
	v_mfma_f32_16x16x32_bf16 v[98:101], v[162:165], v[216:219], v[98:101]
	v_mfma_f32_16x16x32_bf16 v[62:65], v[166:169], v[188:191], v[62:65]
	v_mfma_f32_16x16x32_bf16 v[58:61], v[180:183], v[188:191], v[58:61]
	v_mfma_f32_16x16x32_bf16 v[54:57], v[166:169], v[196:199], v[54:57]
	v_mfma_f32_16x16x32_bf16 v[50:53], v[180:183], v[196:199], v[50:53]
	v_mfma_f32_16x16x32_bf16 v[46:49], v[166:169], v[204:207], v[46:49]
	v_mfma_f32_16x16x32_bf16 v[42:45], v[180:183], v[204:207], v[42:45]
	v_mfma_f32_16x16x32_bf16 v[38:41], v[166:169], v[212:215], v[38:41]
	v_mfma_f32_16x16x32_bf16 v[34:37], v[180:183], v[212:215], v[34:37]
	v_mfma_f32_16x16x32_bf16 v[62:65], v[170:173], v[192:195], v[62:65]
	v_mfma_f32_16x16x32_bf16 v[58:61], v[184:187], v[192:195], v[58:61]
	v_mfma_f32_16x16x32_bf16 v[54:57], v[170:173], v[200:203], v[54:57]
	v_mfma_f32_16x16x32_bf16 v[50:53], v[184:187], v[200:203], v[50:53]
	v_mfma_f32_16x16x32_bf16 v[46:49], v[170:173], v[208:211], v[46:49]
	v_mfma_f32_16x16x32_bf16 v[42:45], v[184:187], v[208:211], v[42:45]
	v_mfma_f32_16x16x32_bf16 v[38:41], v[170:173], v[216:219], v[38:41]
	v_mfma_f32_16x16x32_bf16 v[34:37], v[184:187], v[216:219], v[34:37]
	s_setprio 0
	s_barrier
	s_add_i32 s0, s50, s54
	v_lshl_add_u64 v[152:153], s[14:15], 0, v[136:137]
	s_mov_b32 m0, s0
	ds_read_b128 v[188:191], v156 offset:16384
	ds_read_b128 v[192:195], v156 offset:17408
	ds_read_b128 v[196:199], v156 offset:18432
	ds_read_b128 v[200:203], v156 offset:19456
	ds_read_b128 v[204:207], v156 offset:20480
	ds_read_b128 v[208:211], v156 offset:21504
	ds_read_b128 v[212:215], v156 offset:22528
	ds_read_b128 v[216:219], v156 offset:23552
	global_load_lds_dwordx4 v[152:153], off
	s_add_i32 m0, s0, 0x2000
	s_add_u32 s0, s14, 0x30000
	v_lshl_add_u64 v[174:175], s[14:15], 0, v[140:141]
	s_addc_u32 s1, s15, 0
	s_add_i32 s50, s51, s54
	global_load_lds_dwordx4 v[174:175], off
	v_lshl_add_u64 v[220:221], s[0:1], 0, v[136:137]
	s_mov_b32 m0, s50
	v_lshl_add_u64 v[222:223], s[16:17], 0, v[138:139]
	global_load_lds_dwordx4 v[220:221], off
	v_lshl_add_u64 v[220:221], s[0:1], 0, v[140:141]
	s_add_i32 m0, s50, 0x2000
	s_nop 0
	global_load_lds_dwordx4 v[220:221], off
	v_lshl_add_u64 v[220:221], s[16:17], 0, v[134:135]
	s_mov_b32 m0, s28
	s_nop 0
	global_load_lds_dwordx4 v[220:221], off
	s_mov_b32 m0, s29
	s_nop 0
	global_load_lds_dwordx4 v[222:223], off
	s_waitcnt vmcnt(8)
	s_waitcnt lgkmcnt(0)
	s_barrier
; #define PG8_STAGE(bufoff, gbase, voff) do { _Pragma("unroll") for (int _i = 0; _i < 2; ++_i) \
;         __builtin_amdgcn_global_load_lds((const unsigned*)((const char*)(gbase) + (voff)[_i]), (LAS unsigned*)(lds + (bufoff) + ldsw + _i * 8192), 16, 0, 0); } while (0)
; #define PG8_LDA(dst, b, h) do { _Pragma("unroll") for (int m = 0; m < 4; ++m) _Pragma("unroll") for (int k = 0; k < 2; ++k) dst[m][k] = *(const LAS bf16x8*)(lds + PG8_SA(b, h) + aoff + m * 2048 + k * 1024); } while (0)
; #define PG8_LDB(dst, b, h) do { _Pragma("unroll") for (int n = 0; n < 2; ++n) _Pragma("unroll") for (int k = 0; k < 2; ++k) dst[n][k] = *(const LAS bf16x8*)(lds + PG8_SB(b, h) + boff + n * 2048 + k * 1024); } while (0)
; #define PG8_MMA(ai, bj, At, Bt) do { __builtin_amdgcn_s_setprio(1); _Pragma("unroll") for (int m = 0; m < 4; ++m) _Pragma("unroll") for (int n = 0; n < 2; ++n) _Pragma("unroll") for (int k = 0; k < 2; ++k) \
;         acc[ai][bj][m][n] = __builtin_amdgcn_mfma_f32_16x16x32_bf16(Bt[n][k], At[m][k], acc[ai][bj][m][n], 0, 0, 0); __builtin_amdgcn_s_setprio(0); } while (0)
; #define PG8_WAIT_V(n) asm volatile("s_waitcnt vmcnt(" #n ")" ::: "memory")
; #define PG8_WAIT_L(n) asm volatile("s_waitcnt lgkmcnt(" #n ")" ::: "memory")
; #define PG8_BAR __builtin_amdgcn_s_barrier()
; #define PG8_SCHED __builtin_amdgcn_sched_barrier(0)
; template <class Epi, class Sched, int LDA, int LDB, bool ALIGN_EPI = true>
; __device__ __forceinline__ void gemm_phase(LAS unsigned char* lds, const Gemm g, const Sched& S, const Epi& E, int wave) {
;     ...
;             PG8_WAIT_V(8); PG8_WAIT_L(0); PG8_BAR; PG8_MMA(1, 0, At, B0); PG8_MMA(1, 1, At, B1); PG8_BAR; PG8_SCHED;
;             PG8_LDB(B0, 1, 0); PG8_LDB(B1, 1, 1); PG8_SCHED; PG8_LDA(At, 1, 0); PG8_STAGE(PG8_SA(0, 1), a2 + hstepA, voffA);
;             PG8_WAIT_V(8); PG8_WAIT_L(0); PG8_BAR; PG8_MMA(0, 0, At, B0); PG8_MMA(0, 1, At, B1); PG8_BAR; PG8_SCHED;
;             PG8_LDA(At, 1, 1); PG8_STAGE(PG8_SB(1, 0), b3, voffB); PG8_STAGE(PG8_SB(1, 1), b3 + hstepB, voffB); PG8_STAGE(PG8_SA(1, 0), a3, voffA);
	s_setprio 1
	v_mfma_f32_16x16x32_bf16 v[94:97], v[130:133], v[188:191], v[94:97]
	v_mfma_f32_16x16x32_bf16 v[90:93], v[158:161], v[188:191], v[90:93]
	v_mfma_f32_16x16x32_bf16 v[86:89], v[130:133], v[196:199], v[86:89]
	v_mfma_f32_16x16x32_bf16 v[82:85], v[158:161], v[196:199], v[82:85]
	v_mfma_f32_16x16x32_bf16 v[78:81], v[130:133], v[204:207], v[78:81]
	v_mfma_f32_16x16x32_bf16 v[74:77], v[158:161], v[204:207], v[74:77]
	v_mfma_f32_16x16x32_bf16 v[70:73], v[130:133], v[212:215], v[70:73]
	v_mfma_f32_16x16x32_bf16 v[66:69], v[158:161], v[212:215], v[66:69]
	v_mfma_f32_16x16x32_bf16 v[94:97], v[148:151], v[192:195], v[94:97]
	v_mfma_f32_16x16x32_bf16 v[90:93], v[162:165], v[192:195], v[90:93]
	v_mfma_f32_16x16x32_bf16 v[86:89], v[148:151], v[200:203], v[86:89]
	v_mfma_f32_16x16x32_bf16 v[82:85], v[162:165], v[200:203], v[82:85]
	v_mfma_f32_16x16x32_bf16 v[78:81], v[148:151], v[208:211], v[78:81]
	v_mfma_f32_16x16x32_bf16 v[74:77], v[162:165], v[208:211], v[74:77]
	v_mfma_f32_16x16x32_bf16 v[70:73], v[148:151], v[216:219], v[70:73]
	v_mfma_f32_16x16x32_bf16 v[66:69], v[162:165], v[216:219], v[66:69]
	v_mfma_f32_16x16x32_bf16 v[30:33], v[166:169], v[188:191], v[30:33]
	v_mfma_f32_16x16x32_bf16 v[26:29], v[180:183], v[188:191], v[26:29]
	v_mfma_f32_16x16x32_bf16 v[22:25], v[166:169], v[196:199], v[22:25]
	v_mfma_f32_16x16x32_bf16 v[18:21], v[180:183], v[196:199], v[18:21]
	v_mfma_f32_16x16x32_bf16 v[14:17], v[166:169], v[204:207], v[14:17]
	v_mfma_f32_16x16x32_bf16 v[10:13], v[180:183], v[204:207], v[10:13]
	v_mfma_f32_16x16x32_bf16 v[6:9], v[166:169], v[212:215], v[6:9]
	v_mfma_f32_16x16x32_bf16 v[2:5], v[180:183], v[212:215], v[2:5]
	v_mfma_f32_16x16x32_bf16 v[30:33], v[170:173], v[192:195], v[30:33]
	v_mfma_f32_16x16x32_bf16 v[26:29], v[184:187], v[192:195], v[26:29]
	v_mfma_f32_16x16x32_bf16 v[22:25], v[170:173], v[200:203], v[22:25]
	v_mfma_f32_16x16x32_bf16 v[18:21], v[184:187], v[200:203], v[18:21]
	v_mfma_f32_16x16x32_bf16 v[14:17], v[170:173], v[208:211], v[14:17]
	v_mfma_f32_16x16x32_bf16 v[10:13], v[184:187], v[208:211], v[10:13]
	v_mfma_f32_16x16x32_bf16 v[6:9], v[170:173], v[216:219], v[6:9]
	v_mfma_f32_16x16x32_bf16 v[2:5], v[184:187], v[216:219], v[2:5]
	s_setprio 0
	s_barrier
	s_add_i32 s50, 0, 0x18000
	v_add_u32_e32 v0, s50, v154
	s_add_i32 s51, 0, 0x1c000
	ds_read_b128 v[130:133], v0
	ds_read_b128 v[148:151], v0 offset:1024
	ds_read_b128 v[158:161], v0 offset:2048
	ds_read_b128 v[162:165], v0 offset:3072
	v_add_u32_e32 v0, s51, v154
	ds_read_b128 v[166:169], v0
	ds_read_b128 v[170:173], v0 offset:1024
	ds_read_b128 v[180:183], v0 offset:2048
	ds_read_b128 v[184:187], v0 offset:3072
	s_add_u32 s0, s16, 0x30000
	s_addc_u32 s1, s17, 0
	s_mov_b32 m0, s34
	v_lshl_add_u64 v[224:225], s[0:1], 0, v[134:135]
	ds_read_b128 v[188:191], v156 offset:32768
	ds_read_b128 v[192:195], v156 offset:33792
	ds_read_b128 v[196:199], v156 offset:34816
	ds_read_b128 v[200:203], v156 offset:35840
	ds_read_b128 v[204:207], v156 offset:36864
	ds_read_b128 v[208:211], v156 offset:37888
	ds_read_b128 v[212:215], v156 offset:38912
	ds_read_b128 v[216:219], v156 offset:39936
	global_load_lds_dwordx4 v[224:225], off
	v_lshl_add_u64 v[224:225], s[0:1], 0, v[138:139]
	s_mov_b32 m0, s35
	s_nop 0
	global_load_lds_dwordx4 v[224:225], off
	s_waitcnt vmcnt(8)
	s_waitcnt lgkmcnt(0)
	s_barrier
	s_setprio 1
	v_mfma_f32_16x16x32_bf16 v[126:129], v[130:133], v[188:191], v[126:129]
	v_mfma_f32_16x16x32_bf16 v[122:125], v[158:161], v[188:191], v[122:125]
	v_mfma_f32_16x16x32_bf16 v[118:121], v[130:133], v[196:199], v[118:121]
	v_mfma_f32_16x16x32_bf16 v[114:117], v[158:161], v[196:199], v[114:117]
	v_mfma_f32_16x16x32_bf16 v[110:113], v[130:133], v[204:207], v[110:113]
	v_mfma_f32_16x16x32_bf16 v[106:109], v[158:161], v[204:207], v[106:109]
	v_mfma_f32_16x16x32_bf16 v[102:105], v[130:133], v[212:215], v[102:105]
	v_mfma_f32_16x16x32_bf16 v[98:101], v[158:161], v[212:215], v[98:101]
	v_mfma_f32_16x16x32_bf16 v[126:129], v[148:151], v[192:195], v[126:129]
	v_mfma_f32_16x16x32_bf16 v[122:125], v[162:165], v[192:195], v[122:125]
	v_mfma_f32_16x16x32_bf16 v[118:121], v[148:151], v[200:203], v[118:121]
	v_mfma_f32_16x16x32_bf16 v[114:117], v[162:165], v[200:203], v[114:117]
	v_mfma_f32_16x16x32_bf16 v[110:113], v[148:151], v[208:211], v[110:113]
	v_mfma_f32_16x16x32_bf16 v[106:109], v[162:165], v[208:211], v[106:109]
	v_mfma_f32_16x16x32_bf16 v[102:105], v[148:151], v[216:219], v[102:105]
	v_mfma_f32_16x16x32_bf16 v[98:101], v[162:165], v[216:219], v[98:101]
	v_mfma_f32_16x16x32_bf16 v[62:65], v[166:169], v[188:191], v[62:65]
	v_mfma_f32_16x16x32_bf16 v[58:61], v[180:183], v[188:191], v[58:61]
	v_mfma_f32_16x16x32_bf16 v[54:57], v[166:169], v[196:199], v[54:57]
	v_mfma_f32_16x16x32_bf16 v[50:53], v[180:183], v[196:199], v[50:53]
	v_mfma_f32_16x16x32_bf16 v[46:49], v[166:169], v[204:207], v[46:49]
	v_mfma_f32_16x16x32_bf16 v[42:45], v[180:183], v[204:207], v[42:45]
	v_mfma_f32_16x16x32_bf16 v[38:41], v[166:169], v[212:215], v[38:41]
	v_mfma_f32_16x16x32_bf16 v[34:37], v[180:183], v[212:215], v[34:37]
	v_mfma_f32_16x16x32_bf16 v[62:65], v[170:173], v[192:195], v[62:65]
	v_mfma_f32_16x16x32_bf16 v[58:61], v[184:187], v[192:195], v[58:61]
	v_mfma_f32_16x16x32_bf16 v[54:57], v[170:173], v[200:203], v[54:57]
	v_mfma_f32_16x16x32_bf16 v[50:53], v[184:187], v[200:203], v[50:53]
	v_mfma_f32_16x16x32_bf16 v[46:49], v[170:173], v[208:211], v[46:49]
	v_mfma_f32_16x16x32_bf16 v[42:45], v[184:187], v[208:211], v[42:45]
	v_mfma_f32_16x16x32_bf16 v[38:41], v[170:173], v[216:219], v[38:41]
	v_mfma_f32_16x16x32_bf16 v[34:37], v[184:187], v[216:219], v[34:37]
	s_setprio 0
	s_barrier
; #define PG8_STAGE(bufoff, gbase, voff) do { _Pragma("unroll") for (int _i = 0; _i < 2; ++_i) \
;         __builtin_amdgcn_global_load_lds((const unsigned*)((const char*)(gbase) + (voff)[_i]), (LAS unsigned*)(lds + (bufoff) + ldsw + _i * 8192), 16, 0, 0); } while (0)
; #define PG8_LDA(dst, b, h) do { _Pragma("unroll") for (int m = 0; m < 4; ++m) _Pragma("unroll") for (int k = 0; k < 2; ++k) dst[m][k] = *(const LAS bf16x8*)(lds + PG8_SA(b, h) + aoff + m * 2048 + k * 1024); } while (0)
; #define PG8_MMA(ai, bj, At, Bt) do { __builtin_amdgcn_s_setprio(1); _Pragma("unroll") for (int m = 0; m < 4; ++m) _Pragma("unroll") for (int n = 0; n < 2; ++n) _Pragma("unroll") for (int k = 0; k < 2; ++k) \
;         acc[ai][bj][m][n] = __builtin_amdgcn_mfma_f32_16x16x32_bf16(Bt[n][k], At[m][k], acc[ai][bj][m][n], 0, 0, 0); __builtin_amdgcn_s_setprio(0); } while (0)
; #define PG8_WAIT_V(n) asm volatile("s_waitcnt vmcnt(" #n ")" ::: "memory")
; #define PG8_WAIT_L(n) asm volatile("s_waitcnt lgkmcnt(" #n ")" ::: "memory")
; #define PG8_BAR __builtin_amdgcn_s_barrier()
; #define PG8_SCHED __builtin_amdgcn_sched_barrier(0)
; template <class Epi, class Sched, int LDA, int LDB, bool ALIGN_EPI = true>
; __device__ __forceinline__ void gemm_phase(LAS unsigned char* lds, const Gemm g, const Sched& S, const Epi& E, int wave) {
;     ...
;             PG8_LDA(At, 1, 1); PG8_STAGE(PG8_SB(1, 0), b3, voffB); PG8_STAGE(PG8_SB(1, 1), b3 + hstepB, voffB); PG8_STAGE(PG8_SA(1, 0), a3, voffA);
;             PG8_WAIT_V(8); PG8_WAIT_L(0); PG8_BAR; PG8_MMA(1, 0, At, B0); PG8_MMA(1, 1, At, B1); PG8_BAR; PG8_SCHED;
;         }
;         if constexpr (ALIGN_EPI) { if (wr == 0) PG8_BAR; }
	s_add_i32 s0, s50, s54
	v_lshl_add_u64 v[152:153], v[152:153], 0, s[72:73]
	s_mov_b32 m0, s0
	ds_read_b128 v[188:191], v156 offset:49152
	ds_read_b128 v[192:195], v156 offset:50176
	ds_read_b128 v[196:199], v156 offset:51200
	ds_read_b128 v[200:203], v156 offset:52224
	ds_read_b128 v[204:207], v156 offset:53248
	ds_read_b128 v[208:211], v156 offset:54272
	ds_read_b128 v[212:215], v156 offset:55296
	ds_read_b128 v[216:219], v156 offset:56320
	global_load_lds_dwordx4 v[152:153], off
	s_add_i32 m0, s0, 0x2000
	s_add_u32 s0, s14, 0x30080
	v_lshl_add_u64 v[152:153], v[174:175], 0, s[72:73]
	s_addc_u32 s1, s15, 0
	s_add_i32 s14, s51, s54
	global_load_lds_dwordx4 v[152:153], off
	v_lshl_add_u64 v[152:153], s[0:1], 0, v[136:137]
	s_mov_b32 m0, s14
	s_nop 0
	global_load_lds_dwordx4 v[152:153], off
	v_lshl_add_u64 v[152:153], s[0:1], 0, v[140:141]
	s_add_i32 m0, s14, 0x2000
	s_nop 0
	global_load_lds_dwordx4 v[152:153], off
	v_lshl_add_u64 v[152:153], v[220:221], 0, s[72:73]
	s_mov_b32 m0, s36
	s_nop 0
	global_load_lds_dwordx4 v[152:153], off
	v_lshl_add_u64 v[152:153], v[222:223], 0, s[72:73]
	s_mov_b32 m0, s37
	s_nop 0
	global_load_lds_dwordx4 v[152:153], off
	s_waitcnt vmcnt(8)
	s_waitcnt lgkmcnt(0)
	s_barrier
	s_setprio 1
	v_mfma_f32_16x16x32_bf16 v[94:97], v[130:133], v[188:191], v[94:97]
	v_mfma_f32_16x16x32_bf16 v[90:93], v[158:161], v[188:191], v[90:93]
	v_mfma_f32_16x16x32_bf16 v[86:89], v[130:133], v[196:199], v[86:89]
	v_mfma_f32_16x16x32_bf16 v[82:85], v[158:161], v[196:199], v[82:85]
	v_mfma_f32_16x16x32_bf16 v[78:81], v[130:133], v[204:207], v[78:81]
	v_mfma_f32_16x16x32_bf16 v[74:77], v[158:161], v[204:207], v[74:77]
	v_mfma_f32_16x16x32_bf16 v[70:73], v[130:133], v[212:215], v[70:73]
	v_mfma_f32_16x16x32_bf16 v[66:69], v[158:161], v[212:215], v[66:69]
	v_mfma_f32_16x16x32_bf16 v[94:97], v[148:151], v[192:195], v[94:97]
	v_mfma_f32_16x16x32_bf16 v[90:93], v[162:165], v[192:195], v[90:93]
	v_mfma_f32_16x16x32_bf16 v[86:89], v[148:151], v[200:203], v[86:89]
	v_mfma_f32_16x16x32_bf16 v[82:85], v[162:165], v[200:203], v[82:85]
	v_mfma_f32_16x16x32_bf16 v[78:81], v[148:151], v[208:211], v[78:81]
	v_mfma_f32_16x16x32_bf16 v[74:77], v[162:165], v[208:211], v[74:77]
	v_mfma_f32_16x16x32_bf16 v[70:73], v[148:151], v[216:219], v[70:73]
	v_mfma_f32_16x16x32_bf16 v[66:69], v[162:165], v[216:219], v[66:69]
	v_mfma_f32_16x16x32_bf16 v[30:33], v[166:169], v[188:191], v[30:33]
	v_mfma_f32_16x16x32_bf16 v[26:29], v[180:183], v[188:191], v[26:29]
	v_mfma_f32_16x16x32_bf16 v[22:25], v[166:169], v[196:199], v[22:25]
	v_mfma_f32_16x16x32_bf16 v[18:21], v[180:183], v[196:199], v[18:21]
	v_mfma_f32_16x16x32_bf16 v[14:17], v[166:169], v[204:207], v[14:17]
	v_mfma_f32_16x16x32_bf16 v[10:13], v[180:183], v[204:207], v[10:13]
	v_mfma_f32_16x16x32_bf16 v[6:9], v[166:169], v[212:215], v[6:9]
	v_mfma_f32_16x16x32_bf16 v[2:5], v[180:183], v[212:215], v[2:5]
	v_mfma_f32_16x16x32_bf16 v[30:33], v[170:173], v[192:195], v[30:33]
	v_mfma_f32_16x16x32_bf16 v[26:29], v[184:187], v[192:195], v[26:29]
	v_mfma_f32_16x16x32_bf16 v[22:25], v[170:173], v[200:203], v[22:25]
	v_mfma_f32_16x16x32_bf16 v[18:21], v[184:187], v[200:203], v[18:21]
	v_mfma_f32_16x16x32_bf16 v[14:17], v[170:173], v[208:211], v[14:17]
	v_mfma_f32_16x16x32_bf16 v[10:13], v[184:187], v[208:211], v[10:13]
	v_mfma_f32_16x16x32_bf16 v[6:9], v[170:173], v[216:219], v[6:9]
	v_mfma_f32_16x16x32_bf16 v[2:5], v[184:187], v[216:219], v[2:5]
	s_setprio 0
	s_barrier
	s_add_i32 s49, s49, 2
	s_add_u32 s46, s46, 0x100
	s_addc_u32 s47, s47, 0
	s_cmp_gt_u32 s49, 9
	s_mov_b64 s[0:1], s[2:3]
	s_cbranch_scc0 .LBB0_2551
	v_readlane_b32 s0, v252, 14
	v_readlane_b32 s1, v252, 15
	s_and_b64 vcc, exec, s[0:1]
	s_cbranch_vccz .LBB0_2554
	s_barrier

; #define PG8_STAGE(bufoff, gbase, voff) do { _Pragma("unroll") for (int _i = 0; _i < 2; ++_i) \
;         __builtin_amdgcn_global_load_lds((const unsigned*)((const char*)(gbase) + (voff)[_i]), (LAS unsigned*)(lds + (bufoff) + ldsw + _i * 8192), 16, 0, 0); } while (0)
; #define PG8_LDA(dst, b, h) do { _Pragma("unroll") for (int m = 0; m < 4; ++m) _Pragma("unroll") for (int k = 0; k < 2; ++k) dst[m][k] = *(const LAS bf16x8*)(lds + PG8_SA(b, h) + aoff + m * 2048 + k * 1024); } while (0)
; #define PG8_LDB(dst, b, h) do { _Pragma("unroll") for (int n = 0; n < 2; ++n) _Pragma("unroll") for (int k = 0; k < 2; ++k) dst[n][k] = *(const LAS bf16x8*)(lds + PG8_SB(b, h) + boff + n * 2048 + k * 1024); } while (0)
; #define PG8_MMA(ai, bj, At, Bt) do { __builtin_amdgcn_s_setprio(1); _Pragma("unroll") for (int m = 0; m < 4; ++m) _Pragma("unroll") for (int n = 0; n < 2; ++n) _Pragma("unroll") for (int k = 0; k < 2; ++k) \
;         acc[ai][bj][m][n] = __builtin_amdgcn_mfma_f32_16x16x32_bf16(Bt[n][k], At[m][k], acc[ai][bj][m][n], 0, 0, 0); __builtin_amdgcn_s_setprio(0); } while (0)
; #define PG8_WAIT_V(n) asm volatile("s_waitcnt vmcnt(" #n ")" ::: "memory")
; #define PG8_WAIT_L(n) asm volatile("s_waitcnt lgkmcnt(" #n ")" ::: "memory")
; #define PG8_BAR __builtin_amdgcn_s_barrier()
; #define PG8_SCHED __builtin_amdgcn_sched_barrier(0)
; template <class Epi, class Sched, int LDA, int LDB, bool ALIGN_EPI = true>
; __device__ __forceinline__ void gemm_phase(LAS unsigned char* lds, const Gemm g, const Sched& S, const Epi& E, int wave) {
;     ...
;             const bool last = (t == nt - 2);
;             const char* a1 = cA + (size_t)(t + 1) * kstep;
;             const char* a2 = last ? nA : cA + (size_t)(t + 2) * kstep; const char* b2 = last ? nB : cB + (size_t)(t + 2) * kstep;
;             const char* a3 = a2 + kstep; const char* b3 = b2 + kstep;
;             PG8_LDB(B0, 0, 0); PG8_LDB(B1, 0, 1); PG8_SCHED; PG8_LDA(At, 0, 0); PG8_STAGE(PG8_SA(1, 1), a1 + hstepA, voffA);
;             PG8_WAIT_V(8); PG8_WAIT_L(0); PG8_BAR; PG8_MMA(0, 0, At, B0); PG8_MMA(0, 1, At, B1); PG8_BAR; PG8_SCHED;
;             PG8_LDA(At, 0, 1); PG8_STAGE(PG8_SB(0, 0), b2, voffB); PG8_STAGE(PG8_SB(0, 1), b2 + hstepB, voffB); PG8_STAGE(PG8_SA(0, 0), a2, voffA);
;             PG8_WAIT_V(8); PG8_WAIT_L(0); PG8_BAR; PG8_MMA(1, 0, At, B0); PG8_MMA(1, 1, At, B1); PG8_BAR; PG8_SCHED;
.LBB0_2619:
	s_add_u32 s16, s14, 0xfffe0080
	s_addc_u32 s17, s15, -1
	s_add_i32 s53, 0, 0x10000
	s_cmp_eq_u32 s52, 4
	s_cselect_b32 s19, s7, s17
	s_cselect_b32 s18, s13, s16
	v_add_u32_e32 v0, s53, v150
	s_cselect_b32 s17, s3, s51
	s_cselect_b32 s16, s44, s45
	s_add_i32 s58, 0, 0x14000
	ds_read_b128 v[144:147], v0
	ds_read_b128 v[152:155], v0 offset:1024
	ds_read_b128 v[156:159], v0 offset:2048
	ds_read_b128 v[160:163], v0 offset:3072
	v_add_u32_e32 v0, s58, v150
	ds_read_b128 v[164:167], v0
	ds_read_b128 v[168:171], v0 offset:1024
	ds_read_b128 v[172:175], v0 offset:2048
	ds_read_b128 v[180:183], v0 offset:3072
	v_lshl_add_u64 v[148:149], s[14:15], 0, v[140:141]
	s_add_i32 m0, s36, 0xc000
	ds_read_b128 v[184:187], v151
	ds_read_b128 v[188:191], v151 offset:1024
	ds_read_b128 v[192:195], v151 offset:2048
	ds_read_b128 v[196:199], v151 offset:3072
	ds_read_b128 v[200:203], v151 offset:4096
	ds_read_b128 v[204:207], v151 offset:5120
	ds_read_b128 v[208:211], v151 offset:6144
	ds_read_b128 v[212:215], v151 offset:7168
	global_load_lds_dwordx4 v[148:149], off
	v_lshl_add_u64 v[148:149], s[14:15], 0, v[142:143]
	s_add_i32 m0, s36, 0xe000
	s_nop 0
	global_load_lds_dwordx4 v[148:149], off
	s_waitcnt vmcnt(8)
	s_waitcnt lgkmcnt(0)
	s_barrier
	s_setprio 1
	v_mfma_f32_16x16x32_bf16 v[126:129], v[144:147], v[184:187], v[126:129]
	v_mfma_f32_16x16x32_bf16 v[122:125], v[156:159], v[184:187], v[122:125]
	v_mfma_f32_16x16x32_bf16 v[118:121], v[144:147], v[192:195], v[118:121]
	v_mfma_f32_16x16x32_bf16 v[114:117], v[156:159], v[192:195], v[114:117]
	v_mfma_f32_16x16x32_bf16 v[110:113], v[144:147], v[200:203], v[110:113]
	v_mfma_f32_16x16x32_bf16 v[106:109], v[156:159], v[200:203], v[106:109]
	v_mfma_f32_16x16x32_bf16 v[102:105], v[144:147], v[208:211], v[102:105]
	v_mfma_f32_16x16x32_bf16 v[98:101], v[156:159], v[208:211], v[98:101]
	v_mfma_f32_16x16x32_bf16 v[126:129], v[152:155], v[188:191], v[126:129]
	v_mfma_f32_16x16x32_bf16 v[122:125], v[160:163], v[188:191], v[122:125]
	v_mfma_f32_16x16x32_bf16 v[118:121], v[152:155], v[196:199], v[118:121]
	v_mfma_f32_16x16x32_bf16 v[114:117], v[160:163], v[196:199], v[114:117]
	v_mfma_f32_16x16x32_bf16 v[110:113], v[152:155], v[204:207], v[110:113]
	v_mfma_f32_16x16x32_bf16 v[106:109], v[160:163], v[204:207], v[106:109]
	v_mfma_f32_16x16x32_bf16 v[102:105], v[152:155], v[212:215], v[102:105]
	v_mfma_f32_16x16x32_bf16 v[98:101], v[160:163], v[212:215], v[98:101]
	v_mfma_f32_16x16x32_bf16 v[62:65], v[164:167], v[184:187], v[62:65]
	v_mfma_f32_16x16x32_bf16 v[58:61], v[172:175], v[184:187], v[58:61]
	v_mfma_f32_16x16x32_bf16 v[54:57], v[164:167], v[192:195], v[54:57]
	v_mfma_f32_16x16x32_bf16 v[50:53], v[172:175], v[192:195], v[50:53]
	v_mfma_f32_16x16x32_bf16 v[46:49], v[164:167], v[200:203], v[46:49]
	v_mfma_f32_16x16x32_bf16 v[42:45], v[172:175], v[200:203], v[42:45]
	v_mfma_f32_16x16x32_bf16 v[38:41], v[164:167], v[208:211], v[38:41]
	v_mfma_f32_16x16x32_bf16 v[34:37], v[172:175], v[208:211], v[34:37]
	v_mfma_f32_16x16x32_bf16 v[62:65], v[168:171], v[188:191], v[62:65]
	v_mfma_f32_16x16x32_bf16 v[58:61], v[180:183], v[188:191], v[58:61]
	v_mfma_f32_16x16x32_bf16 v[54:57], v[168:171], v[196:199], v[54:57]
	v_mfma_f32_16x16x32_bf16 v[50:53], v[180:183], v[196:199], v[50:53]
	v_mfma_f32_16x16x32_bf16 v[46:49], v[168:171], v[204:207], v[46:49]
	v_mfma_f32_16x16x32_bf16 v[42:45], v[180:183], v[204:207], v[42:45]
	v_mfma_f32_16x16x32_bf16 v[38:41], v[168:171], v[212:215], v[38:41]
	v_mfma_f32_16x16x32_bf16 v[34:37], v[180:183], v[212:215], v[34:37]
	s_setprio 0
	s_barrier
	s_add_i32 s53, s53, s59
	v_lshl_add_u64 v[148:149], s[16:17], 0, v[132:133]
	s_mov_b32 m0, s53
	ds_read_b128 v[184:187], v151 offset:16384
	ds_read_b128 v[188:191], v151 offset:17408
	ds_read_b128 v[192:195], v151 offset:18432
	ds_read_b128 v[196:199], v151 offset:19456
	ds_read_b128 v[200:203], v151 offset:20480
	ds_read_b128 v[204:207], v151 offset:21504
	ds_read_b128 v[208:211], v151 offset:22528
	ds_read_b128 v[212:215], v151 offset:23552
	global_load_lds_dwordx4 v[148:149], off
	s_add_i32 m0, s53, 0x2000
	s_add_u32 s54, s16, 0x20000
	v_lshl_add_u64 v[216:217], s[16:17], 0, v[136:137]
	s_addc_u32 s55, s17, 0
	s_add_i32 s53, s58, s59
	global_load_lds_dwordx4 v[216:217], off
	v_lshl_add_u64 v[218:219], s[54:55], 0, v[132:133]
	s_mov_b32 m0, s53
	v_lshl_add_u64 v[220:221], s[18:19], 0, v[134:135]
	global_load_lds_dwordx4 v[218:219], off
	v_lshl_add_u64 v[218:219], s[54:55], 0, v[136:137]
	s_add_i32 m0, s53, 0x2000
	s_nop 0
	global_load_lds_dwordx4 v[218:219], off
	v_lshl_add_u64 v[218:219], s[18:19], 0, v[130:131]
	s_mov_b32 m0, s36
	s_nop 0
	global_load_lds_dwordx4 v[218:219], off
	s_mov_b32 m0, s37
	s_nop 0
	global_load_lds_dwordx4 v[220:221], off
	s_waitcnt vmcnt(8)
	s_waitcnt lgkmcnt(0)
	s_barrier
; #define PG8_STAGE(bufoff, gbase, voff) do { _Pragma("unroll") for (int _i = 0; _i < 2; ++_i) \
;         __builtin_amdgcn_global_load_lds((const unsigned*)((const char*)(gbase) + (voff)[_i]), (LAS unsigned*)(lds + (bufoff) + ldsw + _i * 8192), 16, 0, 0); } while (0)
; #define PG8_LDA(dst, b, h) do { _Pragma("unroll") for (int m = 0; m < 4; ++m) _Pragma("unroll") for (int k = 0; k < 2; ++k) dst[m][k] = *(const LAS bf16x8*)(lds + PG8_SA(b, h) + aoff + m * 2048 + k * 1024); } while (0)
; #define PG8_LDB(dst, b, h) do { _Pragma("unroll") for (int n = 0; n < 2; ++n) _Pragma("unroll") for (int k = 0; k < 2; ++k) dst[n][k] = *(const LAS bf16x8*)(lds + PG8_SB(b, h) + boff + n * 2048 + k * 1024); } while (0)
; #define PG8_MMA(ai, bj, At, Bt) do { __builtin_amdgcn_s_setprio(1); _Pragma("unroll") for (int m = 0; m < 4; ++m) _Pragma("unroll") for (int n = 0; n < 2; ++n) _Pragma("unroll") for (int k = 0; k < 2; ++k) \
;         acc[ai][bj][m][n] = __builtin_amdgcn_mfma_f32_16x16x32_bf16(Bt[n][k], At[m][k], acc[ai][bj][m][n], 0, 0, 0); __builtin_amdgcn_s_setprio(0); } while (0)
; #define PG8_WAIT_V(n) asm volatile("s_waitcnt vmcnt(" #n ")" ::: "memory")
; #define PG8_WAIT_L(n) asm volatile("s_waitcnt lgkmcnt(" #n ")" ::: "memory")
; #define PG8_BAR __builtin_amdgcn_s_barrier()
; #define PG8_SCHED __builtin_amdgcn_sched_barrier(0)
; template <class Epi, class Sched, int LDA, int LDB, bool ALIGN_EPI = true>
; __device__ __forceinline__ void gemm_phase(LAS unsigned char* lds, const Gemm g, const Sched& S, const Epi& E, int wave) {
;     ...
;             PG8_WAIT_V(8); PG8_WAIT_L(0); PG8_BAR; PG8_MMA(1, 0, At, B0); PG8_MMA(1, 1, At, B1); PG8_BAR; PG8_SCHED;
;             PG8_LDB(B0, 1, 0); PG8_LDB(B1, 1, 1); PG8_SCHED; PG8_LDA(At, 1, 0); PG8_STAGE(PG8_SA(0, 1), a2 + hstepA, voffA);
;             PG8_WAIT_V(8); PG8_WAIT_L(0); PG8_BAR; PG8_MMA(0, 0, At, B0); PG8_MMA(0, 1, At, B1); PG8_BAR; PG8_SCHED;
	s_setprio 1
	v_mfma_f32_16x16x32_bf16 v[94:97], v[144:147], v[184:187], v[94:97]
	v_mfma_f32_16x16x32_bf16 v[90:93], v[156:159], v[184:187], v[90:93]
	v_mfma_f32_16x16x32_bf16 v[86:89], v[144:147], v[192:195], v[86:89]
	v_mfma_f32_16x16x32_bf16 v[82:85], v[156:159], v[192:195], v[82:85]
	v_mfma_f32_16x16x32_bf16 v[78:81], v[144:147], v[200:203], v[78:81]
	v_mfma_f32_16x16x32_bf16 v[74:77], v[156:159], v[200:203], v[74:77]
	v_mfma_f32_16x16x32_bf16 v[70:73], v[144:147], v[208:211], v[70:73]
	v_mfma_f32_16x16x32_bf16 v[66:69], v[156:159], v[208:211], v[66:69]
	v_mfma_f32_16x16x32_bf16 v[94:97], v[152:155], v[188:191], v[94:97]
	v_mfma_f32_16x16x32_bf16 v[90:93], v[160:163], v[188:191], v[90:93]
	v_mfma_f32_16x16x32_bf16 v[86:89], v[152:155], v[196:199], v[86:89]
	v_mfma_f32_16x16x32_bf16 v[82:85], v[160:163], v[196:199], v[82:85]
	v_mfma_f32_16x16x32_bf16 v[78:81], v[152:155], v[204:207], v[78:81]
	v_mfma_f32_16x16x32_bf16 v[74:77], v[160:163], v[204:207], v[74:77]
	v_mfma_f32_16x16x32_bf16 v[70:73], v[152:155], v[212:215], v[70:73]
	v_mfma_f32_16x16x32_bf16 v[66:69], v[160:163], v[212:215], v[66:69]
	v_mfma_f32_16x16x32_bf16 v[30:33], v[164:167], v[184:187], v[30:33]
	v_mfma_f32_16x16x32_bf16 v[26:29], v[172:175], v[184:187], v[26:29]
	v_mfma_f32_16x16x32_bf16 v[22:25], v[164:167], v[192:195], v[22:25]
	v_mfma_f32_16x16x32_bf16 v[18:21], v[172:175], v[192:195], v[18:21]
	v_mfma_f32_16x16x32_bf16 v[14:17], v[164:167], v[200:203], v[14:17]
	v_mfma_f32_16x16x32_bf16 v[10:13], v[172:175], v[200:203], v[10:13]
	v_mfma_f32_16x16x32_bf16 v[6:9], v[164:167], v[208:211], v[6:9]
	v_mfma_f32_16x16x32_bf16 v[2:5], v[172:175], v[208:211], v[2:5]
	v_mfma_f32_16x16x32_bf16 v[30:33], v[168:171], v[188:191], v[30:33]
	v_mfma_f32_16x16x32_bf16 v[26:29], v[180:183], v[188:191], v[26:29]
	v_mfma_f32_16x16x32_bf16 v[22:25], v[168:171], v[196:199], v[22:25]
	v_mfma_f32_16x16x32_bf16 v[18:21], v[180:183], v[196:199], v[18:21]
	v_mfma_f32_16x16x32_bf16 v[14:17], v[168:171], v[204:207], v[14:17]
	v_mfma_f32_16x16x32_bf16 v[10:13], v[180:183], v[204:207], v[10:13]
	v_mfma_f32_16x16x32_bf16 v[6:9], v[168:171], v[212:215], v[6:9]
	v_mfma_f32_16x16x32_bf16 v[2:5], v[180:183], v[212:215], v[2:5]
	s_setprio 0
	s_barrier
	s_add_i32 s53, 0, 0x18000
	v_add_u32_e32 v0, s53, v150
	s_add_i32 s54, 0, 0x1c000
	ds_read_b128 v[144:147], v0
	ds_read_b128 v[152:155], v0 offset:1024
	ds_read_b128 v[156:159], v0 offset:2048
	ds_read_b128 v[160:163], v0 offset:3072
	v_add_u32_e32 v0, s54, v150
	ds_read_b128 v[164:167], v0
	ds_read_b128 v[168:171], v0 offset:1024
	ds_read_b128 v[172:175], v0 offset:2048
	ds_read_b128 v[180:183], v0 offset:3072
	s_add_u32 s18, s18, 0x20000
	s_addc_u32 s19, s19, 0
	s_mov_b32 m0, s38
	v_lshl_add_u64 v[222:223], s[18:19], 0, v[130:131]
	ds_read_b128 v[184:187], v151 offset:32768
	ds_read_b128 v[188:191], v151 offset:33792
	ds_read_b128 v[192:195], v151 offset:34816
	ds_read_b128 v[196:199], v151 offset:35840
	ds_read_b128 v[200:203], v151 offset:36864
	ds_read_b128 v[204:207], v151 offset:37888
	ds_read_b128 v[208:211], v151 offset:38912
	ds_read_b128 v[212:215], v151 offset:39936
	global_load_lds_dwordx4 v[222:223], off
	v_lshl_add_u64 v[222:223], s[18:19], 0, v[134:135]
	s_mov_b32 m0, s39
	s_nop 0
	global_load_lds_dwordx4 v[222:223], off
	s_waitcnt vmcnt(8)
	s_waitcnt lgkmcnt(0)
	s_barrier
	s_setprio 1
	v_mfma_f32_16x16x32_bf16 v[126:129], v[144:147], v[184:187], v[126:129]
	v_mfma_f32_16x16x32_bf16 v[122:125], v[156:159], v[184:187], v[122:125]
	v_mfma_f32_16x16x32_bf16 v[118:121], v[144:147], v[192:195], v[118:121]
	v_mfma_f32_16x16x32_bf16 v[114:117], v[156:159], v[192:195], v[114:117]
	v_mfma_f32_16x16x32_bf16 v[110:113], v[144:147], v[200:203], v[110:113]
	v_mfma_f32_16x16x32_bf16 v[106:109], v[156:159], v[200:203], v[106:109]
	v_mfma_f32_16x16x32_bf16 v[102:105], v[144:147], v[208:211], v[102:105]
	v_mfma_f32_16x16x32_bf16 v[98:101], v[156:159], v[208:211], v[98:101]
	v_mfma_f32_16x16x32_bf16 v[126:129], v[152:155], v[188:191], v[126:129]
	v_mfma_f32_16x16x32_bf16 v[122:125], v[160:163], v[188:191], v[122:125]
	v_mfma_f32_16x16x32_bf16 v[118:121], v[152:155], v[196:199], v[118:121]
	v_mfma_f32_16x16x32_bf16 v[114:117], v[160:163], v[196:199], v[114:117]
	v_mfma_f32_16x16x32_bf16 v[110:113], v[152:155], v[204:207], v[110:113]
	v_mfma_f32_16x16x32_bf16 v[106:109], v[160:163], v[204:207], v[106:109]
	v_mfma_f32_16x16x32_bf16 v[102:105], v[152:155], v[212:215], v[102:105]
	v_mfma_f32_16x16x32_bf16 v[98:101], v[160:163], v[212:215], v[98:101]
	v_mfma_f32_16x16x32_bf16 v[62:65], v[164:167], v[184:187], v[62:65]
	v_mfma_f32_16x16x32_bf16 v[58:61], v[172:175], v[184:187], v[58:61]
	v_mfma_f32_16x16x32_bf16 v[54:57], v[164:167], v[192:195], v[54:57]
	v_mfma_f32_16x16x32_bf16 v[50:53], v[172:175], v[192:195], v[50:53]
	v_mfma_f32_16x16x32_bf16 v[46:49], v[164:167], v[200:203], v[46:49]
	v_mfma_f32_16x16x32_bf16 v[42:45], v[172:175], v[200:203], v[42:45]
	v_mfma_f32_16x16x32_bf16 v[38:41], v[164:167], v[208:211], v[38:41]
	v_mfma_f32_16x16x32_bf16 v[34:37], v[172:175], v[208:211], v[34:37]
	v_mfma_f32_16x16x32_bf16 v[62:65], v[168:171], v[188:191], v[62:65]
	v_mfma_f32_16x16x32_bf16 v[58:61], v[180:183], v[188:191], v[58:61]
	v_mfma_f32_16x16x32_bf16 v[54:57], v[168:171], v[196:199], v[54:57]
	v_mfma_f32_16x16x32_bf16 v[50:53], v[180:183], v[196:199], v[50:53]
	v_mfma_f32_16x16x32_bf16 v[46:49], v[168:171], v[204:207], v[46:49]
	v_mfma_f32_16x16x32_bf16 v[42:45], v[180:183], v[204:207], v[42:45]
	v_mfma_f32_16x16x32_bf16 v[38:41], v[168:171], v[212:215], v[38:41]
	v_mfma_f32_16x16x32_bf16 v[34:37], v[180:183], v[212:215], v[34:37]
	s_setprio 0
	s_barrier
; #define PG8_STAGE(bufoff, gbase, voff) do { _Pragma("unroll") for (int _i = 0; _i < 2; ++_i) \
;         __builtin_amdgcn_global_load_lds((const unsigned*)((const char*)(gbase) + (voff)[_i]), (LAS unsigned*)(lds + (bufoff) + ldsw + _i * 8192), 16, 0, 0); } while (0)
; #define PG8_LDA(dst, b, h) do { _Pragma("unroll") for (int m = 0; m < 4; ++m) _Pragma("unroll") for (int k = 0; k < 2; ++k) dst[m][k] = *(const LAS bf16x8*)(lds + PG8_SA(b, h) + aoff + m * 2048 + k * 1024); } while (0)
; #define PG8_MMA(ai, bj, At, Bt) do { __builtin_amdgcn_s_setprio(1); _Pragma("unroll") for (int m = 0; m < 4; ++m) _Pragma("unroll") for (int n = 0; n < 2; ++n) _Pragma("unroll") for (int k = 0; k < 2; ++k) \
;         acc[ai][bj][m][n] = __builtin_amdgcn_mfma_f32_16x16x32_bf16(Bt[n][k], At[m][k], acc[ai][bj][m][n], 0, 0, 0); __builtin_amdgcn_s_setprio(0); } while (0)
; #define PG8_WAIT_V(n) asm volatile("s_waitcnt vmcnt(" #n ")" ::: "memory")
; #define PG8_WAIT_L(n) asm volatile("s_waitcnt lgkmcnt(" #n ")" ::: "memory")
; #define PG8_BAR __builtin_amdgcn_s_barrier()
; #define PG8_SCHED __builtin_amdgcn_sched_barrier(0)
; template <class Epi, class Sched, int LDA, int LDB, bool ALIGN_EPI = true>
; __device__ __forceinline__ void gemm_phase(LAS unsigned char* lds, const Gemm g, const Sched& S, const Epi& E, int wave) {
;     ...
;             PG8_LDA(At, 1, 1); PG8_STAGE(PG8_SB(1, 0), b3, voffB); PG8_STAGE(PG8_SB(1, 1), b3 + hstepB, voffB); PG8_STAGE(PG8_SA(1, 0), a3, voffA);
;             PG8_WAIT_V(8); PG8_WAIT_L(0); PG8_BAR; PG8_MMA(1, 0, At, B0); PG8_MMA(1, 1, At, B1); PG8_BAR; PG8_SCHED;
;         }
;         if constexpr (ALIGN_EPI) { if (wr == 0) PG8_BAR; }
	s_add_i32 s18, s53, s59
	v_lshl_add_u64 v[148:149], v[148:149], 0, s[70:71]
	s_mov_b32 m0, s18
	ds_read_b128 v[184:187], v151 offset:49152
	ds_read_b128 v[188:191], v151 offset:50176
	ds_read_b128 v[192:195], v151 offset:51200
	ds_read_b128 v[196:199], v151 offset:52224
	ds_read_b128 v[200:203], v151 offset:53248
	ds_read_b128 v[204:207], v151 offset:54272
	ds_read_b128 v[208:211], v151 offset:55296
	ds_read_b128 v[212:215], v151 offset:56320
	global_load_lds_dwordx4 v[148:149], off
	s_add_i32 m0, s18, 0x2000
	s_add_u32 s16, s16, 0x20080
	v_lshl_add_u64 v[148:149], v[216:217], 0, s[70:71]
	s_addc_u32 s17, s17, 0
	s_add_i32 s18, s54, s59
	global_load_lds_dwordx4 v[148:149], off
	v_lshl_add_u64 v[148:149], s[16:17], 0, v[132:133]
	s_mov_b32 m0, s18
	s_nop 0
	global_load_lds_dwordx4 v[148:149], off
	v_lshl_add_u64 v[148:149], s[16:17], 0, v[136:137]
	s_add_i32 m0, s18, 0x2000
	s_nop 0
	global_load_lds_dwordx4 v[148:149], off
	v_lshl_add_u64 v[148:149], v[218:219], 0, s[70:71]
	s_mov_b32 m0, s46
	s_nop 0
	global_load_lds_dwordx4 v[148:149], off
	v_lshl_add_u64 v[148:149], v[220:221], 0, s[70:71]
	s_mov_b32 m0, s47
	s_nop 0
	global_load_lds_dwordx4 v[148:149], off
	s_waitcnt vmcnt(8)
	s_waitcnt lgkmcnt(0)
	s_barrier
	s_setprio 1
	v_mfma_f32_16x16x32_bf16 v[94:97], v[144:147], v[184:187], v[94:97]
	v_mfma_f32_16x16x32_bf16 v[90:93], v[156:159], v[184:187], v[90:93]
	v_mfma_f32_16x16x32_bf16 v[86:89], v[144:147], v[192:195], v[86:89]
	v_mfma_f32_16x16x32_bf16 v[82:85], v[156:159], v[192:195], v[82:85]
	v_mfma_f32_16x16x32_bf16 v[78:81], v[144:147], v[200:203], v[78:81]
	v_mfma_f32_16x16x32_bf16 v[74:77], v[156:159], v[200:203], v[74:77]
	v_mfma_f32_16x16x32_bf16 v[70:73], v[144:147], v[208:211], v[70:73]
	v_mfma_f32_16x16x32_bf16 v[66:69], v[156:159], v[208:211], v[66:69]
	v_mfma_f32_16x16x32_bf16 v[94:97], v[152:155], v[188:191], v[94:97]
	v_mfma_f32_16x16x32_bf16 v[90:93], v[160:163], v[188:191], v[90:93]
	v_mfma_f32_16x16x32_bf16 v[86:89], v[152:155], v[196:199], v[86:89]
	v_mfma_f32_16x16x32_bf16 v[82:85], v[160:163], v[196:199], v[82:85]
	v_mfma_f32_16x16x32_bf16 v[78:81], v[152:155], v[204:207], v[78:81]
	v_mfma_f32_16x16x32_bf16 v[74:77], v[160:163], v[204:207], v[74:77]
	v_mfma_f32_16x16x32_bf16 v[70:73], v[152:155], v[212:215], v[70:73]
	v_mfma_f32_16x16x32_bf16 v[66:69], v[160:163], v[212:215], v[66:69]
	v_mfma_f32_16x16x32_bf16 v[30:33], v[164:167], v[184:187], v[30:33]
	v_mfma_f32_16x16x32_bf16 v[26:29], v[172:175], v[184:187], v[26:29]
	v_mfma_f32_16x16x32_bf16 v[22:25], v[164:167], v[192:195], v[22:25]
	v_mfma_f32_16x16x32_bf16 v[18:21], v[172:175], v[192:195], v[18:21]
	v_mfma_f32_16x16x32_bf16 v[14:17], v[164:167], v[200:203], v[14:17]
	v_mfma_f32_16x16x32_bf16 v[10:13], v[172:175], v[200:203], v[10:13]
	v_mfma_f32_16x16x32_bf16 v[6:9], v[164:167], v[208:211], v[6:9]
	v_mfma_f32_16x16x32_bf16 v[2:5], v[172:175], v[208:211], v[2:5]
	v_mfma_f32_16x16x32_bf16 v[30:33], v[168:171], v[188:191], v[30:33]
	v_mfma_f32_16x16x32_bf16 v[26:29], v[180:183], v[188:191], v[26:29]
	v_mfma_f32_16x16x32_bf16 v[22:25], v[168:171], v[196:199], v[22:25]
	v_mfma_f32_16x16x32_bf16 v[18:21], v[180:183], v[196:199], v[18:21]
	v_mfma_f32_16x16x32_bf16 v[14:17], v[168:171], v[204:207], v[14:17]
	v_mfma_f32_16x16x32_bf16 v[10:13], v[180:183], v[204:207], v[10:13]
	v_mfma_f32_16x16x32_bf16 v[6:9], v[168:171], v[212:215], v[6:9]
	v_mfma_f32_16x16x32_bf16 v[2:5], v[180:183], v[212:215], v[2:5]
	s_setprio 0
	s_barrier
	s_add_i32 s52, s52, 2
	s_add_u32 s14, s14, 0x100
	s_addc_u32 s15, s15, 0
	s_add_u32 s45, s45, 0x100
	s_addc_u32 s51, s51, 0
	s_cmp_gt_u32 s52, 5
	s_cbranch_scc0 .LBB0_2619
	v_readlane_b32 s14, v252, 14
	v_readlane_b32 s15, v252, 15
	s_and_b64 vcc, exec, s[14:15]
	s_cbranch_vccz .LBB0_2622
	s_barrier

; #define PG8_STAGE(bufoff, gbase, voff) do { _Pragma("unroll") for (int _i = 0; _i < 2; ++_i) \
;         __builtin_amdgcn_global_load_lds((const unsigned*)((const char*)(gbase) + (voff)[_i]), (LAS unsigned*)(lds + (bufoff) + ldsw + _i * 8192), 16, 0, 0); } while (0)
; #define PG8_LDA(dst, b, h) do { _Pragma("unroll") for (int m = 0; m < 4; ++m) _Pragma("unroll") for (int k = 0; k < 2; ++k) dst[m][k] = *(const LAS bf16x8*)(lds + PG8_SA(b, h) + aoff + m * 2048 + k * 1024); } while (0)
; #define PG8_LDB(dst, b, h) do { _Pragma("unroll") for (int n = 0; n < 2; ++n) _Pragma("unroll") for (int k = 0; k < 2; ++k) dst[n][k] = *(const LAS bf16x8*)(lds + PG8_SB(b, h) + boff + n * 2048 + k * 1024); } while (0)
; #define PG8_MMA(ai, bj, At, Bt) do { __builtin_amdgcn_s_setprio(1); _Pragma("unroll") for (int m = 0; m < 4; ++m) _Pragma("unroll") for (int n = 0; n < 2; ++n) _Pragma("unroll") for (int k = 0; k < 2; ++k) \
;         acc[ai][bj][m][n] = __builtin_amdgcn_mfma_f32_16x16x32_bf16(Bt[n][k], At[m][k], acc[ai][bj][m][n], 0, 0, 0); __builtin_amdgcn_s_setprio(0); } while (0)
; #define PG8_WAIT_V(n) asm volatile("s_waitcnt vmcnt(" #n ")" ::: "memory")
; #define PG8_WAIT_L(n) asm volatile("s_waitcnt lgkmcnt(" #n ")" ::: "memory")
; #define PG8_BAR __builtin_amdgcn_s_barrier()
; template <class Epi, class Sched, int LDA, int LDB, bool ALIGN_EPI = true>
; __device__ __forceinline__ void gemm_phase(LAS unsigned char* lds, const Gemm g, const Sched& S, const Epi& E, int wave) {
;     ...
;         for (int t = 0; t < nt; t += 2) {
;             const bool last = (t == nt - 2);
;             const char* a1 = cA + (size_t)(t + 1) * kstep;
;             const char* a2 = last ? nA : cA + (size_t)(t + 2) * kstep; const char* b2 = last ? nB : cB + (size_t)(t + 2) * kstep;
;             const char* a3 = a2 + kstep; const char* b3 = b2 + kstep;
;             PG8_LDB(B0, 0, 0); PG8_LDB(B1, 0, 1); PG8_SCHED; PG8_LDA(At, 0, 0); PG8_STAGE(PG8_SA(1, 1), a1 + hstepA, voffA);
;             PG8_WAIT_V(8); PG8_WAIT_L(0); PG8_BAR; PG8_MMA(0, 0, At, B0); PG8_MMA(0, 1, At, B1); PG8_BAR; PG8_SCHED;
;             PG8_LDA(At, 0, 1); PG8_STAGE(PG8_SB(0, 0), b2, voffB); PG8_STAGE(PG8_SB(0, 1), b2 + hstepB, voffB); PG8_STAGE(PG8_SA(0, 0), a2, voffA);
;             PG8_WAIT_V(8); PG8_WAIT_L(0); PG8_BAR; PG8_MMA(1, 0, At, B0); PG8_MMA(1, 1, At, B1); PG8_BAR; PG8_SCHED;
.LBB0_2649:
	s_add_u32 s18, s16, 0xfffe0080
	s_addc_u32 s19, s17, -1
	s_add_i32 s48, 0, 0x10000
	s_cmp_eq_u32 s47, 4
	s_cselect_b32 s25, s7, s19
	s_cselect_b32 s24, s13, s18
	s_cselect_b32 s19, s3, s46
	s_cselect_b32 s18, s44, s45
	s_add_i32 s50, 0, 0x14000
	v_add_u32_e32 v152, s48, v161
	v_add_u32_e32 v172, s50, v161
	ds_read_b128 v[130:133], v152
	ds_read_b128 v[134:137], v152 offset:1024
	ds_read_b128 v[148:151], v152 offset:2048
	ds_read_b128 v[152:155], v152 offset:3072
	ds_read_b128 v[156:159], v172
	ds_read_b128 v[164:167], v172 offset:1024
	ds_read_b128 v[168:171], v172 offset:2048
	ds_read_b128 v[172:175], v172 offset:3072
	v_lshl_add_u64 v[212:213], s[16:17], 0, v[144:145]
	s_add_i32 m0, s15, 0xc000
	ds_read_b128 v[180:183], v163
	ds_read_b128 v[184:187], v163 offset:1024
	ds_read_b128 v[188:191], v163 offset:2048
	ds_read_b128 v[192:195], v163 offset:3072
	ds_read_b128 v[196:199], v163 offset:4096
	ds_read_b128 v[200:203], v163 offset:5120
	ds_read_b128 v[204:207], v163 offset:6144
	ds_read_b128 v[208:211], v163 offset:7168
	global_load_lds_dwordx4 v[212:213], off
	v_lshl_add_u64 v[212:213], s[16:17], 0, v[146:147]
	s_add_i32 m0, s15, 0xe000
	s_nop 0
	global_load_lds_dwordx4 v[212:213], off
	s_waitcnt vmcnt(8)
	s_waitcnt lgkmcnt(0)
	s_barrier
	s_setprio 1
	v_mfma_f32_16x16x32_bf16 v[126:129], v[130:133], v[180:183], v[126:129]
	v_mfma_f32_16x16x32_bf16 v[122:125], v[148:151], v[180:183], v[122:125]
	v_mfma_f32_16x16x32_bf16 v[110:113], v[130:133], v[188:191], v[110:113]
	v_mfma_f32_16x16x32_bf16 v[106:109], v[148:151], v[188:191], v[106:109]
	v_mfma_f32_16x16x32_bf16 v[94:97], v[130:133], v[196:199], v[94:97]
	v_mfma_f32_16x16x32_bf16 v[90:93], v[148:151], v[196:199], v[90:93]
	v_mfma_f32_16x16x32_bf16 v[78:81], v[130:133], v[204:207], v[78:81]
	v_mfma_f32_16x16x32_bf16 v[74:77], v[148:151], v[204:207], v[74:77]
	v_mfma_f32_16x16x32_bf16 v[126:129], v[134:137], v[184:187], v[126:129]
	v_mfma_f32_16x16x32_bf16 v[122:125], v[152:155], v[184:187], v[122:125]
	v_mfma_f32_16x16x32_bf16 v[110:113], v[134:137], v[192:195], v[110:113]
	v_mfma_f32_16x16x32_bf16 v[106:109], v[152:155], v[192:195], v[106:109]
	v_mfma_f32_16x16x32_bf16 v[94:97], v[134:137], v[200:203], v[94:97]
	v_mfma_f32_16x16x32_bf16 v[90:93], v[152:155], v[200:203], v[90:93]
	v_mfma_f32_16x16x32_bf16 v[78:81], v[134:137], v[208:211], v[78:81]
	v_mfma_f32_16x16x32_bf16 v[74:77], v[152:155], v[208:211], v[74:77]
	v_mfma_f32_16x16x32_bf16 v[118:121], v[156:159], v[180:183], v[118:121]
	v_mfma_f32_16x16x32_bf16 v[114:117], v[168:171], v[180:183], v[114:117]
	v_mfma_f32_16x16x32_bf16 v[102:105], v[156:159], v[188:191], v[102:105]
	v_mfma_f32_16x16x32_bf16 v[98:101], v[168:171], v[188:191], v[98:101]
	v_mfma_f32_16x16x32_bf16 v[86:89], v[156:159], v[196:199], v[86:89]
	v_mfma_f32_16x16x32_bf16 v[82:85], v[168:171], v[196:199], v[82:85]
	v_mfma_f32_16x16x32_bf16 v[70:73], v[156:159], v[204:207], v[70:73]
	v_mfma_f32_16x16x32_bf16 v[66:69], v[168:171], v[204:207], v[66:69]
	v_mfma_f32_16x16x32_bf16 v[118:121], v[164:167], v[184:187], v[118:121]
	v_mfma_f32_16x16x32_bf16 v[114:117], v[172:175], v[184:187], v[114:117]
	v_mfma_f32_16x16x32_bf16 v[102:105], v[164:167], v[192:195], v[102:105]
	v_mfma_f32_16x16x32_bf16 v[98:101], v[172:175], v[192:195], v[98:101]
	v_mfma_f32_16x16x32_bf16 v[86:89], v[164:167], v[200:203], v[86:89]
	v_mfma_f32_16x16x32_bf16 v[82:85], v[172:175], v[200:203], v[82:85]
	v_mfma_f32_16x16x32_bf16 v[70:73], v[164:167], v[208:211], v[70:73]
	v_mfma_f32_16x16x32_bf16 v[66:69], v[172:175], v[208:211], v[66:69]
	s_setprio 0
	s_barrier
	s_add_i32 s48, s48, s51
	v_lshl_add_u64 v[212:213], s[18:19], 0, v[0:1]
	s_mov_b32 m0, s48
	ds_read_b128 v[180:183], v163 offset:16384
	ds_read_b128 v[184:187], v163 offset:17408
	ds_read_b128 v[188:191], v163 offset:18432
	ds_read_b128 v[192:195], v163 offset:19456
	ds_read_b128 v[196:199], v163 offset:20480
	ds_read_b128 v[200:203], v163 offset:21504
	ds_read_b128 v[204:207], v163 offset:22528
	ds_read_b128 v[208:211], v163 offset:23552
	global_load_lds_dwordx4 v[212:213], off
	s_add_i32 m0, s48, 0x2000
	s_add_u32 s48, s18, 0x20000
	v_lshl_add_u64 v[214:215], s[18:19], 0, v[142:143]
	s_addc_u32 s49, s19, 0
	s_add_i32 s50, s50, s51
	global_load_lds_dwordx4 v[214:215], off
	v_lshl_add_u64 v[216:217], s[48:49], 0, v[0:1]
	s_mov_b32 m0, s50
	v_lshl_add_u64 v[218:219], s[24:25], 0, v[140:141]
	global_load_lds_dwordx4 v[216:217], off
	v_lshl_add_u64 v[216:217], s[48:49], 0, v[142:143]
	s_add_i32 m0, s50, 0x2000
	s_nop 0
	global_load_lds_dwordx4 v[216:217], off
	v_lshl_add_u64 v[216:217], s[24:25], 0, v[138:139]
	s_mov_b32 m0, s15
	s_nop 0
	global_load_lds_dwordx4 v[216:217], off
	s_mov_b32 m0, s28
	s_nop 0
	global_load_lds_dwordx4 v[218:219], off
	s_waitcnt vmcnt(8)
	s_waitcnt lgkmcnt(0)
	s_barrier
; #define PG8_STAGE(bufoff, gbase, voff) do { _Pragma("unroll") for (int _i = 0; _i < 2; ++_i) \
;         __builtin_amdgcn_global_load_lds((const unsigned*)((const char*)(gbase) + (voff)[_i]), (LAS unsigned*)(lds + (bufoff) + ldsw + _i * 8192), 16, 0, 0); } while (0)
; #define PG8_LDA(dst, b, h) do { _Pragma("unroll") for (int m = 0; m < 4; ++m) _Pragma("unroll") for (int k = 0; k < 2; ++k) dst[m][k] = *(const LAS bf16x8*)(lds + PG8_SA(b, h) + aoff + m * 2048 + k * 1024); } while (0)
; #define PG8_LDB(dst, b, h) do { _Pragma("unroll") for (int n = 0; n < 2; ++n) _Pragma("unroll") for (int k = 0; k < 2; ++k) dst[n][k] = *(const LAS bf16x8*)(lds + PG8_SB(b, h) + boff + n * 2048 + k * 1024); } while (0)
; #define PG8_MMA(ai, bj, At, Bt) do { __builtin_amdgcn_s_setprio(1); _Pragma("unroll") for (int m = 0; m < 4; ++m) _Pragma("unroll") for (int n = 0; n < 2; ++n) _Pragma("unroll") for (int k = 0; k < 2; ++k) \
;         acc[ai][bj][m][n] = __builtin_amdgcn_mfma_f32_16x16x32_bf16(Bt[n][k], At[m][k], acc[ai][bj][m][n], 0, 0, 0); __builtin_amdgcn_s_setprio(0); } while (0)
; #define PG8_WAIT_V(n) asm volatile("s_waitcnt vmcnt(" #n ")" ::: "memory")
; #define PG8_WAIT_L(n) asm volatile("s_waitcnt lgkmcnt(" #n ")" ::: "memory")
; #define PG8_BAR __builtin_amdgcn_s_barrier()
; #define PG8_SCHED __builtin_amdgcn_sched_barrier(0)
; template <class Epi, class Sched, int LDA, int LDB, bool ALIGN_EPI = true>
; __device__ __forceinline__ void gemm_phase(LAS unsigned char* lds, const Gemm g, const Sched& S, const Epi& E, int wave) {
;     ...
;             PG8_WAIT_V(8); PG8_WAIT_L(0); PG8_BAR; PG8_MMA(1, 0, At, B0); PG8_MMA(1, 1, At, B1); PG8_BAR; PG8_SCHED;
;             PG8_LDB(B0, 1, 0); PG8_LDB(B1, 1, 1); PG8_SCHED; PG8_LDA(At, 1, 0); PG8_STAGE(PG8_SA(0, 1), a2 + hstepA, voffA);
;             PG8_WAIT_V(8); PG8_WAIT_L(0); PG8_BAR; PG8_MMA(0, 0, At, B0); PG8_MMA(0, 1, At, B1); PG8_BAR; PG8_SCHED;
	s_setprio 1
	v_mfma_f32_16x16x32_bf16 v[62:65], v[130:133], v[180:183], v[62:65]
	v_mfma_f32_16x16x32_bf16 v[58:61], v[148:151], v[180:183], v[58:61]
	v_mfma_f32_16x16x32_bf16 v[46:49], v[130:133], v[188:191], v[46:49]
	v_mfma_f32_16x16x32_bf16 v[42:45], v[148:151], v[188:191], v[42:45]
	v_mfma_f32_16x16x32_bf16 v[30:33], v[130:133], v[196:199], v[30:33]
	v_mfma_f32_16x16x32_bf16 v[26:29], v[148:151], v[196:199], v[26:29]
	v_mfma_f32_16x16x32_bf16 v[14:17], v[130:133], v[204:207], v[14:17]
	v_mfma_f32_16x16x32_bf16 v[10:13], v[148:151], v[204:207], v[10:13]
	v_mfma_f32_16x16x32_bf16 v[62:65], v[134:137], v[184:187], v[62:65]
	v_mfma_f32_16x16x32_bf16 v[58:61], v[152:155], v[184:187], v[58:61]
	v_mfma_f32_16x16x32_bf16 v[46:49], v[134:137], v[192:195], v[46:49]
	v_mfma_f32_16x16x32_bf16 v[42:45], v[152:155], v[192:195], v[42:45]
	v_mfma_f32_16x16x32_bf16 v[30:33], v[134:137], v[200:203], v[30:33]
	v_mfma_f32_16x16x32_bf16 v[26:29], v[152:155], v[200:203], v[26:29]
	v_mfma_f32_16x16x32_bf16 v[14:17], v[134:137], v[208:211], v[14:17]
	v_mfma_f32_16x16x32_bf16 v[10:13], v[152:155], v[208:211], v[10:13]
	v_mfma_f32_16x16x32_bf16 v[54:57], v[156:159], v[180:183], v[54:57]
	v_mfma_f32_16x16x32_bf16 v[50:53], v[168:171], v[180:183], v[50:53]
	v_mfma_f32_16x16x32_bf16 v[38:41], v[156:159], v[188:191], v[38:41]
	v_mfma_f32_16x16x32_bf16 v[34:37], v[168:171], v[188:191], v[34:37]
	v_mfma_f32_16x16x32_bf16 v[22:25], v[156:159], v[196:199], v[22:25]
	v_mfma_f32_16x16x32_bf16 v[18:21], v[168:171], v[196:199], v[18:21]
	v_mfma_f32_16x16x32_bf16 v[6:9], v[156:159], v[204:207], v[6:9]
	v_mfma_f32_16x16x32_bf16 v[2:5], v[168:171], v[204:207], v[2:5]
	v_mfma_f32_16x16x32_bf16 v[54:57], v[164:167], v[184:187], v[54:57]
	v_mfma_f32_16x16x32_bf16 v[50:53], v[172:175], v[184:187], v[50:53]
	v_mfma_f32_16x16x32_bf16 v[38:41], v[164:167], v[192:195], v[38:41]
	v_mfma_f32_16x16x32_bf16 v[34:37], v[172:175], v[192:195], v[34:37]
	v_mfma_f32_16x16x32_bf16 v[22:25], v[164:167], v[200:203], v[22:25]
	v_mfma_f32_16x16x32_bf16 v[18:21], v[172:175], v[200:203], v[18:21]
	v_mfma_f32_16x16x32_bf16 v[6:9], v[164:167], v[208:211], v[6:9]
	v_mfma_f32_16x16x32_bf16 v[2:5], v[172:175], v[208:211], v[2:5]
	s_setprio 0
	s_barrier
	s_add_i32 s48, 0, 0x18000
	s_add_i32 s49, 0, 0x1c000
	v_add_u32_e32 v152, s48, v161
	v_add_u32_e32 v172, s49, v161
	ds_read_b128 v[130:133], v152
	ds_read_b128 v[134:137], v152 offset:1024
	ds_read_b128 v[148:151], v152 offset:2048
	ds_read_b128 v[152:155], v152 offset:3072
	ds_read_b128 v[156:159], v172
	ds_read_b128 v[164:167], v172 offset:1024
	ds_read_b128 v[168:171], v172 offset:2048
	ds_read_b128 v[172:175], v172 offset:3072
	s_add_u32 s24, s24, 0x20000
	s_addc_u32 s25, s25, 0
	s_mov_b32 m0, s29
	v_lshl_add_u64 v[220:221], s[24:25], 0, v[138:139]
	ds_read_b128 v[180:183], v163 offset:32768
	ds_read_b128 v[184:187], v163 offset:33792
	ds_read_b128 v[188:191], v163 offset:34816
	ds_read_b128 v[192:195], v163 offset:35840
	ds_read_b128 v[196:199], v163 offset:36864
	ds_read_b128 v[200:203], v163 offset:37888
	ds_read_b128 v[204:207], v163 offset:38912
	ds_read_b128 v[208:211], v163 offset:39936
	global_load_lds_dwordx4 v[220:221], off
	v_lshl_add_u64 v[220:221], s[24:25], 0, v[140:141]
	s_mov_b32 m0, s34
	s_nop 0
	global_load_lds_dwordx4 v[220:221], off
	s_waitcnt vmcnt(8)
	s_waitcnt lgkmcnt(0)
	s_barrier
	s_setprio 1
	v_mfma_f32_16x16x32_bf16 v[126:129], v[130:133], v[180:183], v[126:129]
	v_mfma_f32_16x16x32_bf16 v[122:125], v[148:151], v[180:183], v[122:125]
	v_mfma_f32_16x16x32_bf16 v[110:113], v[130:133], v[188:191], v[110:113]
	v_mfma_f32_16x16x32_bf16 v[106:109], v[148:151], v[188:191], v[106:109]
	v_mfma_f32_16x16x32_bf16 v[94:97], v[130:133], v[196:199], v[94:97]
	v_mfma_f32_16x16x32_bf16 v[90:93], v[148:151], v[196:199], v[90:93]
	v_mfma_f32_16x16x32_bf16 v[78:81], v[130:133], v[204:207], v[78:81]
	v_mfma_f32_16x16x32_bf16 v[74:77], v[148:151], v[204:207], v[74:77]
	v_mfma_f32_16x16x32_bf16 v[126:129], v[134:137], v[184:187], v[126:129]
	v_mfma_f32_16x16x32_bf16 v[122:125], v[152:155], v[184:187], v[122:125]
	v_mfma_f32_16x16x32_bf16 v[110:113], v[134:137], v[192:195], v[110:113]
	v_mfma_f32_16x16x32_bf16 v[106:109], v[152:155], v[192:195], v[106:109]
	v_mfma_f32_16x16x32_bf16 v[94:97], v[134:137], v[200:203], v[94:97]
	v_mfma_f32_16x16x32_bf16 v[90:93], v[152:155], v[200:203], v[90:93]
	v_mfma_f32_16x16x32_bf16 v[78:81], v[134:137], v[208:211], v[78:81]
	v_mfma_f32_16x16x32_bf16 v[74:77], v[152:155], v[208:211], v[74:77]
	v_mfma_f32_16x16x32_bf16 v[118:121], v[156:159], v[180:183], v[118:121]
	v_mfma_f32_16x16x32_bf16 v[114:117], v[168:171], v[180:183], v[114:117]
	v_mfma_f32_16x16x32_bf16 v[102:105], v[156:159], v[188:191], v[102:105]
	v_mfma_f32_16x16x32_bf16 v[98:101], v[168:171], v[188:191], v[98:101]
	v_mfma_f32_16x16x32_bf16 v[86:89], v[156:159], v[196:199], v[86:89]
	v_mfma_f32_16x16x32_bf16 v[82:85], v[168:171], v[196:199], v[82:85]
	v_mfma_f32_16x16x32_bf16 v[70:73], v[156:159], v[204:207], v[70:73]
	v_mfma_f32_16x16x32_bf16 v[66:69], v[168:171], v[204:207], v[66:69]
	v_mfma_f32_16x16x32_bf16 v[118:121], v[164:167], v[184:187], v[118:121]
	v_mfma_f32_16x16x32_bf16 v[114:117], v[172:175], v[184:187], v[114:117]
	v_mfma_f32_16x16x32_bf16 v[102:105], v[164:167], v[192:195], v[102:105]
	v_mfma_f32_16x16x32_bf16 v[98:101], v[172:175], v[192:195], v[98:101]
	v_mfma_f32_16x16x32_bf16 v[86:89], v[164:167], v[200:203], v[86:89]
	v_mfma_f32_16x16x32_bf16 v[82:85], v[172:175], v[200:203], v[82:85]
	v_mfma_f32_16x16x32_bf16 v[70:73], v[164:167], v[208:211], v[70:73]
	v_mfma_f32_16x16x32_bf16 v[66:69], v[172:175], v[208:211], v[66:69]
	s_setprio 0
	s_barrier
; #define PG8_STAGE(bufoff, gbase, voff) do { _Pragma("unroll") for (int _i = 0; _i < 2; ++_i) \
;         __builtin_amdgcn_global_load_lds((const unsigned*)((const char*)(gbase) + (voff)[_i]), (LAS unsigned*)(lds + (bufoff) + ldsw + _i * 8192), 16, 0, 0); } while (0)
; #define PG8_LDA(dst, b, h) do { _Pragma("unroll") for (int m = 0; m < 4; ++m) _Pragma("unroll") for (int k = 0; k < 2; ++k) dst[m][k] = *(const LAS bf16x8*)(lds + PG8_SA(b, h) + aoff + m * 2048 + k * 1024); } while (0)
; #define PG8_MMA(ai, bj, At, Bt) do { __builtin_amdgcn_s_setprio(1); _Pragma("unroll") for (int m = 0; m < 4; ++m) _Pragma("unroll") for (int n = 0; n < 2; ++n) _Pragma("unroll") for (int k = 0; k < 2; ++k) \
;         acc[ai][bj][m][n] = __builtin_amdgcn_mfma_f32_16x16x32_bf16(Bt[n][k], At[m][k], acc[ai][bj][m][n], 0, 0, 0); __builtin_amdgcn_s_setprio(0); } while (0)
; #define PG8_WAIT_V(n) asm volatile("s_waitcnt vmcnt(" #n ")" ::: "memory")
; #define PG8_WAIT_L(n) asm volatile("s_waitcnt lgkmcnt(" #n ")" ::: "memory")
; #define PG8_BAR __builtin_amdgcn_s_barrier()
; #define PG8_SCHED __builtin_amdgcn_sched_barrier(0)
; template <class Epi, class Sched, int LDA, int LDB, bool ALIGN_EPI = true>
; __device__ __forceinline__ void gemm_phase(LAS unsigned char* lds, const Gemm g, const Sched& S, const Epi& E, int wave) {
;     ...
;             PG8_LDA(At, 1, 1); PG8_STAGE(PG8_SB(1, 0), b3, voffB); PG8_STAGE(PG8_SB(1, 1), b3 + hstepB, voffB); PG8_STAGE(PG8_SA(1, 0), a3, voffA);
;             PG8_WAIT_V(8); PG8_WAIT_L(0); PG8_BAR; PG8_MMA(1, 0, At, B0); PG8_MMA(1, 1, At, B1); PG8_BAR; PG8_SCHED;
;         }
;         if constexpr (ALIGN_EPI) { if (wr == 0) PG8_BAR; }
	s_add_i32 s24, s48, s51
	v_lshl_add_u64 v[212:213], v[212:213], 0, s[52:53]
	s_mov_b32 m0, s24
	ds_read_b128 v[180:183], v163 offset:49152
	ds_read_b128 v[184:187], v163 offset:50176
	ds_read_b128 v[188:191], v163 offset:51200
	ds_read_b128 v[192:195], v163 offset:52224
	ds_read_b128 v[196:199], v163 offset:53248
	ds_read_b128 v[200:203], v163 offset:54272
	ds_read_b128 v[204:207], v163 offset:55296
	ds_read_b128 v[208:211], v163 offset:56320
	global_load_lds_dwordx4 v[212:213], off
	s_add_i32 m0, s24, 0x2000
	s_add_u32 s18, s18, 0x20080
	v_lshl_add_u64 v[212:213], v[214:215], 0, s[52:53]
	s_addc_u32 s19, s19, 0
	s_add_i32 s24, s49, s51
	global_load_lds_dwordx4 v[212:213], off
	v_lshl_add_u64 v[212:213], s[18:19], 0, v[0:1]
	s_mov_b32 m0, s24
	s_nop 0
	global_load_lds_dwordx4 v[212:213], off
	v_lshl_add_u64 v[212:213], s[18:19], 0, v[142:143]
	s_add_i32 m0, s24, 0x2000
	s_nop 0
	global_load_lds_dwordx4 v[212:213], off
	v_lshl_add_u64 v[212:213], v[216:217], 0, s[52:53]
	s_mov_b32 m0, s35
	s_nop 0
	global_load_lds_dwordx4 v[212:213], off
	v_lshl_add_u64 v[212:213], v[218:219], 0, s[52:53]
	s_mov_b32 m0, s36
	s_nop 0
	global_load_lds_dwordx4 v[212:213], off
	s_waitcnt vmcnt(8)
	s_waitcnt lgkmcnt(0)
	s_barrier
	s_setprio 1
	v_mfma_f32_16x16x32_bf16 v[62:65], v[130:133], v[180:183], v[62:65]
	v_mfma_f32_16x16x32_bf16 v[58:61], v[148:151], v[180:183], v[58:61]
	v_mfma_f32_16x16x32_bf16 v[46:49], v[130:133], v[188:191], v[46:49]
	v_mfma_f32_16x16x32_bf16 v[42:45], v[148:151], v[188:191], v[42:45]
	v_mfma_f32_16x16x32_bf16 v[30:33], v[130:133], v[196:199], v[30:33]
	v_mfma_f32_16x16x32_bf16 v[26:29], v[148:151], v[196:199], v[26:29]
	v_mfma_f32_16x16x32_bf16 v[14:17], v[130:133], v[204:207], v[14:17]
	v_mfma_f32_16x16x32_bf16 v[10:13], v[148:151], v[204:207], v[10:13]
	v_mfma_f32_16x16x32_bf16 v[62:65], v[134:137], v[184:187], v[62:65]
	v_mfma_f32_16x16x32_bf16 v[58:61], v[152:155], v[184:187], v[58:61]
	v_mfma_f32_16x16x32_bf16 v[46:49], v[134:137], v[192:195], v[46:49]
	v_mfma_f32_16x16x32_bf16 v[42:45], v[152:155], v[192:195], v[42:45]
	v_mfma_f32_16x16x32_bf16 v[30:33], v[134:137], v[200:203], v[30:33]
	v_mfma_f32_16x16x32_bf16 v[26:29], v[152:155], v[200:203], v[26:29]
	v_mfma_f32_16x16x32_bf16 v[14:17], v[134:137], v[208:211], v[14:17]
	v_mfma_f32_16x16x32_bf16 v[10:13], v[152:155], v[208:211], v[10:13]
	v_mfma_f32_16x16x32_bf16 v[54:57], v[156:159], v[180:183], v[54:57]
	v_mfma_f32_16x16x32_bf16 v[50:53], v[168:171], v[180:183], v[50:53]
	v_mfma_f32_16x16x32_bf16 v[38:41], v[156:159], v[188:191], v[38:41]
	v_mfma_f32_16x16x32_bf16 v[34:37], v[168:171], v[188:191], v[34:37]
	v_mfma_f32_16x16x32_bf16 v[22:25], v[156:159], v[196:199], v[22:25]
	v_mfma_f32_16x16x32_bf16 v[18:21], v[168:171], v[196:199], v[18:21]
	v_mfma_f32_16x16x32_bf16 v[6:9], v[156:159], v[204:207], v[6:9]
	v_mfma_f32_16x16x32_bf16 v[2:5], v[168:171], v[204:207], v[2:5]
	v_mfma_f32_16x16x32_bf16 v[54:57], v[164:167], v[184:187], v[54:57]
	v_mfma_f32_16x16x32_bf16 v[50:53], v[172:175], v[184:187], v[50:53]
	v_mfma_f32_16x16x32_bf16 v[38:41], v[164:167], v[192:195], v[38:41]
	v_mfma_f32_16x16x32_bf16 v[34:37], v[172:175], v[192:195], v[34:37]
	v_mfma_f32_16x16x32_bf16 v[22:25], v[164:167], v[200:203], v[22:25]
	v_mfma_f32_16x16x32_bf16 v[18:21], v[172:175], v[200:203], v[18:21]
	v_mfma_f32_16x16x32_bf16 v[6:9], v[164:167], v[208:211], v[6:9]
	v_mfma_f32_16x16x32_bf16 v[2:5], v[172:175], v[208:211], v[2:5]
	s_setprio 0
	s_barrier
	s_add_i32 s47, s47, 2
	s_add_u32 s16, s16, 0x100
	s_addc_u32 s17, s17, 0
	s_add_u32 s45, s45, 0x100
	s_addc_u32 s46, s46, 0
	s_cmp_gt_u32 s47, 5
	s_cbranch_scc0 .LBB0_2649
	v_readlane_b32 s16, v252, 14
	v_readlane_b32 s17, v252, 15
	s_and_b64 vcc, exec, s[16:17]
	s_cbranch_vccz .LBB0_2652
	s_barrier

; #define PG8_STAGE(bufoff, gbase, voff) do { _Pragma("unroll") for (int _i = 0; _i < 2; ++_i) \
;         __builtin_amdgcn_global_load_lds((const unsigned*)((const char*)(gbase) + (voff)[_i]), (LAS unsigned*)(lds + (bufoff) + ldsw + _i * 8192), 16, 0, 0); } while (0)
; #define PG8_LDA(dst, b, h) do { _Pragma("unroll") for (int m = 0; m < 4; ++m) _Pragma("unroll") for (int k = 0; k < 2; ++k) dst[m][k] = *(const LAS bf16x8*)(lds + PG8_SA(b, h) + aoff + m * 2048 + k * 1024); } while (0)
; #define PG8_LDB(dst, b, h) do { _Pragma("unroll") for (int n = 0; n < 2; ++n) _Pragma("unroll") for (int k = 0; k < 2; ++k) dst[n][k] = *(const LAS bf16x8*)(lds + PG8_SB(b, h) + boff + n * 2048 + k * 1024); } while (0)
; #define PG8_MMA(ai, bj, At, Bt) do { __builtin_amdgcn_s_setprio(1); _Pragma("unroll") for (int m = 0; m < 4; ++m) _Pragma("unroll") for (int n = 0; n < 2; ++n) _Pragma("unroll") for (int k = 0; k < 2; ++k) \
;         acc[ai][bj][m][n] = __builtin_amdgcn_mfma_f32_16x16x32_bf16(Bt[n][k], At[m][k], acc[ai][bj][m][n], 0, 0, 0); __builtin_amdgcn_s_setprio(0); } while (0)
; #define PG8_WAIT_V(n) asm volatile("s_waitcnt vmcnt(" #n ")" ::: "memory")
; #define PG8_WAIT_L(n) asm volatile("s_waitcnt lgkmcnt(" #n ")" ::: "memory")
; #define PG8_BAR __builtin_amdgcn_s_barrier()
; template <class Epi, class Sched, int LDA, int LDB, bool ALIGN_EPI = true>
; __device__ __forceinline__ void gemm_phase(LAS unsigned char* lds, const Gemm g, const Sched& S, const Epi& E, int wave) {
;     ...
;         for (int t = 0; t < nt; t += 2) {
;             const bool last = (t == nt - 2);
;             const char* a1 = cA + (size_t)(t + 1) * kstep;
;             const char* a2 = last ? nA : cA + (size_t)(t + 2) * kstep; const char* b2 = last ? nB : cB + (size_t)(t + 2) * kstep;
;             const char* a3 = a2 + kstep; const char* b3 = b2 + kstep;
;             PG8_LDB(B0, 0, 0); PG8_LDB(B1, 0, 1); PG8_SCHED; PG8_LDA(At, 0, 0); PG8_STAGE(PG8_SA(1, 1), a1 + hstepA, voffA);
;             PG8_WAIT_V(8); PG8_WAIT_L(0); PG8_BAR; PG8_MMA(0, 0, At, B0); PG8_MMA(0, 1, At, B1); PG8_BAR; PG8_SCHED;
;             PG8_LDA(At, 0, 1); PG8_STAGE(PG8_SB(0, 0), b2, voffB); PG8_STAGE(PG8_SB(0, 1), b2 + hstepB, voffB); PG8_STAGE(PG8_SA(0, 0), a2, voffA);
;             PG8_WAIT_V(8); PG8_WAIT_L(0); PG8_BAR; PG8_MMA(1, 0, At, B0); PG8_MMA(1, 1, At, B1); PG8_BAR; PG8_SCHED;
.LBB0_4715:
	s_add_i32 s49, s24, 2
	s_add_u32 s25, s18, 0xfff80080
	s_addc_u32 s28, s19, -1
	s_add_i32 s50, 0, 0x10000
	s_cmp_eq_u32 s17, s24
	s_cselect_b32 s29, s1, s28
	s_cselect_b32 s28, s7, s25
	v_add_u32_e32 v0, s50, v153
	s_cselect_b32 s25, s3, s45
	s_cselect_b32 s24, s15, s44
	s_add_i32 s52, 0, 0x14000
	ds_read_b128 v[144:147], v0
	ds_read_b128 v[148:151], v0 offset:1024
	ds_read_b128 v[156:159], v0 offset:2048
	ds_read_b128 v[160:163], v0 offset:3072
	v_add_u32_e32 v0, s52, v153
	ds_read_b128 v[164:167], v0
	ds_read_b128 v[168:171], v0 offset:1024
	ds_read_b128 v[172:175], v0 offset:2048
	ds_read_b128 v[180:183], v0 offset:3072
	v_lshl_add_u64 v[216:217], s[18:19], 0, v[140:141]
	s_add_i32 m0, s27, 0xc000
	ds_read_b128 v[184:187], v155
	ds_read_b128 v[188:191], v155 offset:1024
	ds_read_b128 v[192:195], v155 offset:2048
	ds_read_b128 v[196:199], v155 offset:3072
	ds_read_b128 v[200:203], v155 offset:4096
	ds_read_b128 v[204:207], v155 offset:5120
	ds_read_b128 v[208:211], v155 offset:6144
	ds_read_b128 v[212:215], v155 offset:7168
	global_load_lds_dwordx4 v[216:217], off
	v_lshl_add_u64 v[216:217], s[18:19], 0, v[142:143]
	s_add_i32 m0, s27, 0xe000
	s_nop 0
	global_load_lds_dwordx4 v[216:217], off
	s_waitcnt vmcnt(8)
	s_waitcnt lgkmcnt(0)
	s_barrier
	s_setprio 1
	v_mfma_f32_16x16x32_bf16 v[126:129], v[144:147], v[184:187], v[126:129]
	v_mfma_f32_16x16x32_bf16 v[122:125], v[156:159], v[184:187], v[122:125]
	v_mfma_f32_16x16x32_bf16 v[110:113], v[144:147], v[192:195], v[110:113]
	v_mfma_f32_16x16x32_bf16 v[106:109], v[156:159], v[192:195], v[106:109]
	v_mfma_f32_16x16x32_bf16 v[94:97], v[144:147], v[200:203], v[94:97]
	v_mfma_f32_16x16x32_bf16 v[90:93], v[156:159], v[200:203], v[90:93]
	v_mfma_f32_16x16x32_bf16 v[78:81], v[144:147], v[208:211], v[78:81]
	v_mfma_f32_16x16x32_bf16 v[74:77], v[156:159], v[208:211], v[74:77]
	v_mfma_f32_16x16x32_bf16 v[126:129], v[148:151], v[188:191], v[126:129]
	v_mfma_f32_16x16x32_bf16 v[122:125], v[160:163], v[188:191], v[122:125]
	v_mfma_f32_16x16x32_bf16 v[110:113], v[148:151], v[196:199], v[110:113]
	v_mfma_f32_16x16x32_bf16 v[106:109], v[160:163], v[196:199], v[106:109]
	v_mfma_f32_16x16x32_bf16 v[94:97], v[148:151], v[204:207], v[94:97]
	v_mfma_f32_16x16x32_bf16 v[90:93], v[160:163], v[204:207], v[90:93]
	v_mfma_f32_16x16x32_bf16 v[78:81], v[148:151], v[212:215], v[78:81]
	v_mfma_f32_16x16x32_bf16 v[74:77], v[160:163], v[212:215], v[74:77]
	v_mfma_f32_16x16x32_bf16 v[118:121], v[164:167], v[184:187], v[118:121]
	v_mfma_f32_16x16x32_bf16 v[114:117], v[172:175], v[184:187], v[114:117]
	v_mfma_f32_16x16x32_bf16 v[102:105], v[164:167], v[192:195], v[102:105]
	v_mfma_f32_16x16x32_bf16 v[98:101], v[172:175], v[192:195], v[98:101]
	v_mfma_f32_16x16x32_bf16 v[86:89], v[164:167], v[200:203], v[86:89]
	v_mfma_f32_16x16x32_bf16 v[82:85], v[172:175], v[200:203], v[82:85]
	v_mfma_f32_16x16x32_bf16 v[70:73], v[164:167], v[208:211], v[70:73]
	v_mfma_f32_16x16x32_bf16 v[66:69], v[172:175], v[208:211], v[66:69]
	v_mfma_f32_16x16x32_bf16 v[118:121], v[168:171], v[188:191], v[118:121]
	v_mfma_f32_16x16x32_bf16 v[114:117], v[180:183], v[188:191], v[114:117]
	v_mfma_f32_16x16x32_bf16 v[102:105], v[168:171], v[196:199], v[102:105]
	v_mfma_f32_16x16x32_bf16 v[98:101], v[180:183], v[196:199], v[98:101]
	v_mfma_f32_16x16x32_bf16 v[86:89], v[168:171], v[204:207], v[86:89]
	v_mfma_f32_16x16x32_bf16 v[82:85], v[180:183], v[204:207], v[82:85]
	v_mfma_f32_16x16x32_bf16 v[70:73], v[168:171], v[212:215], v[70:73]
	v_mfma_f32_16x16x32_bf16 v[66:69], v[180:183], v[212:215], v[66:69]
	s_setprio 0
	s_barrier
	s_add_i32 s50, s50, s53
	v_lshl_add_u64 v[216:217], s[24:25], 0, v[132:133]
	s_mov_b32 m0, s50
	ds_read_b128 v[184:187], v155 offset:16384
	ds_read_b128 v[188:191], v155 offset:17408
	ds_read_b128 v[192:195], v155 offset:18432
	ds_read_b128 v[196:199], v155 offset:19456
	ds_read_b128 v[200:203], v155 offset:20480
	ds_read_b128 v[204:207], v155 offset:21504
	ds_read_b128 v[208:211], v155 offset:22528
	ds_read_b128 v[212:215], v155 offset:23552
	global_load_lds_dwordx4 v[216:217], off
	s_add_i32 m0, s50, 0x2000
	s_add_u32 s50, s24, 0x80000
	v_lshl_add_u64 v[218:219], s[24:25], 0, v[136:137]
	s_addc_u32 s51, s25, 0
	s_add_i32 s52, s52, s53
	global_load_lds_dwordx4 v[218:219], off
	v_lshl_add_u64 v[220:221], s[50:51], 0, v[132:133]
	s_mov_b32 m0, s52
	v_lshl_add_u64 v[222:223], s[28:29], 0, v[134:135]
	global_load_lds_dwordx4 v[220:221], off
	v_lshl_add_u64 v[220:221], s[50:51], 0, v[136:137]
	s_add_i32 m0, s52, 0x2000
	s_nop 0
	global_load_lds_dwordx4 v[220:221], off
	v_lshl_add_u64 v[220:221], s[28:29], 0, v[130:131]
	s_mov_b32 m0, s27
	s_nop 0
	global_load_lds_dwordx4 v[220:221], off
	s_mov_b32 m0, s34
	s_nop 0
	global_load_lds_dwordx4 v[222:223], off
	s_waitcnt vmcnt(8)
	s_waitcnt lgkmcnt(0)
	s_barrier
; #define PG8_STAGE(bufoff, gbase, voff) do { _Pragma("unroll") for (int _i = 0; _i < 2; ++_i) \
;         __builtin_amdgcn_global_load_lds((const unsigned*)((const char*)(gbase) + (voff)[_i]), (LAS unsigned*)(lds + (bufoff) + ldsw + _i * 8192), 16, 0, 0); } while (0)
; #define PG8_LDA(dst, b, h) do { _Pragma("unroll") for (int m = 0; m < 4; ++m) _Pragma("unroll") for (int k = 0; k < 2; ++k) dst[m][k] = *(const LAS bf16x8*)(lds + PG8_SA(b, h) + aoff + m * 2048 + k * 1024); } while (0)
; #define PG8_LDB(dst, b, h) do { _Pragma("unroll") for (int n = 0; n < 2; ++n) _Pragma("unroll") for (int k = 0; k < 2; ++k) dst[n][k] = *(const LAS bf16x8*)(lds + PG8_SB(b, h) + boff + n * 2048 + k * 1024); } while (0)
; #define PG8_MMA(ai, bj, At, Bt) do { __builtin_amdgcn_s_setprio(1); _Pragma("unroll") for (int m = 0; m < 4; ++m) _Pragma("unroll") for (int n = 0; n < 2; ++n) _Pragma("unroll") for (int k = 0; k < 2; ++k) \
;         acc[ai][bj][m][n] = __builtin_amdgcn_mfma_f32_16x16x32_bf16(Bt[n][k], At[m][k], acc[ai][bj][m][n], 0, 0, 0); __builtin_amdgcn_s_setprio(0); } while (0)
; #define PG8_WAIT_V(n) asm volatile("s_waitcnt vmcnt(" #n ")" ::: "memory")
; #define PG8_WAIT_L(n) asm volatile("s_waitcnt lgkmcnt(" #n ")" ::: "memory")
; #define PG8_BAR __builtin_amdgcn_s_barrier()
; #define PG8_SCHED __builtin_amdgcn_sched_barrier(0)
; template <class Epi, class Sched, int LDA, int LDB, bool ALIGN_EPI = true>
; __device__ __forceinline__ void gemm_phase(LAS unsigned char* lds, const Gemm g, const Sched& S, const Epi& E, int wave) {
;     ...
;             PG8_WAIT_V(8); PG8_WAIT_L(0); PG8_BAR; PG8_MMA(1, 0, At, B0); PG8_MMA(1, 1, At, B1); PG8_BAR; PG8_SCHED;
;             PG8_LDB(B0, 1, 0); PG8_LDB(B1, 1, 1); PG8_SCHED; PG8_LDA(At, 1, 0); PG8_STAGE(PG8_SA(0, 1), a2 + hstepA, voffA);
;             PG8_WAIT_V(8); PG8_WAIT_L(0); PG8_BAR; PG8_MMA(0, 0, At, B0); PG8_MMA(0, 1, At, B1); PG8_BAR; PG8_SCHED;
	s_setprio 1
	v_mfma_f32_16x16x32_bf16 v[62:65], v[144:147], v[184:187], v[62:65]
	v_mfma_f32_16x16x32_bf16 v[58:61], v[156:159], v[184:187], v[58:61]
	v_mfma_f32_16x16x32_bf16 v[46:49], v[144:147], v[192:195], v[46:49]
	v_mfma_f32_16x16x32_bf16 v[42:45], v[156:159], v[192:195], v[42:45]
	v_mfma_f32_16x16x32_bf16 v[30:33], v[144:147], v[200:203], v[30:33]
	v_mfma_f32_16x16x32_bf16 v[26:29], v[156:159], v[200:203], v[26:29]
	v_mfma_f32_16x16x32_bf16 v[14:17], v[144:147], v[208:211], v[14:17]
	v_mfma_f32_16x16x32_bf16 v[10:13], v[156:159], v[208:211], v[10:13]
	v_mfma_f32_16x16x32_bf16 v[62:65], v[148:151], v[188:191], v[62:65]
	v_mfma_f32_16x16x32_bf16 v[58:61], v[160:163], v[188:191], v[58:61]
	v_mfma_f32_16x16x32_bf16 v[46:49], v[148:151], v[196:199], v[46:49]
	v_mfma_f32_16x16x32_bf16 v[42:45], v[160:163], v[196:199], v[42:45]
	v_mfma_f32_16x16x32_bf16 v[30:33], v[148:151], v[204:207], v[30:33]
	v_mfma_f32_16x16x32_bf16 v[26:29], v[160:163], v[204:207], v[26:29]
	v_mfma_f32_16x16x32_bf16 v[14:17], v[148:151], v[212:215], v[14:17]
	v_mfma_f32_16x16x32_bf16 v[10:13], v[160:163], v[212:215], v[10:13]
	v_mfma_f32_16x16x32_bf16 v[54:57], v[164:167], v[184:187], v[54:57]
	v_mfma_f32_16x16x32_bf16 v[50:53], v[172:175], v[184:187], v[50:53]
	v_mfma_f32_16x16x32_bf16 v[38:41], v[164:167], v[192:195], v[38:41]
	v_mfma_f32_16x16x32_bf16 v[34:37], v[172:175], v[192:195], v[34:37]
	v_mfma_f32_16x16x32_bf16 v[22:25], v[164:167], v[200:203], v[22:25]
	v_mfma_f32_16x16x32_bf16 v[18:21], v[172:175], v[200:203], v[18:21]
	v_mfma_f32_16x16x32_bf16 v[6:9], v[164:167], v[208:211], v[6:9]
	v_mfma_f32_16x16x32_bf16 v[2:5], v[172:175], v[208:211], v[2:5]
	v_mfma_f32_16x16x32_bf16 v[54:57], v[168:171], v[188:191], v[54:57]
	v_mfma_f32_16x16x32_bf16 v[50:53], v[180:183], v[188:191], v[50:53]
	v_mfma_f32_16x16x32_bf16 v[38:41], v[168:171], v[196:199], v[38:41]
	v_mfma_f32_16x16x32_bf16 v[34:37], v[180:183], v[196:199], v[34:37]
	v_mfma_f32_16x16x32_bf16 v[22:25], v[168:171], v[204:207], v[22:25]
	v_mfma_f32_16x16x32_bf16 v[18:21], v[180:183], v[204:207], v[18:21]
	v_mfma_f32_16x16x32_bf16 v[6:9], v[168:171], v[212:215], v[6:9]
	v_mfma_f32_16x16x32_bf16 v[2:5], v[180:183], v[212:215], v[2:5]
	s_setprio 0
	s_barrier
	s_add_i32 s50, 0, 0x18000
	v_add_u32_e32 v0, s50, v153
	s_add_i32 s51, 0, 0x1c000
	ds_read_b128 v[144:147], v0
	ds_read_b128 v[148:151], v0 offset:1024
	ds_read_b128 v[156:159], v0 offset:2048
	ds_read_b128 v[160:163], v0 offset:3072
	v_add_u32_e32 v0, s51, v153
	ds_read_b128 v[164:167], v0
	ds_read_b128 v[168:171], v0 offset:1024
	ds_read_b128 v[172:175], v0 offset:2048
	ds_read_b128 v[180:183], v0 offset:3072
	s_add_u32 s28, s28, 0x80000
	s_addc_u32 s29, s29, 0
	s_mov_b32 m0, s35
	v_lshl_add_u64 v[224:225], s[28:29], 0, v[130:131]
	ds_read_b128 v[184:187], v155 offset:32768
	ds_read_b128 v[188:191], v155 offset:33792
	ds_read_b128 v[192:195], v155 offset:34816
	ds_read_b128 v[196:199], v155 offset:35840
	ds_read_b128 v[200:203], v155 offset:36864
	ds_read_b128 v[204:207], v155 offset:37888
	ds_read_b128 v[208:211], v155 offset:38912
	ds_read_b128 v[212:215], v155 offset:39936
	global_load_lds_dwordx4 v[224:225], off
	v_lshl_add_u64 v[224:225], s[28:29], 0, v[134:135]
	s_mov_b32 m0, s36
	s_nop 0
	global_load_lds_dwordx4 v[224:225], off
	s_waitcnt vmcnt(8)
	s_waitcnt lgkmcnt(0)
	s_barrier
	s_setprio 1
	v_mfma_f32_16x16x32_bf16 v[126:129], v[144:147], v[184:187], v[126:129]
	v_mfma_f32_16x16x32_bf16 v[122:125], v[156:159], v[184:187], v[122:125]
	v_mfma_f32_16x16x32_bf16 v[110:113], v[144:147], v[192:195], v[110:113]
	v_mfma_f32_16x16x32_bf16 v[106:109], v[156:159], v[192:195], v[106:109]
	v_mfma_f32_16x16x32_bf16 v[94:97], v[144:147], v[200:203], v[94:97]
	v_mfma_f32_16x16x32_bf16 v[90:93], v[156:159], v[200:203], v[90:93]
	v_mfma_f32_16x16x32_bf16 v[78:81], v[144:147], v[208:211], v[78:81]
	v_mfma_f32_16x16x32_bf16 v[74:77], v[156:159], v[208:211], v[74:77]
	v_mfma_f32_16x16x32_bf16 v[126:129], v[148:151], v[188:191], v[126:129]
	v_mfma_f32_16x16x32_bf16 v[122:125], v[160:163], v[188:191], v[122:125]
	v_mfma_f32_16x16x32_bf16 v[110:113], v[148:151], v[196:199], v[110:113]
	v_mfma_f32_16x16x32_bf16 v[106:109], v[160:163], v[196:199], v[106:109]
	v_mfma_f32_16x16x32_bf16 v[94:97], v[148:151], v[204:207], v[94:97]
	v_mfma_f32_16x16x32_bf16 v[90:93], v[160:163], v[204:207], v[90:93]
	v_mfma_f32_16x16x32_bf16 v[78:81], v[148:151], v[212:215], v[78:81]
	v_mfma_f32_16x16x32_bf16 v[74:77], v[160:163], v[212:215], v[74:77]
	v_mfma_f32_16x16x32_bf16 v[118:121], v[164:167], v[184:187], v[118:121]
	v_mfma_f32_16x16x32_bf16 v[114:117], v[172:175], v[184:187], v[114:117]
	v_mfma_f32_16x16x32_bf16 v[102:105], v[164:167], v[192:195], v[102:105]
	v_mfma_f32_16x16x32_bf16 v[98:101], v[172:175], v[192:195], v[98:101]
	v_mfma_f32_16x16x32_bf16 v[86:89], v[164:167], v[200:203], v[86:89]
	v_mfma_f32_16x16x32_bf16 v[82:85], v[172:175], v[200:203], v[82:85]
	v_mfma_f32_16x16x32_bf16 v[70:73], v[164:167], v[208:211], v[70:73]
	v_mfma_f32_16x16x32_bf16 v[66:69], v[172:175], v[208:211], v[66:69]
	v_mfma_f32_16x16x32_bf16 v[118:121], v[168:171], v[188:191], v[118:121]
	v_mfma_f32_16x16x32_bf16 v[114:117], v[180:183], v[188:191], v[114:117]
	v_mfma_f32_16x16x32_bf16 v[102:105], v[168:171], v[196:199], v[102:105]
	v_mfma_f32_16x16x32_bf16 v[98:101], v[180:183], v[196:199], v[98:101]
	v_mfma_f32_16x16x32_bf16 v[86:89], v[168:171], v[204:207], v[86:89]
	v_mfma_f32_16x16x32_bf16 v[82:85], v[180:183], v[204:207], v[82:85]
	v_mfma_f32_16x16x32_bf16 v[70:73], v[168:171], v[212:215], v[70:73]
	v_mfma_f32_16x16x32_bf16 v[66:69], v[180:183], v[212:215], v[66:69]
	s_setprio 0
	s_barrier
; #define PG8_STAGE(bufoff, gbase, voff) do { _Pragma("unroll") for (int _i = 0; _i < 2; ++_i) \
;         __builtin_amdgcn_global_load_lds((const unsigned*)((const char*)(gbase) + (voff)[_i]), (LAS unsigned*)(lds + (bufoff) + ldsw + _i * 8192), 16, 0, 0); } while (0)
; #define PG8_LDA(dst, b, h) do { _Pragma("unroll") for (int m = 0; m < 4; ++m) _Pragma("unroll") for (int k = 0; k < 2; ++k) dst[m][k] = *(const LAS bf16x8*)(lds + PG8_SA(b, h) + aoff + m * 2048 + k * 1024); } while (0)
; #define PG8_MMA(ai, bj, At, Bt) do { __builtin_amdgcn_s_setprio(1); _Pragma("unroll") for (int m = 0; m < 4; ++m) _Pragma("unroll") for (int n = 0; n < 2; ++n) _Pragma("unroll") for (int k = 0; k < 2; ++k) \
;         acc[ai][bj][m][n] = __builtin_amdgcn_mfma_f32_16x16x32_bf16(Bt[n][k], At[m][k], acc[ai][bj][m][n], 0, 0, 0); __builtin_amdgcn_s_setprio(0); } while (0)
; #define PG8_WAIT_V(n) asm volatile("s_waitcnt vmcnt(" #n ")" ::: "memory")
; #define PG8_WAIT_L(n) asm volatile("s_waitcnt lgkmcnt(" #n ")" ::: "memory")
; #define PG8_BAR __builtin_amdgcn_s_barrier()
; #define PG8_SCHED __builtin_amdgcn_sched_barrier(0)
; template <class Epi, class Sched, int LDA, int LDB, bool ALIGN_EPI = true>
; __device__ __forceinline__ void gemm_phase(LAS unsigned char* lds, const Gemm g, const Sched& S, const Epi& E, int wave) {
;     ...
;             PG8_LDA(At, 1, 1); PG8_STAGE(PG8_SB(1, 0), b3, voffB); PG8_STAGE(PG8_SB(1, 1), b3 + hstepB, voffB); PG8_STAGE(PG8_SA(1, 0), a3, voffA);
;             PG8_WAIT_V(8); PG8_WAIT_L(0); PG8_BAR; PG8_MMA(1, 0, At, B0); PG8_MMA(1, 1, At, B1); PG8_BAR; PG8_SCHED;
;         }
;         if constexpr (ALIGN_EPI) { if (wr == 0) PG8_BAR; }
	s_add_i32 s28, s50, s53
	v_lshl_add_u64 v[216:217], v[216:217], 0, s[54:55]
	s_mov_b32 m0, s28
	ds_read_b128 v[184:187], v155 offset:49152
	ds_read_b128 v[188:191], v155 offset:50176
	ds_read_b128 v[192:195], v155 offset:51200
	ds_read_b128 v[196:199], v155 offset:52224
	ds_read_b128 v[200:203], v155 offset:53248
	ds_read_b128 v[204:207], v155 offset:54272
	ds_read_b128 v[208:211], v155 offset:55296
	ds_read_b128 v[212:215], v155 offset:56320
	global_load_lds_dwordx4 v[216:217], off
	s_add_i32 m0, s28, 0x2000
	s_add_u32 s24, s24, 0x80080
	v_lshl_add_u64 v[216:217], v[218:219], 0, s[54:55]
	s_addc_u32 s25, s25, 0
	s_add_i32 s28, s51, s53
	global_load_lds_dwordx4 v[216:217], off
	v_lshl_add_u64 v[216:217], s[24:25], 0, v[132:133]
	s_mov_b32 m0, s28
	s_nop 0
	global_load_lds_dwordx4 v[216:217], off
	v_lshl_add_u64 v[216:217], s[24:25], 0, v[136:137]
	s_add_i32 m0, s28, 0x2000
	s_nop 0
	global_load_lds_dwordx4 v[216:217], off
	v_lshl_add_u64 v[216:217], v[220:221], 0, s[54:55]
	s_mov_b32 m0, s37
	s_nop 0
	global_load_lds_dwordx4 v[216:217], off
	v_lshl_add_u64 v[216:217], v[222:223], 0, s[54:55]
	s_mov_b32 m0, s38
	s_nop 0
	global_load_lds_dwordx4 v[216:217], off
	s_waitcnt vmcnt(8)
	s_waitcnt lgkmcnt(0)
	s_barrier
	s_setprio 1
	v_mfma_f32_16x16x32_bf16 v[62:65], v[144:147], v[184:187], v[62:65]
	v_mfma_f32_16x16x32_bf16 v[58:61], v[156:159], v[184:187], v[58:61]
	v_mfma_f32_16x16x32_bf16 v[46:49], v[144:147], v[192:195], v[46:49]
	v_mfma_f32_16x16x32_bf16 v[42:45], v[156:159], v[192:195], v[42:45]
	v_mfma_f32_16x16x32_bf16 v[30:33], v[144:147], v[200:203], v[30:33]
	v_mfma_f32_16x16x32_bf16 v[26:29], v[156:159], v[200:203], v[26:29]
	v_mfma_f32_16x16x32_bf16 v[14:17], v[144:147], v[208:211], v[14:17]
	v_mfma_f32_16x16x32_bf16 v[10:13], v[156:159], v[208:211], v[10:13]
	v_mfma_f32_16x16x32_bf16 v[62:65], v[148:151], v[188:191], v[62:65]
	v_mfma_f32_16x16x32_bf16 v[58:61], v[160:163], v[188:191], v[58:61]
	v_mfma_f32_16x16x32_bf16 v[46:49], v[148:151], v[196:199], v[46:49]
	v_mfma_f32_16x16x32_bf16 v[42:45], v[160:163], v[196:199], v[42:45]
	v_mfma_f32_16x16x32_bf16 v[30:33], v[148:151], v[204:207], v[30:33]
	v_mfma_f32_16x16x32_bf16 v[26:29], v[160:163], v[204:207], v[26:29]
	v_mfma_f32_16x16x32_bf16 v[14:17], v[148:151], v[212:215], v[14:17]
	v_mfma_f32_16x16x32_bf16 v[10:13], v[160:163], v[212:215], v[10:13]
	v_mfma_f32_16x16x32_bf16 v[54:57], v[164:167], v[184:187], v[54:57]
	v_mfma_f32_16x16x32_bf16 v[50:53], v[172:175], v[184:187], v[50:53]
	v_mfma_f32_16x16x32_bf16 v[38:41], v[164:167], v[192:195], v[38:41]
	v_mfma_f32_16x16x32_bf16 v[34:37], v[172:175], v[192:195], v[34:37]
	v_mfma_f32_16x16x32_bf16 v[22:25], v[164:167], v[200:203], v[22:25]
	v_mfma_f32_16x16x32_bf16 v[18:21], v[172:175], v[200:203], v[18:21]
	v_mfma_f32_16x16x32_bf16 v[6:9], v[164:167], v[208:211], v[6:9]
	v_mfma_f32_16x16x32_bf16 v[2:5], v[172:175], v[208:211], v[2:5]
	v_mfma_f32_16x16x32_bf16 v[54:57], v[168:171], v[188:191], v[54:57]
	v_mfma_f32_16x16x32_bf16 v[50:53], v[180:183], v[188:191], v[50:53]
	v_mfma_f32_16x16x32_bf16 v[38:41], v[168:171], v[196:199], v[38:41]
	v_mfma_f32_16x16x32_bf16 v[34:37], v[180:183], v[196:199], v[34:37]
	v_mfma_f32_16x16x32_bf16 v[22:25], v[168:171], v[204:207], v[22:25]
	v_mfma_f32_16x16x32_bf16 v[18:21], v[180:183], v[204:207], v[18:21]
	v_mfma_f32_16x16x32_bf16 v[6:9], v[168:171], v[212:215], v[6:9]
	v_mfma_f32_16x16x32_bf16 v[2:5], v[180:183], v[212:215], v[2:5]
	s_setprio 0
	s_barrier
	s_add_u32 s18, s18, 0x100
	s_addc_u32 s19, s19, 0
	s_add_u32 s44, s44, 0x100
	s_addc_u32 s45, s45, 0
	s_cmp_ge_i32 s49, s43
	s_mov_b32 s24, s49
	s_cbranch_scc0 .LBB0_4715
	v_readlane_b32 s18, v252, 14
	v_readlane_b32 s19, v252, 15
	s_and_b64 vcc, exec, s[18:19]
	s_cbranch_vccz .LBB0_4718
	s_barrier

; #define PG8_STAGE(bufoff, gbase, voff) do { _Pragma("unroll") for (int _i = 0; _i < 2; ++_i) \
;         __builtin_amdgcn_global_load_lds((const unsigned*)((const char*)(gbase) + (voff)[_i]), (LAS unsigned*)(lds + (bufoff) + ldsw + _i * 8192), 16, 0, 0); } while (0)
; #define PG8_LDA(dst, b, h) do { _Pragma("unroll") for (int m = 0; m < 4; ++m) _Pragma("unroll") for (int k = 0; k < 2; ++k) dst[m][k] = *(const LAS bf16x8*)(lds + PG8_SA(b, h) + aoff + m * 2048 + k * 1024); } while (0)
; #define PG8_LDB(dst, b, h) do { _Pragma("unroll") for (int n = 0; n < 2; ++n) _Pragma("unroll") for (int k = 0; k < 2; ++k) dst[n][k] = *(const LAS bf16x8*)(lds + PG8_SB(b, h) + boff + n * 2048 + k * 1024); } while (0)
; #define PG8_MMA(ai, bj, At, Bt) do { __builtin_amdgcn_s_setprio(1); _Pragma("unroll") for (int m = 0; m < 4; ++m) _Pragma("unroll") for (int n = 0; n < 2; ++n) _Pragma("unroll") for (int k = 0; k < 2; ++k) \
;         acc[ai][bj][m][n] = __builtin_amdgcn_mfma_f32_16x16x32_bf16(Bt[n][k], At[m][k], acc[ai][bj][m][n], 0, 0, 0); __builtin_amdgcn_s_setprio(0); } while (0)
; #define PG8_WAIT_V(n) asm volatile("s_waitcnt vmcnt(" #n ")" ::: "memory")
; #define PG8_WAIT_L(n) asm volatile("s_waitcnt lgkmcnt(" #n ")" ::: "memory")
; #define PG8_BAR __builtin_amdgcn_s_barrier()
; template <class Epi, class Sched, int LDA, int LDB, bool ALIGN_EPI = true>
; __device__ __forceinline__ void gemm_phase(LAS unsigned char* lds, const Gemm g, const Sched& S, const Epi& E, int wave) {
;     ...
;         for (int t = 0; t < nt; t += 2) {
;             const bool last = (t == nt - 2);
;             const char* a1 = cA + (size_t)(t + 1) * kstep;
;             const char* a2 = last ? nA : cA + (size_t)(t + 2) * kstep; const char* b2 = last ? nB : cB + (size_t)(t + 2) * kstep;
;             const char* a3 = a2 + kstep; const char* b3 = b2 + kstep;
;             PG8_LDB(B0, 0, 0); PG8_LDB(B1, 0, 1); PG8_SCHED; PG8_LDA(At, 0, 0); PG8_STAGE(PG8_SA(1, 1), a1 + hstepA, voffA);
;             PG8_WAIT_V(8); PG8_WAIT_L(0); PG8_BAR; PG8_MMA(0, 0, At, B0); PG8_MMA(0, 1, At, B1); PG8_BAR; PG8_SCHED;
;             PG8_LDA(At, 0, 1); PG8_STAGE(PG8_SB(0, 0), b2, voffB); PG8_STAGE(PG8_SB(0, 1), b2 + hstepB, voffB); PG8_STAGE(PG8_SA(0, 0), a2, voffA);
;             PG8_WAIT_V(8); PG8_WAIT_L(0); PG8_BAR; PG8_MMA(1, 0, At, B0); PG8_MMA(1, 1, At, B1); PG8_BAR; PG8_SCHED;
.LBB0_4901:
	s_add_i32 s65, s36, 2
	s_add_u32 s37, s34, 0xfff80080
	s_addc_u32 s38, s35, -1
	s_add_i32 s66, 0, 0x10000
	s_cmp_eq_u32 s29, s36
	s_cselect_b32 s39, s9, s38
	s_cselect_b32 s38, s13, s37
	s_cselect_b32 s37, s11, s64
	s_cselect_b32 s36, s25, s59
	s_add_i32 s72, 0, 0x14000
	v_add_u32_e32 v70, s66, v213
	v_add_u32_e32 v168, s72, v213
	ds_read_b128 v[50:53], v70
	ds_read_b128 v[54:57], v70 offset:1024
	ds_read_b128 v[66:69], v70 offset:2048
	ds_read_b128 v[70:73], v70 offset:3072
	ds_read_b128 v[156:159], v168
	ds_read_b128 v[160:163], v168 offset:1024
	ds_read_b128 v[164:167], v168 offset:2048
	ds_read_b128 v[168:171], v168 offset:3072
	v_lshl_add_u64 v[208:209], s[34:35], 0, v[152:153]
	s_add_i32 m0, s27, 0xc000
	ds_read_b128 v[172:175], v215
	ds_read_b128 v[180:183], v215 offset:1024
	ds_read_b128 v[184:187], v215 offset:2048
	ds_read_b128 v[188:191], v215 offset:3072
	ds_read_b128 v[192:195], v215 offset:4096
	ds_read_b128 v[196:199], v215 offset:5120
	ds_read_b128 v[200:203], v215 offset:6144
	ds_read_b128 v[204:207], v215 offset:7168
	global_load_lds_dwordx4 v[208:209], off
	v_lshl_add_u64 v[208:209], s[34:35], 0, v[154:155]
	s_add_i32 m0, s27, 0xe000
	s_nop 0
	global_load_lds_dwordx4 v[208:209], off
	s_waitcnt vmcnt(8)
	s_waitcnt lgkmcnt(0)
	s_barrier
	s_setprio 1
	v_mfma_f32_16x16x32_bf16 v[142:145], v[50:53], v[172:175], v[142:145]
	v_mfma_f32_16x16x32_bf16 v[138:141], v[66:69], v[172:175], v[138:141]
	v_mfma_f32_16x16x32_bf16 v[126:129], v[50:53], v[184:187], v[126:129]
	v_mfma_f32_16x16x32_bf16 v[122:125], v[66:69], v[184:187], v[122:125]
	v_mfma_f32_16x16x32_bf16 v[110:113], v[50:53], v[192:195], v[110:113]
	v_mfma_f32_16x16x32_bf16 v[106:109], v[66:69], v[192:195], v[106:109]
	v_mfma_f32_16x16x32_bf16 v[94:97], v[50:53], v[200:203], v[94:97]
	v_mfma_f32_16x16x32_bf16 v[90:93], v[66:69], v[200:203], v[90:93]
	v_mfma_f32_16x16x32_bf16 v[142:145], v[54:57], v[180:183], v[142:145]
	v_mfma_f32_16x16x32_bf16 v[138:141], v[70:73], v[180:183], v[138:141]
	v_mfma_f32_16x16x32_bf16 v[126:129], v[54:57], v[188:191], v[126:129]
	v_mfma_f32_16x16x32_bf16 v[122:125], v[70:73], v[188:191], v[122:125]
	v_mfma_f32_16x16x32_bf16 v[110:113], v[54:57], v[196:199], v[110:113]
	v_mfma_f32_16x16x32_bf16 v[106:109], v[70:73], v[196:199], v[106:109]
	v_mfma_f32_16x16x32_bf16 v[94:97], v[54:57], v[204:207], v[94:97]
	v_mfma_f32_16x16x32_bf16 v[90:93], v[70:73], v[204:207], v[90:93]
	v_mfma_f32_16x16x32_bf16 v[134:137], v[156:159], v[172:175], v[134:137]
	v_mfma_f32_16x16x32_bf16 v[130:133], v[164:167], v[172:175], v[130:133]
	v_mfma_f32_16x16x32_bf16 v[118:121], v[156:159], v[184:187], v[118:121]
	v_mfma_f32_16x16x32_bf16 v[114:117], v[164:167], v[184:187], v[114:117]
	v_mfma_f32_16x16x32_bf16 v[102:105], v[156:159], v[192:195], v[102:105]
	v_mfma_f32_16x16x32_bf16 v[98:101], v[164:167], v[192:195], v[98:101]
	v_mfma_f32_16x16x32_bf16 v[86:89], v[156:159], v[200:203], v[86:89]
	v_mfma_f32_16x16x32_bf16 v[82:85], v[164:167], v[200:203], v[82:85]
	v_mfma_f32_16x16x32_bf16 v[134:137], v[160:163], v[180:183], v[134:137]
	v_mfma_f32_16x16x32_bf16 v[130:133], v[168:171], v[180:183], v[130:133]
	v_mfma_f32_16x16x32_bf16 v[118:121], v[160:163], v[188:191], v[118:121]
	v_mfma_f32_16x16x32_bf16 v[114:117], v[168:171], v[188:191], v[114:117]
	v_mfma_f32_16x16x32_bf16 v[102:105], v[160:163], v[196:199], v[102:105]
	v_mfma_f32_16x16x32_bf16 v[98:101], v[168:171], v[196:199], v[98:101]
	v_mfma_f32_16x16x32_bf16 v[86:89], v[160:163], v[204:207], v[86:89]
	v_mfma_f32_16x16x32_bf16 v[82:85], v[168:171], v[204:207], v[82:85]
	s_setprio 0
	s_barrier
	s_add_i32 s66, s66, s60
	v_lshl_add_u64 v[208:209], s[36:37], 0, v[0:1]
	s_mov_b32 m0, s66
	ds_read_b128 v[172:175], v215 offset:16384
	ds_read_b128 v[180:183], v215 offset:17408
	ds_read_b128 v[184:187], v215 offset:18432
	ds_read_b128 v[188:191], v215 offset:19456
	ds_read_b128 v[192:195], v215 offset:20480
	ds_read_b128 v[196:199], v215 offset:21504
	ds_read_b128 v[200:203], v215 offset:22528
	ds_read_b128 v[204:207], v215 offset:23552
	global_load_lds_dwordx4 v[208:209], off
	s_add_i32 m0, s66, 0x2000
	s_add_u32 s66, s36, 0x80000
	v_lshl_add_u64 v[210:211], s[36:37], 0, v[150:151]
	s_addc_u32 s67, s37, 0
	s_add_i32 s72, s72, s60
	global_load_lds_dwordx4 v[210:211], off
	v_lshl_add_u64 v[216:217], s[66:67], 0, v[0:1]
	s_mov_b32 m0, s72
	v_lshl_add_u64 v[218:219], s[38:39], 0, v[148:149]
	global_load_lds_dwordx4 v[216:217], off
	v_lshl_add_u64 v[216:217], s[66:67], 0, v[150:151]
	s_add_i32 m0, s72, 0x2000
	s_nop 0
	global_load_lds_dwordx4 v[216:217], off
	v_lshl_add_u64 v[216:217], s[38:39], 0, v[146:147]
	s_mov_b32 m0, s27
	s_nop 0
	global_load_lds_dwordx4 v[216:217], off
	s_mov_b32 m0, s44
	s_nop 0
	global_load_lds_dwordx4 v[218:219], off
	s_waitcnt vmcnt(8)
	s_waitcnt lgkmcnt(0)
	s_barrier
; #define PG8_STAGE(bufoff, gbase, voff) do { _Pragma("unroll") for (int _i = 0; _i < 2; ++_i) \
;         __builtin_amdgcn_global_load_lds((const unsigned*)((const char*)(gbase) + (voff)[_i]), (LAS unsigned*)(lds + (bufoff) + ldsw + _i * 8192), 16, 0, 0); } while (0)
; #define PG8_LDA(dst, b, h) do { _Pragma("unroll") for (int m = 0; m < 4; ++m) _Pragma("unroll") for (int k = 0; k < 2; ++k) dst[m][k] = *(const LAS bf16x8*)(lds + PG8_SA(b, h) + aoff + m * 2048 + k * 1024); } while (0)
; #define PG8_LDB(dst, b, h) do { _Pragma("unroll") for (int n = 0; n < 2; ++n) _Pragma("unroll") for (int k = 0; k < 2; ++k) dst[n][k] = *(const LAS bf16x8*)(lds + PG8_SB(b, h) + boff + n * 2048 + k * 1024); } while (0)
; #define PG8_MMA(ai, bj, At, Bt) do { __builtin_amdgcn_s_setprio(1); _Pragma("unroll") for (int m = 0; m < 4; ++m) _Pragma("unroll") for (int n = 0; n < 2; ++n) _Pragma("unroll") for (int k = 0; k < 2; ++k) \
;         acc[ai][bj][m][n] = __builtin_amdgcn_mfma_f32_16x16x32_bf16(Bt[n][k], At[m][k], acc[ai][bj][m][n], 0, 0, 0); __builtin_amdgcn_s_setprio(0); } while (0)
; #define PG8_WAIT_V(n) asm volatile("s_waitcnt vmcnt(" #n ")" ::: "memory")
; #define PG8_WAIT_L(n) asm volatile("s_waitcnt lgkmcnt(" #n ")" ::: "memory")
; #define PG8_BAR __builtin_amdgcn_s_barrier()
; #define PG8_SCHED __builtin_amdgcn_sched_barrier(0)
; template <class Epi, class Sched, int LDA, int LDB, bool ALIGN_EPI = true>
; __device__ __forceinline__ void gemm_phase(LAS unsigned char* lds, const Gemm g, const Sched& S, const Epi& E, int wave) {
;     ...
;             PG8_WAIT_V(8); PG8_WAIT_L(0); PG8_BAR; PG8_MMA(1, 0, At, B0); PG8_MMA(1, 1, At, B1); PG8_BAR; PG8_SCHED;
;             PG8_LDB(B0, 1, 0); PG8_LDB(B1, 1, 1); PG8_SCHED; PG8_LDA(At, 1, 0); PG8_STAGE(PG8_SA(0, 1), a2 + hstepA, voffA);
;             PG8_WAIT_V(8); PG8_WAIT_L(0); PG8_BAR; PG8_MMA(0, 0, At, B0); PG8_MMA(0, 1, At, B1); PG8_BAR; PG8_SCHED;
	s_setprio 1
	v_mfma_f32_16x16x32_bf16 v[78:81], v[50:53], v[172:175], v[78:81]
	v_mfma_f32_16x16x32_bf16 v[74:77], v[66:69], v[172:175], v[74:77]
	v_mfma_f32_16x16x32_bf16 v[46:49], v[50:53], v[184:187], v[46:49]
	v_mfma_f32_16x16x32_bf16 v[42:45], v[66:69], v[184:187], v[42:45]
	v_mfma_f32_16x16x32_bf16 v[30:33], v[50:53], v[192:195], v[30:33]
	v_mfma_f32_16x16x32_bf16 v[26:29], v[66:69], v[192:195], v[26:29]
	v_mfma_f32_16x16x32_bf16 v[14:17], v[50:53], v[200:203], v[14:17]
	v_mfma_f32_16x16x32_bf16 v[10:13], v[66:69], v[200:203], v[10:13]
	v_mfma_f32_16x16x32_bf16 v[78:81], v[54:57], v[180:183], v[78:81]
	v_mfma_f32_16x16x32_bf16 v[74:77], v[70:73], v[180:183], v[74:77]
	v_mfma_f32_16x16x32_bf16 v[46:49], v[54:57], v[188:191], v[46:49]
	v_mfma_f32_16x16x32_bf16 v[42:45], v[70:73], v[188:191], v[42:45]
	v_mfma_f32_16x16x32_bf16 v[30:33], v[54:57], v[196:199], v[30:33]
	v_mfma_f32_16x16x32_bf16 v[26:29], v[70:73], v[196:199], v[26:29]
	v_mfma_f32_16x16x32_bf16 v[14:17], v[54:57], v[204:207], v[14:17]
	v_mfma_f32_16x16x32_bf16 v[10:13], v[70:73], v[204:207], v[10:13]
	v_mfma_f32_16x16x32_bf16 v[38:41], v[156:159], v[184:187], v[38:41]
	v_mfma_f32_16x16x32_bf16 v[34:37], v[164:167], v[184:187], v[34:37]
	v_mfma_f32_16x16x32_bf16 v[22:25], v[156:159], v[192:195], v[22:25]
	v_mfma_f32_16x16x32_bf16 v[18:21], v[164:167], v[192:195], v[18:21]
	v_mfma_f32_16x16x32_bf16 v[6:9], v[156:159], v[200:203], v[6:9]
	v_mfma_f32_16x16x32_bf16 v[2:5], v[164:167], v[200:203], v[2:5]
	v_mfma_f32_16x16x32_bf16 v[50:53], v[156:159], v[172:175], v[62:65]
	v_mfma_f32_16x16x32_bf16 v[54:57], v[164:167], v[172:175], v[58:61]
	v_mfma_f32_16x16x32_bf16 v[38:41], v[160:163], v[188:191], v[38:41]
	v_mfma_f32_16x16x32_bf16 v[34:37], v[168:171], v[188:191], v[34:37]
	v_mfma_f32_16x16x32_bf16 v[22:25], v[160:163], v[196:199], v[22:25]
	v_mfma_f32_16x16x32_bf16 v[18:21], v[168:171], v[196:199], v[18:21]
	v_mfma_f32_16x16x32_bf16 v[6:9], v[160:163], v[204:207], v[6:9]
	v_mfma_f32_16x16x32_bf16 v[2:5], v[168:171], v[204:207], v[2:5]
	v_mfma_f32_16x16x32_bf16 v[50:53], v[160:163], v[180:183], v[50:53]
	v_mfma_f32_16x16x32_bf16 v[54:57], v[168:171], v[180:183], v[54:57]
	s_setprio 0
	s_barrier
	s_add_i32 s66, 0, 0x18000
	s_add_i32 s67, 0, 0x1c000
	v_add_u32_e32 v70, s66, v213
	v_add_u32_e32 v168, s67, v213
	ds_read_b128 v[58:61], v70
	ds_read_b128 v[62:65], v70 offset:1024
	ds_read_b128 v[66:69], v70 offset:2048
	ds_read_b128 v[70:73], v70 offset:3072
	ds_read_b128 v[156:159], v168
	ds_read_b128 v[160:163], v168 offset:1024
	ds_read_b128 v[164:167], v168 offset:2048
	ds_read_b128 v[168:171], v168 offset:3072
	s_add_u32 s38, s38, 0x80000
	s_addc_u32 s39, s39, 0
	s_mov_b32 m0, s45
	v_lshl_add_u64 v[220:221], s[38:39], 0, v[146:147]
	ds_read_b128 v[172:175], v215 offset:32768
	ds_read_b128 v[180:183], v215 offset:33792
	ds_read_b128 v[184:187], v215 offset:34816
	ds_read_b128 v[188:191], v215 offset:35840
	ds_read_b128 v[192:195], v215 offset:36864
	ds_read_b128 v[196:199], v215 offset:37888
	ds_read_b128 v[200:203], v215 offset:38912
	ds_read_b128 v[204:207], v215 offset:39936
	global_load_lds_dwordx4 v[220:221], off
	v_lshl_add_u64 v[220:221], s[38:39], 0, v[148:149]
	s_mov_b32 m0, s46
	s_nop 0
	global_load_lds_dwordx4 v[220:221], off
	s_waitcnt vmcnt(8)
	s_waitcnt lgkmcnt(0)
	s_barrier
	s_setprio 1
	v_mfma_f32_16x16x32_bf16 v[142:145], v[58:61], v[172:175], v[142:145]
	v_mfma_f32_16x16x32_bf16 v[138:141], v[66:69], v[172:175], v[138:141]
	v_mfma_f32_16x16x32_bf16 v[126:129], v[58:61], v[184:187], v[126:129]
	v_mfma_f32_16x16x32_bf16 v[122:125], v[66:69], v[184:187], v[122:125]
	v_mfma_f32_16x16x32_bf16 v[110:113], v[58:61], v[192:195], v[110:113]
	v_mfma_f32_16x16x32_bf16 v[106:109], v[66:69], v[192:195], v[106:109]
	v_mfma_f32_16x16x32_bf16 v[94:97], v[58:61], v[200:203], v[94:97]
	v_mfma_f32_16x16x32_bf16 v[90:93], v[66:69], v[200:203], v[90:93]
	v_mfma_f32_16x16x32_bf16 v[142:145], v[62:65], v[180:183], v[142:145]
	v_mfma_f32_16x16x32_bf16 v[138:141], v[70:73], v[180:183], v[138:141]
	v_mfma_f32_16x16x32_bf16 v[126:129], v[62:65], v[188:191], v[126:129]
	v_mfma_f32_16x16x32_bf16 v[122:125], v[70:73], v[188:191], v[122:125]
	v_mfma_f32_16x16x32_bf16 v[110:113], v[62:65], v[196:199], v[110:113]
	v_mfma_f32_16x16x32_bf16 v[106:109], v[70:73], v[196:199], v[106:109]
	v_mfma_f32_16x16x32_bf16 v[94:97], v[62:65], v[204:207], v[94:97]
	v_mfma_f32_16x16x32_bf16 v[90:93], v[70:73], v[204:207], v[90:93]
	v_mfma_f32_16x16x32_bf16 v[134:137], v[156:159], v[172:175], v[134:137]
	v_mfma_f32_16x16x32_bf16 v[130:133], v[164:167], v[172:175], v[130:133]
	v_mfma_f32_16x16x32_bf16 v[118:121], v[156:159], v[184:187], v[118:121]
	v_mfma_f32_16x16x32_bf16 v[114:117], v[164:167], v[184:187], v[114:117]
	v_mfma_f32_16x16x32_bf16 v[102:105], v[156:159], v[192:195], v[102:105]
	v_mfma_f32_16x16x32_bf16 v[98:101], v[164:167], v[192:195], v[98:101]
	v_mfma_f32_16x16x32_bf16 v[86:89], v[156:159], v[200:203], v[86:89]
	v_mfma_f32_16x16x32_bf16 v[82:85], v[164:167], v[200:203], v[82:85]
	v_mfma_f32_16x16x32_bf16 v[134:137], v[160:163], v[180:183], v[134:137]
	v_mfma_f32_16x16x32_bf16 v[130:133], v[168:171], v[180:183], v[130:133]
	v_mfma_f32_16x16x32_bf16 v[118:121], v[160:163], v[188:191], v[118:121]
	v_mfma_f32_16x16x32_bf16 v[114:117], v[168:171], v[188:191], v[114:117]
	v_mfma_f32_16x16x32_bf16 v[102:105], v[160:163], v[196:199], v[102:105]
	v_mfma_f32_16x16x32_bf16 v[98:101], v[168:171], v[196:199], v[98:101]
	v_mfma_f32_16x16x32_bf16 v[86:89], v[160:163], v[204:207], v[86:89]
	v_mfma_f32_16x16x32_bf16 v[82:85], v[168:171], v[204:207], v[82:85]
	s_setprio 0
	s_barrier
; #define PG8_STAGE(bufoff, gbase, voff) do { _Pragma("unroll") for (int _i = 0; _i < 2; ++_i) \
;         __builtin_amdgcn_global_load_lds((const unsigned*)((const char*)(gbase) + (voff)[_i]), (LAS unsigned*)(lds + (bufoff) + ldsw + _i * 8192), 16, 0, 0); } while (0)
; #define PG8_LDA(dst, b, h) do { _Pragma("unroll") for (int m = 0; m < 4; ++m) _Pragma("unroll") for (int k = 0; k < 2; ++k) dst[m][k] = *(const LAS bf16x8*)(lds + PG8_SA(b, h) + aoff + m * 2048 + k * 1024); } while (0)
; #define PG8_MMA(ai, bj, At, Bt) do { __builtin_amdgcn_s_setprio(1); _Pragma("unroll") for (int m = 0; m < 4; ++m) _Pragma("unroll") for (int n = 0; n < 2; ++n) _Pragma("unroll") for (int k = 0; k < 2; ++k) \
;         acc[ai][bj][m][n] = __builtin_amdgcn_mfma_f32_16x16x32_bf16(Bt[n][k], At[m][k], acc[ai][bj][m][n], 0, 0, 0); __builtin_amdgcn_s_setprio(0); } while (0)
; #define PG8_WAIT_V(n) asm volatile("s_waitcnt vmcnt(" #n ")" ::: "memory")
; #define PG8_WAIT_L(n) asm volatile("s_waitcnt lgkmcnt(" #n ")" ::: "memory")
; #define PG8_BAR __builtin_amdgcn_s_barrier()
; #define PG8_SCHED __builtin_amdgcn_sched_barrier(0)
; template <class Epi, class Sched, int LDA, int LDB, bool ALIGN_EPI = true>
; __device__ __forceinline__ void gemm_phase(LAS unsigned char* lds, const Gemm g, const Sched& S, const Epi& E, int wave) {
;     ...
;             PG8_LDA(At, 1, 1); PG8_STAGE(PG8_SB(1, 0), b3, voffB); PG8_STAGE(PG8_SB(1, 1), b3 + hstepB, voffB); PG8_STAGE(PG8_SA(1, 0), a3, voffA);
;             PG8_WAIT_V(8); PG8_WAIT_L(0); PG8_BAR; PG8_MMA(1, 0, At, B0); PG8_MMA(1, 1, At, B1); PG8_BAR; PG8_SCHED;
;         }
;         if constexpr (ALIGN_EPI) { if (wr == 0) PG8_BAR; }
	s_add_i32 s38, s66, s60
	v_lshl_add_u64 v[208:209], v[208:209], 0, s[70:71]
	s_mov_b32 m0, s38
	ds_read_b128 v[172:175], v215 offset:49152
	ds_read_b128 v[180:183], v215 offset:50176
	ds_read_b128 v[184:187], v215 offset:51200
	ds_read_b128 v[188:191], v215 offset:52224
	ds_read_b128 v[192:195], v215 offset:53248
	ds_read_b128 v[196:199], v215 offset:54272
	ds_read_b128 v[200:203], v215 offset:55296
	ds_read_b128 v[204:207], v215 offset:56320
	global_load_lds_dwordx4 v[208:209], off
	s_add_i32 m0, s38, 0x2000
	s_add_u32 s36, s36, 0x80080
	v_lshl_add_u64 v[208:209], v[210:211], 0, s[70:71]
	s_addc_u32 s37, s37, 0
	s_add_i32 s38, s67, s60
	global_load_lds_dwordx4 v[208:209], off
	v_lshl_add_u64 v[208:209], s[36:37], 0, v[0:1]
	s_mov_b32 m0, s38
	s_nop 0
	global_load_lds_dwordx4 v[208:209], off
	v_lshl_add_u64 v[208:209], s[36:37], 0, v[150:151]
	s_add_i32 m0, s38, 0x2000
	s_nop 0
	global_load_lds_dwordx4 v[208:209], off
	v_lshl_add_u64 v[208:209], v[216:217], 0, s[70:71]
	s_mov_b32 m0, s51
	s_nop 0
	global_load_lds_dwordx4 v[208:209], off
	v_lshl_add_u64 v[208:209], v[218:219], 0, s[70:71]
	s_mov_b32 m0, s52
	s_nop 0
	global_load_lds_dwordx4 v[208:209], off
	s_waitcnt vmcnt(8)
	s_waitcnt lgkmcnt(0)
	s_barrier
	s_setprio 1
	v_mfma_f32_16x16x32_bf16 v[78:81], v[58:61], v[172:175], v[78:81]
	v_mfma_f32_16x16x32_bf16 v[74:77], v[66:69], v[172:175], v[74:77]
	v_mfma_f32_16x16x32_bf16 v[46:49], v[58:61], v[184:187], v[46:49]
	v_mfma_f32_16x16x32_bf16 v[42:45], v[66:69], v[184:187], v[42:45]
	v_mfma_f32_16x16x32_bf16 v[30:33], v[58:61], v[192:195], v[30:33]
	v_mfma_f32_16x16x32_bf16 v[26:29], v[66:69], v[192:195], v[26:29]
	v_mfma_f32_16x16x32_bf16 v[14:17], v[58:61], v[200:203], v[14:17]
	v_mfma_f32_16x16x32_bf16 v[10:13], v[66:69], v[200:203], v[10:13]
	v_mfma_f32_16x16x32_bf16 v[78:81], v[62:65], v[180:183], v[78:81]
	v_mfma_f32_16x16x32_bf16 v[74:77], v[70:73], v[180:183], v[74:77]
	v_mfma_f32_16x16x32_bf16 v[46:49], v[62:65], v[188:191], v[46:49]
	v_mfma_f32_16x16x32_bf16 v[42:45], v[70:73], v[188:191], v[42:45]
	v_mfma_f32_16x16x32_bf16 v[30:33], v[62:65], v[196:199], v[30:33]
	v_mfma_f32_16x16x32_bf16 v[26:29], v[70:73], v[196:199], v[26:29]
	v_mfma_f32_16x16x32_bf16 v[14:17], v[62:65], v[204:207], v[14:17]
	v_mfma_f32_16x16x32_bf16 v[10:13], v[70:73], v[204:207], v[10:13]
	v_mfma_f32_16x16x32_bf16 v[50:53], v[156:159], v[172:175], v[50:53]
	v_mfma_f32_16x16x32_bf16 v[62:65], v[160:163], v[180:183], v[50:53]
	v_mfma_f32_16x16x32_bf16 v[50:53], v[164:167], v[172:175], v[54:57]
	v_mfma_f32_16x16x32_bf16 v[38:41], v[156:159], v[184:187], v[38:41]
	v_mfma_f32_16x16x32_bf16 v[34:37], v[164:167], v[184:187], v[34:37]
	v_mfma_f32_16x16x32_bf16 v[22:25], v[156:159], v[192:195], v[22:25]
	v_mfma_f32_16x16x32_bf16 v[18:21], v[164:167], v[192:195], v[18:21]
	v_mfma_f32_16x16x32_bf16 v[6:9], v[156:159], v[200:203], v[6:9]
	v_mfma_f32_16x16x32_bf16 v[2:5], v[164:167], v[200:203], v[2:5]
	v_mfma_f32_16x16x32_bf16 v[58:61], v[168:171], v[180:183], v[50:53]
	v_mfma_f32_16x16x32_bf16 v[38:41], v[160:163], v[188:191], v[38:41]
	v_mfma_f32_16x16x32_bf16 v[34:37], v[168:171], v[188:191], v[34:37]
	v_mfma_f32_16x16x32_bf16 v[22:25], v[160:163], v[196:199], v[22:25]
	v_mfma_f32_16x16x32_bf16 v[18:21], v[168:171], v[196:199], v[18:21]
	v_mfma_f32_16x16x32_bf16 v[6:9], v[160:163], v[204:207], v[6:9]
	v_mfma_f32_16x16x32_bf16 v[2:5], v[168:171], v[204:207], v[2:5]
	s_setprio 0
	s_barrier
	s_add_u32 s34, s34, 0x100
	s_addc_u32 s35, s35, 0
	s_add_u32 s59, s59, 0x100
	s_addc_u32 s64, s64, 0
	s_cmp_ge_i32 s65, s43
	s_mov_b32 s36, s65
	s_cbranch_scc0 .LBB0_4901
	v_readlane_b32 s34, v252, 14
	v_readlane_b32 s35, v252, 15
	s_and_b64 vcc, exec, s[34:35]
	s_cbranch_vccz .LBB0_4904
	s_barrier
